# v091 + P10 sweep waits relaxed (rows 0..6 of buffer B wait with vmcnt(15..9), 8 dummy dword loads on the last iteration)
# speedup vs baseline: 1.0071x; 1.0071x over previous
; #define PU_LOAD(BUF, EV, S0) do { _Pragma("unroll") for (int i = 0; i < 8; ++i) { const int row_ = __builtin_amdgcn_readlane(EV, (S0) + i); BUF[i & 3][i >> 2] = *(const u32x4*)(PU8 + (size_t)row_ * 1024 + lane * 16); } } while (0)
; __global__ void __launch_bounds__(NT, 2) mk_fwd(Args args) {
;     ...
;             float act0 = 0.f, act1 = 0.f;
;             u32x4 bA[4][2], bB[4][2];
; #pragma unroll
;             for (int hh = 0; hh < 2; ++hh) {
;                 const int ev = hh ? e1 : e0; const float gv = hh ? g1 : g0; float dv = 0.f;
;                 PU_LOAD(bA, ev, 0);
; #pragma unroll 1
;                 for (int s = 0; s < 64; s += 16) {
;                     PU_LOAD(bB, ev, s + 8);
;                     PU_DOT4(bA, 0, s); PU_DOT4(bA, 1, s + 4);
;                     if (s + 16 < 64) PU_LOAD(bA, ev, s + 16);
;                     PU_DOT4(bB, 0, s + 8); PU_DOT4(bB, 1, s + 12);
.LBB0_887:
	s_add_i32 s4, s10, 8
	v_readlane_b32 s4, v108, s4
	s_ashr_i32 s5, s4, 31
	s_lshl_b64 s[4:5], s[4:5], 10
	v_lshl_add_u64 v[32:33], v[98:99], 0, s[4:5]
	s_add_i32 s4, s10, 9
	v_readlane_b32 s4, v108, s4
	s_ashr_i32 s5, s4, 31
	s_lshl_b64 s[4:5], s[4:5], 10
	v_lshl_add_u64 v[34:35], v[98:99], 0, s[4:5]
	s_add_i32 s4, s10, 10
	v_readlane_b32 s4, v108, s4
	s_ashr_i32 s5, s4, 31
	s_lshl_b64 s[4:5], s[4:5], 10
	global_load_dwordx4 v[60:63], v[32:33], off
	global_load_dwordx4 v[52:55], v[34:35], off
	v_lshl_add_u64 v[32:33], v[98:99], 0, s[4:5]
	s_add_i32 s4, s10, 11
	v_readlane_b32 s4, v108, s4
	s_ashr_i32 s5, s4, 31
	s_lshl_b64 s[4:5], s[4:5], 10
	v_lshl_add_u64 v[34:35], v[98:99], 0, s[4:5]
	s_add_i32 s4, s10, 12
	v_readlane_b32 s4, v108, s4
	s_ashr_i32 s5, s4, 31
	s_lshl_b64 s[4:5], s[4:5], 10
	v_lshl_add_u64 v[44:45], v[98:99], 0, s[4:5]
	s_add_i32 s4, s10, 13
	v_readlane_b32 s4, v108, s4
	s_ashr_i32 s5, s4, 31
	s_lshl_b64 s[4:5], s[4:5], 10
	v_lshl_add_u64 v[46:47], v[98:99], 0, s[4:5]
	global_load_dwordx4 v[48:51], v[32:33], off
	global_load_dwordx4 v[40:43], v[34:35], off
	global_load_dwordx4 v[36:39], v[44:45], off
	s_nop 0
	global_load_dwordx4 v[32:35], v[46:47], off
	s_waitcnt vmcnt(13)
	v_cvt_scalef32_pk_f32_fp4 v[46:47], v0, 1.0
	v_pk_fma_f32 v[46:47], v[46:47], v[64:65], 0 op_sel_hi:[1,1,0]
	v_cvt_scalef32_pk_f32_fp4 v[56:57], v0, 1.0 op_sel:[1,0,0]
	v_pk_fma_f32 v[46:47], v[56:57], v[66:67], v[46:47]
	v_cvt_scalef32_pk_f32_fp4 v[56:57], v0, 1.0 op_sel:[0,1,0]
	v_pk_fma_f32 v[46:47], v[56:57], v[68:69], v[46:47]
	v_cvt_scalef32_pk_f32_fp4 v[56:57], v0, 1.0 op_sel:[1,1,0]
	v_pk_fma_f32 v[46:47], v[56:57], v[70:71], v[46:47]
	v_cvt_scalef32_pk_f32_fp4 v[56:57], v1, 1.0
	v_pk_fma_f32 v[46:47], v[56:57], v[72:73], v[46:47]
	v_cvt_scalef32_pk_f32_fp4 v[56:57], v1, 1.0 op_sel:[1,0,0]
	v_pk_fma_f32 v[46:47], v[56:57], v[74:75], v[46:47]
	v_cvt_scalef32_pk_f32_fp4 v[56:57], v1, 1.0 op_sel:[0,1,0]
	v_pk_fma_f32 v[46:47], v[56:57], v[76:77], v[46:47]
	v_cvt_scalef32_pk_f32_fp4 v[56:57], v1, 1.0 op_sel:[1,1,0]
	v_pk_fma_f32 v[46:47], v[56:57], v[78:79], v[46:47]
	v_cvt_scalef32_pk_f32_fp4 v[56:57], v2, 1.0
	v_pk_fma_f32 v[46:47], v[56:57], v[80:81], v[46:47]
	v_cvt_scalef32_pk_f32_fp4 v[56:57], v2, 1.0 op_sel:[1,0,0]
	v_pk_fma_f32 v[46:47], v[56:57], v[82:83], v[46:47]
	v_cvt_scalef32_pk_f32_fp4 v[56:57], v2, 1.0 op_sel:[0,1,0]
	v_pk_fma_f32 v[46:47], v[56:57], v[84:85], v[46:47]
	v_cvt_scalef32_pk_f32_fp4 v[56:57], v2, 1.0 op_sel:[1,1,0]
	v_pk_fma_f32 v[46:47], v[56:57], v[86:87], v[46:47]
	v_cvt_scalef32_pk_f32_fp4 v[56:57], v3, 1.0
	v_pk_fma_f32 v[46:47], v[56:57], v[88:89], v[46:47]
	v_cvt_scalef32_pk_f32_fp4 v[56:57], v3, 1.0 op_sel:[1,0,0]
	v_pk_fma_f32 v[46:47], v[56:57], v[90:91], v[46:47]
	v_cvt_scalef32_pk_f32_fp4 v[56:57], v3, 1.0 op_sel:[0,1,0]
	v_pk_fma_f32 v[46:47], v[56:57], v[92:93], v[46:47]
	v_cvt_scalef32_pk_f32_fp4 v[56:57], v3, 1.0 op_sel:[1,1,0]
	v_pk_fma_f32 v[46:47], v[56:57], v[94:95], v[46:47]
	s_waitcnt vmcnt(12)
	v_cvt_scalef32_pk_f32_fp4 v[56:57], v4, 1.0 op_sel:[1,0,0]
	v_add_f32_e32 v58, v46, v47
	v_cvt_scalef32_pk_f32_fp4 v[46:47], v4, 1.0
	v_pk_fma_f32 v[46:47], v[46:47], v[64:65], 0 op_sel_hi:[1,1,0]
	s_waitcnt vmcnt(9)
	v_cvt_scalef32_pk_f32_fp4 v[114:115], v16, 1.0 op_sel:[1,0,0]
	v_pk_fma_f32 v[46:47], v[56:57], v[66:67], v[46:47]
	v_cvt_scalef32_pk_f32_fp4 v[56:57], v4, 1.0 op_sel:[0,1,0]
	v_pk_fma_f32 v[46:47], v[56:57], v[68:69], v[46:47]
	v_cvt_scalef32_pk_f32_fp4 v[56:57], v4, 1.0 op_sel:[1,1,0]
	v_pk_fma_f32 v[46:47], v[56:57], v[70:71], v[46:47]
	v_cvt_scalef32_pk_f32_fp4 v[56:57], v5, 1.0
	v_pk_fma_f32 v[46:47], v[56:57], v[72:73], v[46:47]
	v_cvt_scalef32_pk_f32_fp4 v[56:57], v5, 1.0 op_sel:[1,0,0]
	v_pk_fma_f32 v[46:47], v[56:57], v[74:75], v[46:47]
	v_cvt_scalef32_pk_f32_fp4 v[56:57], v5, 1.0 op_sel:[0,1,0]
	v_pk_fma_f32 v[46:47], v[56:57], v[76:77], v[46:47]
	v_cvt_scalef32_pk_f32_fp4 v[56:57], v5, 1.0 op_sel:[1,1,0]
	v_pk_fma_f32 v[46:47], v[56:57], v[78:79], v[46:47]
	v_cvt_scalef32_pk_f32_fp4 v[56:57], v6, 1.0
	v_pk_fma_f32 v[46:47], v[56:57], v[80:81], v[46:47]
	v_cvt_scalef32_pk_f32_fp4 v[56:57], v6, 1.0 op_sel:[1,0,0]
	v_pk_fma_f32 v[46:47], v[56:57], v[82:83], v[46:47]
	v_cvt_scalef32_pk_f32_fp4 v[56:57], v6, 1.0 op_sel:[0,1,0]
	v_pk_fma_f32 v[46:47], v[56:57], v[84:85], v[46:47]
	v_cvt_scalef32_pk_f32_fp4 v[56:57], v6, 1.0 op_sel:[1,1,0]
	v_pk_fma_f32 v[46:47], v[56:57], v[86:87], v[46:47]
	v_cvt_scalef32_pk_f32_fp4 v[56:57], v7, 1.0
	v_pk_fma_f32 v[46:47], v[56:57], v[88:89], v[46:47]
	v_cvt_scalef32_pk_f32_fp4 v[56:57], v7, 1.0 op_sel:[1,0,0]
	v_pk_fma_f32 v[46:47], v[56:57], v[90:91], v[46:47]
	v_cvt_scalef32_pk_f32_fp4 v[56:57], v7, 1.0 op_sel:[0,1,0]
	v_pk_fma_f32 v[46:47], v[56:57], v[92:93], v[46:47]
	v_cvt_scalef32_pk_f32_fp4 v[56:57], v7, 1.0 op_sel:[1,1,0]
	v_pk_fma_f32 v[46:47], v[56:57], v[94:95], v[46:47]
	v_cvt_scalef32_pk_f32_fp4 v[56:57], v8, 1.0 op_sel:[1,0,0]
	v_add_f32_e32 v59, v46, v47
	v_cvt_scalef32_pk_f32_fp4 v[46:47], v8, 1.0
	v_pk_fma_f32 v[46:47], v[46:47], v[64:65], 0 op_sel_hi:[1,1,0]
	s_add_i32 s4, s10, 14
	v_pk_fma_f32 v[46:47], v[56:57], v[66:67], v[46:47]
	v_cvt_scalef32_pk_f32_fp4 v[56:57], v8, 1.0 op_sel:[0,1,0]
	v_pk_fma_f32 v[46:47], v[56:57], v[68:69], v[46:47]
	v_cvt_scalef32_pk_f32_fp4 v[56:57], v8, 1.0 op_sel:[1,1,0]
	v_pk_fma_f32 v[46:47], v[56:57], v[70:71], v[46:47]
	v_cvt_scalef32_pk_f32_fp4 v[56:57], v9, 1.0
	v_pk_fma_f32 v[46:47], v[56:57], v[72:73], v[46:47]
	v_cvt_scalef32_pk_f32_fp4 v[56:57], v9, 1.0 op_sel:[1,0,0]
	v_pk_fma_f32 v[46:47], v[56:57], v[74:75], v[46:47]
	v_cvt_scalef32_pk_f32_fp4 v[56:57], v9, 1.0 op_sel:[0,1,0]
	v_pk_fma_f32 v[46:47], v[56:57], v[76:77], v[46:47]
	v_cvt_scalef32_pk_f32_fp4 v[56:57], v9, 1.0 op_sel:[1,1,0]
	v_pk_fma_f32 v[46:47], v[56:57], v[78:79], v[46:47]
	v_cvt_scalef32_pk_f32_fp4 v[56:57], v10, 1.0
	v_pk_fma_f32 v[46:47], v[56:57], v[80:81], v[46:47]
	v_cvt_scalef32_pk_f32_fp4 v[56:57], v10, 1.0 op_sel:[1,0,0]
	v_pk_fma_f32 v[46:47], v[56:57], v[82:83], v[46:47]
	v_cvt_scalef32_pk_f32_fp4 v[56:57], v10, 1.0 op_sel:[0,1,0]
	v_pk_fma_f32 v[46:47], v[56:57], v[84:85], v[46:47]
	v_cvt_scalef32_pk_f32_fp4 v[56:57], v10, 1.0 op_sel:[1,1,0]
	v_pk_fma_f32 v[46:47], v[56:57], v[86:87], v[46:47]
	v_cvt_scalef32_pk_f32_fp4 v[56:57], v11, 1.0
	v_pk_fma_f32 v[46:47], v[56:57], v[88:89], v[46:47]
	v_cvt_scalef32_pk_f32_fp4 v[56:57], v11, 1.0 op_sel:[1,0,0]
	v_pk_fma_f32 v[46:47], v[56:57], v[90:91], v[46:47]
	v_cvt_scalef32_pk_f32_fp4 v[56:57], v11, 1.0 op_sel:[0,1,0]
	v_pk_fma_f32 v[46:47], v[56:57], v[92:93], v[46:47]
	v_cvt_scalef32_pk_f32_fp4 v[56:57], v11, 1.0 op_sel:[1,1,0]
	v_pk_fma_f32 v[46:47], v[56:57], v[94:95], v[46:47]
	v_cvt_scalef32_pk_f32_fp4 v[56:57], v12, 1.0 op_sel:[1,0,0]
	v_add_f32_e32 v109, v46, v47
	v_cvt_scalef32_pk_f32_fp4 v[46:47], v12, 1.0
	v_pk_fma_f32 v[46:47], v[46:47], v[64:65], 0 op_sel_hi:[1,1,0]
	v_readlane_b32 s4, v108, s4
	v_pk_fma_f32 v[46:47], v[56:57], v[66:67], v[46:47]
	v_cvt_scalef32_pk_f32_fp4 v[56:57], v12, 1.0 op_sel:[0,1,0]
	v_pk_fma_f32 v[46:47], v[56:57], v[68:69], v[46:47]
	v_cvt_scalef32_pk_f32_fp4 v[56:57], v12, 1.0 op_sel:[1,1,0]
	v_pk_fma_f32 v[46:47], v[56:57], v[70:71], v[46:47]
	v_cvt_scalef32_pk_f32_fp4 v[56:57], v13, 1.0
	v_pk_fma_f32 v[46:47], v[56:57], v[72:73], v[46:47]
	v_cvt_scalef32_pk_f32_fp4 v[56:57], v13, 1.0 op_sel:[1,0,0]
	v_pk_fma_f32 v[46:47], v[56:57], v[74:75], v[46:47]
	v_cvt_scalef32_pk_f32_fp4 v[56:57], v13, 1.0 op_sel:[0,1,0]
	v_pk_fma_f32 v[46:47], v[56:57], v[76:77], v[46:47]
	v_cvt_scalef32_pk_f32_fp4 v[56:57], v13, 1.0 op_sel:[1,1,0]
	v_pk_fma_f32 v[46:47], v[56:57], v[78:79], v[46:47]
	v_cvt_scalef32_pk_f32_fp4 v[56:57], v14, 1.0
	v_pk_fma_f32 v[46:47], v[56:57], v[80:81], v[46:47]
	v_cvt_scalef32_pk_f32_fp4 v[56:57], v14, 1.0 op_sel:[1,0,0]
	v_pk_fma_f32 v[46:47], v[56:57], v[82:83], v[46:47]
	v_cvt_scalef32_pk_f32_fp4 v[56:57], v14, 1.0 op_sel:[0,1,0]
	v_pk_fma_f32 v[46:47], v[56:57], v[84:85], v[46:47]
	v_cvt_scalef32_pk_f32_fp4 v[56:57], v14, 1.0 op_sel:[1,1,0]
	v_pk_fma_f32 v[46:47], v[56:57], v[86:87], v[46:47]
	v_cvt_scalef32_pk_f32_fp4 v[56:57], v15, 1.0
	v_pk_fma_f32 v[46:47], v[56:57], v[88:89], v[46:47]
	v_cvt_scalef32_pk_f32_fp4 v[56:57], v15, 1.0 op_sel:[1,0,0]
	v_pk_fma_f32 v[46:47], v[56:57], v[90:91], v[46:47]
	v_cvt_scalef32_pk_f32_fp4 v[56:57], v15, 1.0 op_sel:[0,1,0]
	v_pk_fma_f32 v[46:47], v[56:57], v[92:93], v[46:47]
	v_cvt_scalef32_pk_f32_fp4 v[56:57], v15, 1.0 op_sel:[1,1,0]
	v_pk_fma_f32 v[46:47], v[56:57], v[94:95], v[46:47]
	v_cndmask_b32_e64 v57, v109, v58, s[0:1]
	v_add_f32_e32 v46, v46, v47
	v_cndmask_b32_e64 v47, v58, v109, s[0:1]
	v_cndmask_b32_e64 v56, v59, v46, s[0:1]
	ds_bpermute_b32 v47, v129, v47
	ds_bpermute_b32 v56, v129, v56
	v_cndmask_b32_e64 v46, v46, v59, s[0:1]
	s_ashr_i32 s5, s4, 31
	s_lshl_b64 s[4:5], s[4:5], 10
	s_waitcnt lgkmcnt(1)
	v_add_f32_e32 v109, v57, v47
	s_waitcnt lgkmcnt(0)
	v_add_f32_e32 v111, v46, v56
	v_cndmask_b32_e64 v46, v109, v111, s[2:3]
	ds_bpermute_b32 v112, v146, v46
	v_cndmask_b32_e64 v109, v111, v109, s[2:3]
	v_lshl_add_u64 v[44:45], v[98:99], 0, s[4:5]
	s_add_i32 s4, s10, 15
	v_readlane_b32 s4, v108, s4
	s_waitcnt lgkmcnt(0)
	v_add_f32_e32 v109, v109, v112
	v_cvt_scalef32_pk_f32_fp4 v[112:113], v16, 1.0
	v_pk_fma_f32 v[112:113], v[112:113], v[64:65], 0 op_sel_hi:[1,1,0]
	s_ashr_i32 s5, s4, 31
	v_pk_fma_f32 v[112:113], v[114:115], v[66:67], v[112:113]
	v_cvt_scalef32_pk_f32_fp4 v[114:115], v16, 1.0 op_sel:[0,1,0]
	v_pk_fma_f32 v[112:113], v[114:115], v[68:69], v[112:113]
	v_cvt_scalef32_pk_f32_fp4 v[114:115], v16, 1.0 op_sel:[1,1,0]
	v_pk_fma_f32 v[112:113], v[114:115], v[70:71], v[112:113]
	v_cvt_scalef32_pk_f32_fp4 v[114:115], v17, 1.0
	v_pk_fma_f32 v[112:113], v[114:115], v[72:73], v[112:113]
	v_cvt_scalef32_pk_f32_fp4 v[114:115], v17, 1.0 op_sel:[1,0,0]
	v_pk_fma_f32 v[112:113], v[114:115], v[74:75], v[112:113]
	v_cvt_scalef32_pk_f32_fp4 v[114:115], v17, 1.0 op_sel:[0,1,0]
	v_pk_fma_f32 v[112:113], v[114:115], v[76:77], v[112:113]
	v_cvt_scalef32_pk_f32_fp4 v[114:115], v17, 1.0 op_sel:[1,1,0]
	v_pk_fma_f32 v[112:113], v[114:115], v[78:79], v[112:113]
	v_cvt_scalef32_pk_f32_fp4 v[114:115], v18, 1.0
	v_pk_fma_f32 v[112:113], v[114:115], v[80:81], v[112:113]
	v_cvt_scalef32_pk_f32_fp4 v[114:115], v18, 1.0 op_sel:[1,0,0]
	s_lshl_b64 s[4:5], s[4:5], 10
	v_pk_fma_f32 v[112:113], v[114:115], v[82:83], v[112:113]
	v_cvt_scalef32_pk_f32_fp4 v[114:115], v18, 1.0 op_sel:[0,1,0]
	v_lshl_add_u64 v[46:47], v[98:99], 0, s[4:5]
	v_pk_fma_f32 v[112:113], v[114:115], v[84:85], v[112:113]
	v_cvt_scalef32_pk_f32_fp4 v[114:115], v18, 1.0 op_sel:[1,1,0]
	global_load_dwordx4 v[56:59], v[44:45], off
	s_nop 0
	global_load_dwordx4 v[44:47], v[46:47], off
	v_pk_fma_f32 v[112:113], v[114:115], v[86:87], v[112:113]
	v_cvt_scalef32_pk_f32_fp4 v[114:115], v19, 1.0
	v_pk_fma_f32 v[112:113], v[114:115], v[88:89], v[112:113]
	v_cvt_scalef32_pk_f32_fp4 v[114:115], v19, 1.0 op_sel:[1,0,0]
	v_pk_fma_f32 v[112:113], v[114:115], v[90:91], v[112:113]
	v_cvt_scalef32_pk_f32_fp4 v[114:115], v19, 1.0 op_sel:[0,1,0]
	v_pk_fma_f32 v[112:113], v[114:115], v[92:93], v[112:113]
	v_cvt_scalef32_pk_f32_fp4 v[114:115], v19, 1.0 op_sel:[1,1,0]
	v_pk_fma_f32 v[112:113], v[114:115], v[94:95], v[112:113]
	s_waitcnt vmcnt(10)
	v_cvt_scalef32_pk_f32_fp4 v[114:115], v20, 1.0 op_sel:[1,0,0]
	v_add_f32_e32 v111, v112, v113
	v_cvt_scalef32_pk_f32_fp4 v[112:113], v20, 1.0
	v_pk_fma_f32 v[112:113], v[112:113], v[64:65], 0 op_sel_hi:[1,1,0]
	v_add_f32_dpp v109, v109, v109 quad_perm:[1,0,3,2] row_mask:0xf bank_mask:0xf bound_ctrl:1
	v_pk_fma_f32 v[112:113], v[114:115], v[66:67], v[112:113]
	v_cvt_scalef32_pk_f32_fp4 v[114:115], v20, 1.0 op_sel:[0,1,0]
	v_pk_fma_f32 v[112:113], v[114:115], v[68:69], v[112:113]
	v_cvt_scalef32_pk_f32_fp4 v[114:115], v20, 1.0 op_sel:[1,1,0]
	v_pk_fma_f32 v[112:113], v[114:115], v[70:71], v[112:113]
	v_cvt_scalef32_pk_f32_fp4 v[114:115], v21, 1.0
	v_pk_fma_f32 v[112:113], v[114:115], v[72:73], v[112:113]
	v_cvt_scalef32_pk_f32_fp4 v[114:115], v21, 1.0 op_sel:[1,0,0]
	v_pk_fma_f32 v[112:113], v[114:115], v[74:75], v[112:113]
	v_cvt_scalef32_pk_f32_fp4 v[114:115], v21, 1.0 op_sel:[0,1,0]
	v_pk_fma_f32 v[112:113], v[114:115], v[76:77], v[112:113]
	v_cvt_scalef32_pk_f32_fp4 v[114:115], v21, 1.0 op_sel:[1,1,0]
	v_pk_fma_f32 v[112:113], v[114:115], v[78:79], v[112:113]
	v_cvt_scalef32_pk_f32_fp4 v[114:115], v22, 1.0
	v_pk_fma_f32 v[112:113], v[114:115], v[80:81], v[112:113]
	v_cvt_scalef32_pk_f32_fp4 v[114:115], v22, 1.0 op_sel:[1,0,0]
	v_pk_fma_f32 v[112:113], v[114:115], v[82:83], v[112:113]
	v_cvt_scalef32_pk_f32_fp4 v[114:115], v22, 1.0 op_sel:[0,1,0]
	v_pk_fma_f32 v[112:113], v[114:115], v[84:85], v[112:113]
	v_cvt_scalef32_pk_f32_fp4 v[114:115], v22, 1.0 op_sel:[1,1,0]
	v_pk_fma_f32 v[112:113], v[114:115], v[86:87], v[112:113]
	v_cvt_scalef32_pk_f32_fp4 v[114:115], v23, 1.0
	v_pk_fma_f32 v[112:113], v[114:115], v[88:89], v[112:113]
	v_cvt_scalef32_pk_f32_fp4 v[114:115], v23, 1.0 op_sel:[1,0,0]
	v_pk_fma_f32 v[112:113], v[114:115], v[90:91], v[112:113]
	v_cvt_scalef32_pk_f32_fp4 v[114:115], v23, 1.0 op_sel:[0,1,0]
	v_pk_fma_f32 v[112:113], v[114:115], v[92:93], v[112:113]
	v_cvt_scalef32_pk_f32_fp4 v[114:115], v23, 1.0 op_sel:[1,1,0]
	v_pk_fma_f32 v[112:113], v[114:115], v[94:95], v[112:113]
	s_waitcnt vmcnt(9)
	v_cvt_scalef32_pk_f32_fp4 v[114:115], v24, 1.0 op_sel:[1,0,0]
	v_add_f32_e32 v116, v112, v113
	v_cvt_scalef32_pk_f32_fp4 v[112:113], v24, 1.0
	v_pk_fma_f32 v[112:113], v[112:113], v[64:65], 0 op_sel_hi:[1,1,0]
	v_add_f32_dpp v109, v109, v109 quad_perm:[2,3,0,1] row_mask:0xf bank_mask:0xf bound_ctrl:1
	v_pk_fma_f32 v[112:113], v[114:115], v[66:67], v[112:113]
	v_cvt_scalef32_pk_f32_fp4 v[114:115], v24, 1.0 op_sel:[0,1,0]
	v_pk_fma_f32 v[112:113], v[114:115], v[68:69], v[112:113]
	v_cvt_scalef32_pk_f32_fp4 v[114:115], v24, 1.0 op_sel:[1,1,0]
	v_pk_fma_f32 v[112:113], v[114:115], v[70:71], v[112:113]
	v_cvt_scalef32_pk_f32_fp4 v[114:115], v25, 1.0
	v_pk_fma_f32 v[112:113], v[114:115], v[72:73], v[112:113]
	v_cvt_scalef32_pk_f32_fp4 v[114:115], v25, 1.0 op_sel:[1,0,0]
	v_pk_fma_f32 v[112:113], v[114:115], v[74:75], v[112:113]
	v_cvt_scalef32_pk_f32_fp4 v[114:115], v25, 1.0 op_sel:[0,1,0]
	v_pk_fma_f32 v[112:113], v[114:115], v[76:77], v[112:113]
	v_cvt_scalef32_pk_f32_fp4 v[114:115], v25, 1.0 op_sel:[1,1,0]
	v_pk_fma_f32 v[112:113], v[114:115], v[78:79], v[112:113]
	v_cvt_scalef32_pk_f32_fp4 v[114:115], v26, 1.0
	v_pk_fma_f32 v[112:113], v[114:115], v[80:81], v[112:113]
	v_cvt_scalef32_pk_f32_fp4 v[114:115], v26, 1.0 op_sel:[1,0,0]
	v_pk_fma_f32 v[112:113], v[114:115], v[82:83], v[112:113]
	v_cvt_scalef32_pk_f32_fp4 v[114:115], v26, 1.0 op_sel:[0,1,0]
	v_pk_fma_f32 v[112:113], v[114:115], v[84:85], v[112:113]
	v_cvt_scalef32_pk_f32_fp4 v[114:115], v26, 1.0 op_sel:[1,1,0]
	v_pk_fma_f32 v[112:113], v[114:115], v[86:87], v[112:113]
	v_cvt_scalef32_pk_f32_fp4 v[114:115], v27, 1.0
	v_pk_fma_f32 v[112:113], v[114:115], v[88:89], v[112:113]
	v_cvt_scalef32_pk_f32_fp4 v[114:115], v27, 1.0 op_sel:[1,0,0]
	v_pk_fma_f32 v[112:113], v[114:115], v[90:91], v[112:113]
	v_cvt_scalef32_pk_f32_fp4 v[114:115], v27, 1.0 op_sel:[0,1,0]
	v_pk_fma_f32 v[112:113], v[114:115], v[92:93], v[112:113]
	v_cvt_scalef32_pk_f32_fp4 v[114:115], v27, 1.0 op_sel:[1,1,0]
	v_pk_fma_f32 v[112:113], v[114:115], v[94:95], v[112:113]
	s_waitcnt vmcnt(8)
	v_cvt_scalef32_pk_f32_fp4 v[114:115], v28, 1.0 op_sel:[1,0,0]
	v_add_f32_e32 v117, v112, v113
	v_cvt_scalef32_pk_f32_fp4 v[112:113], v28, 1.0
	v_pk_fma_f32 v[112:113], v[112:113], v[64:65], 0 op_sel_hi:[1,1,0]
	v_add_f32_dpp v109, v109, v109 row_half_mirror row_mask:0xf bank_mask:0xf bound_ctrl:1
	v_pk_fma_f32 v[112:113], v[114:115], v[66:67], v[112:113]
	v_cvt_scalef32_pk_f32_fp4 v[114:115], v28, 1.0 op_sel:[0,1,0]
	v_pk_fma_f32 v[112:113], v[114:115], v[68:69], v[112:113]
	v_cvt_scalef32_pk_f32_fp4 v[114:115], v28, 1.0 op_sel:[1,1,0]
	v_pk_fma_f32 v[112:113], v[114:115], v[70:71], v[112:113]
	v_cvt_scalef32_pk_f32_fp4 v[114:115], v29, 1.0
	v_pk_fma_f32 v[112:113], v[114:115], v[72:73], v[112:113]
	v_cvt_scalef32_pk_f32_fp4 v[114:115], v29, 1.0 op_sel:[1,0,0]
	v_pk_fma_f32 v[112:113], v[114:115], v[74:75], v[112:113]
	v_cvt_scalef32_pk_f32_fp4 v[114:115], v29, 1.0 op_sel:[0,1,0]
	v_pk_fma_f32 v[112:113], v[114:115], v[76:77], v[112:113]
	v_cvt_scalef32_pk_f32_fp4 v[114:115], v29, 1.0 op_sel:[1,1,0]
	v_pk_fma_f32 v[112:113], v[114:115], v[78:79], v[112:113]
	v_cvt_scalef32_pk_f32_fp4 v[114:115], v30, 1.0
	v_pk_fma_f32 v[112:113], v[114:115], v[80:81], v[112:113]
	v_cvt_scalef32_pk_f32_fp4 v[114:115], v30, 1.0 op_sel:[1,0,0]
	v_pk_fma_f32 v[112:113], v[114:115], v[82:83], v[112:113]
	v_cvt_scalef32_pk_f32_fp4 v[114:115], v30, 1.0 op_sel:[0,1,0]
	v_pk_fma_f32 v[112:113], v[114:115], v[84:85], v[112:113]
	v_cvt_scalef32_pk_f32_fp4 v[114:115], v30, 1.0 op_sel:[1,1,0]
	v_pk_fma_f32 v[112:113], v[114:115], v[86:87], v[112:113]
	v_cvt_scalef32_pk_f32_fp4 v[114:115], v31, 1.0
	v_pk_fma_f32 v[112:113], v[114:115], v[88:89], v[112:113]
	v_cvt_scalef32_pk_f32_fp4 v[114:115], v31, 1.0 op_sel:[1,0,0]
	v_pk_fma_f32 v[112:113], v[114:115], v[90:91], v[112:113]
	v_cvt_scalef32_pk_f32_fp4 v[114:115], v31, 1.0 op_sel:[0,1,0]
	v_pk_fma_f32 v[112:113], v[114:115], v[92:93], v[112:113]
	v_cvt_scalef32_pk_f32_fp4 v[114:115], v31, 1.0 op_sel:[1,1,0]
	v_pk_fma_f32 v[112:113], v[114:115], v[94:95], v[112:113]
	v_add_f32_dpp v109, v109, v109 row_mirror row_mask:0xf bank_mask:0xf bound_ctrl:1
	v_add_f32_e32 v112, v112, v113
	v_cndmask_b32_e64 v113, v111, v117, s[0:1]
	v_cndmask_b32_e64 v114, v116, v112, s[0:1]
	ds_bpermute_b32 v113, v129, v113
	ds_bpermute_b32 v114, v129, v114
	v_cndmask_b32_e64 v111, v117, v111, s[0:1]
	v_cndmask_b32_e64 v112, v112, v116, s[0:1]
	s_add_i32 s12, s10, 16
	s_waitcnt lgkmcnt(1)
; #define PU_LOAD(BUF, EV, S0) do { _Pragma("unroll") for (int i = 0; i < 8; ++i) { const int row_ = __builtin_amdgcn_readlane(EV, (S0) + i); BUF[i & 3][i >> 2] = *(const u32x4*)(PU8 + (size_t)row_ * 1024 + lane * 16); } } while (0)
; __global__ void __launch_bounds__(NT, 2) mk_fwd(Args args) {
;     ...
;                 for (int s = 0; s < 64; s += 16) {
;                     PU_LOAD(bB, ev, s + 8);
;                     PU_DOT4(bA, 0, s); PU_DOT4(bA, 1, s + 4);
;                     if (s + 16 < 64) PU_LOAD(bA, ev, s + 16);
;                     PU_DOT4(bB, 0, s + 8); PU_DOT4(bB, 1, s + 12);
	v_add_f32_e32 v113, v111, v113
	s_waitcnt lgkmcnt(0)
	v_add_f32_e32 v112, v112, v114
	v_cndmask_b32_e64 v111, v113, v112, s[2:3]
	ds_bpermute_b32 v114, v146, v111
	ds_bpermute_b32 v111, v147, v109
	v_cndmask_b32_e64 v109, v112, v113, s[2:3]
	s_cmp_gt_u32 s10, 47
	s_cselect_b64 s[4:5], -1, 0
	s_waitcnt lgkmcnt(1)
	v_add_f32_e32 v109, v109, v114
	s_cmp_lt_u32 s10, 48
	s_nop 0
	v_add_f32_dpp v109, v109, v109 quad_perm:[1,0,3,2] row_mask:0xf bank_mask:0xf bound_ctrl:1
	s_nop 1
	v_add_f32_dpp v109, v109, v109 quad_perm:[2,3,0,1] row_mask:0xf bank_mask:0xf bound_ctrl:1
	s_nop 1
	v_add_f32_dpp v109, v109, v109 row_half_mirror row_mask:0xf bank_mask:0xf bound_ctrl:1
	s_nop 1
	v_add_f32_dpp v109, v109, v109 row_mirror row_mask:0xf bank_mask:0xf bound_ctrl:1
	ds_bpermute_b32 v109, v147, v109
	s_cbranch_scc0 .Lp10_dmy_889
	v_readlane_b32 s30, v108, s12
	s_ashr_i32 s31, s30, 31
	s_lshl_b64 s[30:31], s[30:31], 10
	s_add_i32 s14, s10, 17
	v_lshl_add_u64 v[8:9], v[98:99], 0, s[30:31]
	v_readlane_b32 s30, v108, s14
	s_ashr_i32 s31, s30, 31
	s_lshl_b64 s[30:31], s[30:31], 10
	s_add_i32 s14, s10, 18
	v_lshl_add_u64 v[10:11], v[98:99], 0, s[30:31]
	v_readlane_b32 s30, v108, s14
	s_ashr_i32 s31, s30, 31
	s_lshl_b64 s[30:31], s[30:31], 10
	s_add_i32 s14, s10, 19
	v_lshl_add_u64 v[16:17], v[98:99], 0, s[30:31]
	v_readlane_b32 s30, v108, s14
	s_ashr_i32 s31, s30, 31
	s_lshl_b64 s[30:31], s[30:31], 10
	s_add_i32 s14, s10, 20
	v_lshl_add_u64 v[18:19], v[98:99], 0, s[30:31]
	v_readlane_b32 s30, v108, s14
	s_ashr_i32 s31, s30, 31
	s_lshl_b64 s[30:31], s[30:31], 10
	s_add_i32 s14, s10, 21
	v_lshl_add_u64 v[24:25], v[98:99], 0, s[30:31]
	v_readlane_b32 s30, v108, s14
	s_ashr_i32 s31, s30, 31
	s_lshl_b64 s[30:31], s[30:31], 10
	s_add_i32 s14, s10, 22
	v_lshl_add_u64 v[26:27], v[98:99], 0, s[30:31]
	v_readlane_b32 s30, v108, s14
	s_ashr_i32 s31, s30, 31
	s_lshl_b64 s[30:31], s[30:31], 10
	s_add_i32 s14, s10, 23
	global_load_dwordx4 v[0:3], v[8:9], off
	global_load_dwordx4 v[4:7], v[10:11], off
	s_nop 0
	global_load_dwordx4 v[8:11], v[16:17], off
	global_load_dwordx4 v[12:15], v[18:19], off
	s_nop 0
	global_load_dwordx4 v[16:19], v[24:25], off
	global_load_dwordx4 v[20:23], v[26:27], off
	v_lshl_add_u64 v[24:25], v[98:99], 0, s[30:31]
	v_readlane_b32 s30, v108, s14
	s_ashr_i32 s31, s30, 31
	s_lshl_b64 s[30:31], s[30:31], 10
	v_lshl_add_u64 v[28:29], v[98:99], 0, s[30:31]
	global_load_dwordx4 v[24:27], v[24:25], off
	s_nop 0
	global_load_dwordx4 v[28:31], v[28:29], off
	s_branch .LBB0_889
.Lp10_dmy_889:
	global_load_dword v220, v129, s[6:7]
	global_load_dword v221, v129, s[6:7]
	global_load_dword v222, v129, s[6:7]
	global_load_dword v223, v129, s[6:7]
	global_load_dword v224, v129, s[6:7]
	global_load_dword v225, v129, s[6:7]
	global_load_dword v226, v129, s[6:7]
	global_load_dword v227, v129, s[6:7]
.LBB0_889:
	s_waitcnt vmcnt(15)
	v_cvt_scalef32_pk_f32_fp4 v[112:113], v60, 1.0
	v_pk_fma_f32 v[112:113], v[112:113], v[64:65], 0 op_sel_hi:[1,1,0]
	v_cvt_scalef32_pk_f32_fp4 v[114:115], v60, 1.0 op_sel:[1,0,0]
	v_pk_fma_f32 v[112:113], v[114:115], v[66:67], v[112:113]
	v_cvt_scalef32_pk_f32_fp4 v[114:115], v60, 1.0 op_sel:[0,1,0]
	v_pk_fma_f32 v[112:113], v[114:115], v[68:69], v[112:113]
	v_cvt_scalef32_pk_f32_fp4 v[114:115], v60, 1.0 op_sel:[1,1,0]
	v_pk_fma_f32 v[112:113], v[114:115], v[70:71], v[112:113]
	v_cvt_scalef32_pk_f32_fp4 v[114:115], v61, 1.0
	v_pk_fma_f32 v[112:113], v[114:115], v[72:73], v[112:113]
	v_cvt_scalef32_pk_f32_fp4 v[114:115], v61, 1.0 op_sel:[1,0,0]
	v_pk_fma_f32 v[112:113], v[114:115], v[74:75], v[112:113]
	v_cvt_scalef32_pk_f32_fp4 v[114:115], v61, 1.0 op_sel:[0,1,0]
	v_pk_fma_f32 v[112:113], v[114:115], v[76:77], v[112:113]
	v_cvt_scalef32_pk_f32_fp4 v[60:61], v61, 1.0 op_sel:[1,1,0]
	v_pk_fma_f32 v[60:61], v[60:61], v[78:79], v[112:113]
	v_cvt_scalef32_pk_f32_fp4 v[112:113], v62, 1.0
	v_pk_fma_f32 v[60:61], v[112:113], v[80:81], v[60:61]
	v_cvt_scalef32_pk_f32_fp4 v[112:113], v62, 1.0 op_sel:[1,0,0]
	v_pk_fma_f32 v[60:61], v[112:113], v[82:83], v[60:61]
	v_cvt_scalef32_pk_f32_fp4 v[112:113], v62, 1.0 op_sel:[0,1,0]
	v_pk_fma_f32 v[60:61], v[112:113], v[84:85], v[60:61]
	v_cvt_scalef32_pk_f32_fp4 v[112:113], v62, 1.0 op_sel:[1,1,0]
	v_pk_fma_f32 v[60:61], v[112:113], v[86:87], v[60:61]
	v_cvt_scalef32_pk_f32_fp4 v[112:113], v63, 1.0
	v_pk_fma_f32 v[60:61], v[112:113], v[88:89], v[60:61]
	v_cvt_scalef32_pk_f32_fp4 v[112:113], v63, 1.0 op_sel:[1,0,0]
	v_pk_fma_f32 v[60:61], v[112:113], v[90:91], v[60:61]
	v_cvt_scalef32_pk_f32_fp4 v[112:113], v63, 1.0 op_sel:[0,1,0]
	v_pk_fma_f32 v[60:61], v[112:113], v[92:93], v[60:61]
	v_cvt_scalef32_pk_f32_fp4 v[62:63], v63, 1.0 op_sel:[1,1,0]
	v_pk_fma_f32 v[60:61], v[62:63], v[94:95], v[60:61]
	s_waitcnt vmcnt(14)
; __global__ void __launch_bounds__(NT, 2) mk_fwd(Args args) {
;     ...
;                     PU_DOT4(bB, 0, s + 8); PU_DOT4(bB, 1, s + 12);
	v_cvt_scalef32_pk_f32_fp4 v[62:63], v52, 1.0 op_sel:[1,0,0]
	v_add_f32_e32 v112, v60, v61
	v_cvt_scalef32_pk_f32_fp4 v[60:61], v52, 1.0
	v_pk_fma_f32 v[60:61], v[60:61], v[64:65], 0 op_sel_hi:[1,1,0]
	v_cmp_eq_u32_e32 vcc, s10, v148
	v_pk_fma_f32 v[60:61], v[62:63], v[66:67], v[60:61]
	v_cvt_scalef32_pk_f32_fp4 v[62:63], v52, 1.0 op_sel:[0,1,0]
	v_pk_fma_f32 v[60:61], v[62:63], v[68:69], v[60:61]
	v_cvt_scalef32_pk_f32_fp4 v[62:63], v52, 1.0 op_sel:[1,1,0]
	v_pk_fma_f32 v[60:61], v[62:63], v[70:71], v[60:61]
	v_cvt_scalef32_pk_f32_fp4 v[62:63], v53, 1.0
	v_pk_fma_f32 v[60:61], v[62:63], v[72:73], v[60:61]
	v_cvt_scalef32_pk_f32_fp4 v[62:63], v53, 1.0 op_sel:[1,0,0]
	v_pk_fma_f32 v[60:61], v[62:63], v[74:75], v[60:61]
	v_cvt_scalef32_pk_f32_fp4 v[62:63], v53, 1.0 op_sel:[0,1,0]
	v_pk_fma_f32 v[60:61], v[62:63], v[76:77], v[60:61]
	v_cvt_scalef32_pk_f32_fp4 v[52:53], v53, 1.0 op_sel:[1,1,0]
	v_pk_fma_f32 v[52:53], v[52:53], v[78:79], v[60:61]
	v_cvt_scalef32_pk_f32_fp4 v[60:61], v54, 1.0
	v_pk_fma_f32 v[52:53], v[60:61], v[80:81], v[52:53]
	v_cvt_scalef32_pk_f32_fp4 v[60:61], v54, 1.0 op_sel:[1,0,0]
	v_pk_fma_f32 v[52:53], v[60:61], v[82:83], v[52:53]
	v_cvt_scalef32_pk_f32_fp4 v[60:61], v54, 1.0 op_sel:[0,1,0]
	v_pk_fma_f32 v[52:53], v[60:61], v[84:85], v[52:53]
	v_cvt_scalef32_pk_f32_fp4 v[60:61], v54, 1.0 op_sel:[1,1,0]
	v_pk_fma_f32 v[52:53], v[60:61], v[86:87], v[52:53]
	v_cvt_scalef32_pk_f32_fp4 v[60:61], v55, 1.0
	v_pk_fma_f32 v[52:53], v[60:61], v[88:89], v[52:53]
	v_cvt_scalef32_pk_f32_fp4 v[60:61], v55, 1.0 op_sel:[1,0,0]
	v_pk_fma_f32 v[52:53], v[60:61], v[90:91], v[52:53]
	v_cvt_scalef32_pk_f32_fp4 v[60:61], v55, 1.0 op_sel:[0,1,0]
	v_pk_fma_f32 v[52:53], v[60:61], v[92:93], v[52:53]
	v_cvt_scalef32_pk_f32_fp4 v[54:55], v55, 1.0 op_sel:[1,1,0]
	v_pk_fma_f32 v[52:53], v[54:55], v[94:95], v[52:53]
	s_waitcnt vmcnt(13)
	v_cvt_scalef32_pk_f32_fp4 v[54:55], v48, 1.0 op_sel:[1,0,0]
	v_add_f32_e32 v60, v52, v53
	v_cvt_scalef32_pk_f32_fp4 v[52:53], v48, 1.0
	v_pk_fma_f32 v[52:53], v[52:53], v[64:65], 0 op_sel_hi:[1,1,0]
	s_nop 0
	v_pk_fma_f32 v[52:53], v[54:55], v[66:67], v[52:53]
	v_cvt_scalef32_pk_f32_fp4 v[54:55], v48, 1.0 op_sel:[0,1,0]
	v_pk_fma_f32 v[52:53], v[54:55], v[68:69], v[52:53]
	v_cvt_scalef32_pk_f32_fp4 v[54:55], v48, 1.0 op_sel:[1,1,0]
	v_pk_fma_f32 v[52:53], v[54:55], v[70:71], v[52:53]
	v_cvt_scalef32_pk_f32_fp4 v[54:55], v49, 1.0
	v_pk_fma_f32 v[52:53], v[54:55], v[72:73], v[52:53]
	v_cvt_scalef32_pk_f32_fp4 v[54:55], v49, 1.0 op_sel:[1,0,0]
	v_pk_fma_f32 v[52:53], v[54:55], v[74:75], v[52:53]
	v_cvt_scalef32_pk_f32_fp4 v[54:55], v49, 1.0 op_sel:[0,1,0]
	v_pk_fma_f32 v[52:53], v[54:55], v[76:77], v[52:53]
	v_cvt_scalef32_pk_f32_fp4 v[48:49], v49, 1.0 op_sel:[1,1,0]
	v_pk_fma_f32 v[48:49], v[48:49], v[78:79], v[52:53]
	v_cvt_scalef32_pk_f32_fp4 v[52:53], v50, 1.0
	v_pk_fma_f32 v[48:49], v[52:53], v[80:81], v[48:49]
	v_cvt_scalef32_pk_f32_fp4 v[52:53], v50, 1.0 op_sel:[1,0,0]
	v_pk_fma_f32 v[48:49], v[52:53], v[82:83], v[48:49]
	v_cvt_scalef32_pk_f32_fp4 v[52:53], v50, 1.0 op_sel:[0,1,0]
	v_pk_fma_f32 v[48:49], v[52:53], v[84:85], v[48:49]
	v_cvt_scalef32_pk_f32_fp4 v[52:53], v50, 1.0 op_sel:[1,1,0]
	v_pk_fma_f32 v[48:49], v[52:53], v[86:87], v[48:49]
	v_cvt_scalef32_pk_f32_fp4 v[52:53], v51, 1.0
	v_pk_fma_f32 v[48:49], v[52:53], v[88:89], v[48:49]
	v_cvt_scalef32_pk_f32_fp4 v[52:53], v51, 1.0 op_sel:[1,0,0]
	v_pk_fma_f32 v[48:49], v[52:53], v[90:91], v[48:49]
	v_cvt_scalef32_pk_f32_fp4 v[52:53], v51, 1.0 op_sel:[0,1,0]
	v_pk_fma_f32 v[48:49], v[52:53], v[92:93], v[48:49]
	v_cvt_scalef32_pk_f32_fp4 v[50:51], v51, 1.0 op_sel:[1,1,0]
	v_pk_fma_f32 v[48:49], v[50:51], v[94:95], v[48:49]
	s_waitcnt vmcnt(12)
	v_cvt_scalef32_pk_f32_fp4 v[50:51], v40, 1.0 op_sel:[1,0,0]
	v_add_f32_e32 v52, v48, v49
	v_cvt_scalef32_pk_f32_fp4 v[48:49], v40, 1.0
	v_pk_fma_f32 v[48:49], v[48:49], v[64:65], 0 op_sel_hi:[1,1,0]
	s_nop 0
	v_pk_fma_f32 v[48:49], v[50:51], v[66:67], v[48:49]
	v_cvt_scalef32_pk_f32_fp4 v[50:51], v40, 1.0 op_sel:[0,1,0]
	v_pk_fma_f32 v[48:49], v[50:51], v[68:69], v[48:49]
	v_cvt_scalef32_pk_f32_fp4 v[50:51], v40, 1.0 op_sel:[1,1,0]
	v_pk_fma_f32 v[48:49], v[50:51], v[70:71], v[48:49]
	v_cvt_scalef32_pk_f32_fp4 v[50:51], v41, 1.0
	v_pk_fma_f32 v[48:49], v[50:51], v[72:73], v[48:49]
	v_cvt_scalef32_pk_f32_fp4 v[50:51], v41, 1.0 op_sel:[1,0,0]
	v_pk_fma_f32 v[48:49], v[50:51], v[74:75], v[48:49]
	v_cvt_scalef32_pk_f32_fp4 v[50:51], v41, 1.0 op_sel:[0,1,0]
	v_pk_fma_f32 v[48:49], v[50:51], v[76:77], v[48:49]
	v_cvt_scalef32_pk_f32_fp4 v[40:41], v41, 1.0 op_sel:[1,1,0]
	v_pk_fma_f32 v[40:41], v[40:41], v[78:79], v[48:49]
	v_cvt_scalef32_pk_f32_fp4 v[48:49], v42, 1.0
	v_pk_fma_f32 v[40:41], v[48:49], v[80:81], v[40:41]
	v_cvt_scalef32_pk_f32_fp4 v[48:49], v42, 1.0 op_sel:[1,0,0]
	v_pk_fma_f32 v[40:41], v[48:49], v[82:83], v[40:41]
	v_cvt_scalef32_pk_f32_fp4 v[48:49], v42, 1.0 op_sel:[0,1,0]
	v_pk_fma_f32 v[40:41], v[48:49], v[84:85], v[40:41]
	v_cvt_scalef32_pk_f32_fp4 v[48:49], v42, 1.0 op_sel:[1,1,0]
	v_pk_fma_f32 v[40:41], v[48:49], v[86:87], v[40:41]
	v_cvt_scalef32_pk_f32_fp4 v[48:49], v43, 1.0
	v_pk_fma_f32 v[40:41], v[48:49], v[88:89], v[40:41]
	v_cvt_scalef32_pk_f32_fp4 v[48:49], v43, 1.0 op_sel:[1,0,0]
	v_pk_fma_f32 v[40:41], v[48:49], v[90:91], v[40:41]
	v_cvt_scalef32_pk_f32_fp4 v[48:49], v43, 1.0 op_sel:[0,1,0]
	v_pk_fma_f32 v[40:41], v[48:49], v[92:93], v[40:41]
	v_cvt_scalef32_pk_f32_fp4 v[42:43], v43, 1.0 op_sel:[1,1,0]
	v_pk_fma_f32 v[40:41], v[42:43], v[94:95], v[40:41]
	v_cndmask_b32_e64 v43, v52, v112, s[0:1]
	v_add_f32_e32 v40, v40, v41
	v_cndmask_b32_e64 v41, v112, v52, s[0:1]
	v_cndmask_b32_e64 v42, v60, v40, s[0:1]
	ds_bpermute_b32 v41, v129, v41
	ds_bpermute_b32 v42, v129, v42
	v_cndmask_b32_e64 v40, v40, v60, s[0:1]
	s_waitcnt lgkmcnt(3)
; __global__ void __launch_bounds__(NT, 2) mk_fwd(Args args) {
;     ...
;                     PU_DOT4(bB, 0, s + 8); PU_DOT4(bB, 1, s + 12);
	v_cndmask_b32_e32 v48, v107, v111, vcc
	v_cmp_eq_u32_e32 vcc, s10, v151
	s_waitcnt lgkmcnt(1)
	v_add_f32_e32 v41, v43, v41
	s_waitcnt lgkmcnt(0)
	v_add_f32_e32 v40, v40, v42
	v_cndmask_b32_e64 v42, v41, v40, s[2:3]
	ds_bpermute_b32 v42, v146, v42
	v_cndmask_b32_e64 v40, v40, v41, s[2:3]
	s_waitcnt lgkmcnt(0)
	v_add_f32_e32 v40, v40, v42
	s_nop 1
	v_add_f32_dpp v49, v40, v40 quad_perm:[1,0,3,2] row_mask:0xf bank_mask:0xf bound_ctrl:1
	s_waitcnt vmcnt(11)
	v_cvt_scalef32_pk_f32_fp4 v[40:41], v36, 1.0
	v_pk_fma_f32 v[40:41], v[40:41], v[64:65], 0 op_sel_hi:[1,1,0]
	v_cvt_scalef32_pk_f32_fp4 v[42:43], v36, 1.0 op_sel:[1,0,0]
	v_pk_fma_f32 v[40:41], v[42:43], v[66:67], v[40:41]
	v_cvt_scalef32_pk_f32_fp4 v[42:43], v36, 1.0 op_sel:[0,1,0]
	v_pk_fma_f32 v[40:41], v[42:43], v[68:69], v[40:41]
	v_cvt_scalef32_pk_f32_fp4 v[42:43], v36, 1.0 op_sel:[1,1,0]
	v_pk_fma_f32 v[40:41], v[42:43], v[70:71], v[40:41]
	v_cvt_scalef32_pk_f32_fp4 v[42:43], v37, 1.0
	v_pk_fma_f32 v[40:41], v[42:43], v[72:73], v[40:41]
	v_cvt_scalef32_pk_f32_fp4 v[42:43], v37, 1.0 op_sel:[1,0,0]
	v_pk_fma_f32 v[40:41], v[42:43], v[74:75], v[40:41]
	v_cvt_scalef32_pk_f32_fp4 v[42:43], v37, 1.0 op_sel:[0,1,0]
	v_pk_fma_f32 v[40:41], v[42:43], v[76:77], v[40:41]
	v_cvt_scalef32_pk_f32_fp4 v[36:37], v37, 1.0 op_sel:[1,1,0]
	v_pk_fma_f32 v[36:37], v[36:37], v[78:79], v[40:41]
	v_cvt_scalef32_pk_f32_fp4 v[40:41], v38, 1.0
	v_pk_fma_f32 v[36:37], v[40:41], v[80:81], v[36:37]
	v_cvt_scalef32_pk_f32_fp4 v[40:41], v38, 1.0 op_sel:[1,0,0]
	v_pk_fma_f32 v[36:37], v[40:41], v[82:83], v[36:37]
	v_cvt_scalef32_pk_f32_fp4 v[40:41], v38, 1.0 op_sel:[0,1,0]
	v_pk_fma_f32 v[36:37], v[40:41], v[84:85], v[36:37]
	v_cvt_scalef32_pk_f32_fp4 v[40:41], v38, 1.0 op_sel:[1,1,0]
	v_pk_fma_f32 v[36:37], v[40:41], v[86:87], v[36:37]
	v_cvt_scalef32_pk_f32_fp4 v[40:41], v39, 1.0
	v_pk_fma_f32 v[36:37], v[40:41], v[88:89], v[36:37]
	v_cvt_scalef32_pk_f32_fp4 v[40:41], v39, 1.0 op_sel:[1,0,0]
	v_pk_fma_f32 v[36:37], v[40:41], v[90:91], v[36:37]
	v_cvt_scalef32_pk_f32_fp4 v[40:41], v39, 1.0 op_sel:[0,1,0]
	v_pk_fma_f32 v[36:37], v[40:41], v[92:93], v[36:37]
	v_cvt_scalef32_pk_f32_fp4 v[38:39], v39, 1.0 op_sel:[1,1,0]
	v_pk_fma_f32 v[36:37], v[38:39], v[94:95], v[36:37]
	s_waitcnt vmcnt(10)
	v_cvt_scalef32_pk_f32_fp4 v[38:39], v32, 1.0 op_sel:[1,0,0]
	v_add_f32_e32 v40, v36, v37
	v_cvt_scalef32_pk_f32_fp4 v[36:37], v32, 1.0
	v_pk_fma_f32 v[36:37], v[36:37], v[64:65], 0 op_sel_hi:[1,1,0]
	s_nop 0
	v_pk_fma_f32 v[36:37], v[38:39], v[66:67], v[36:37]
	v_cvt_scalef32_pk_f32_fp4 v[38:39], v32, 1.0 op_sel:[0,1,0]
	v_pk_fma_f32 v[36:37], v[38:39], v[68:69], v[36:37]
	v_cvt_scalef32_pk_f32_fp4 v[38:39], v32, 1.0 op_sel:[1,1,0]
	v_pk_fma_f32 v[36:37], v[38:39], v[70:71], v[36:37]
	v_cvt_scalef32_pk_f32_fp4 v[38:39], v33, 1.0
	v_pk_fma_f32 v[36:37], v[38:39], v[72:73], v[36:37]
	v_cvt_scalef32_pk_f32_fp4 v[38:39], v33, 1.0 op_sel:[1,0,0]
	v_pk_fma_f32 v[36:37], v[38:39], v[74:75], v[36:37]
	v_cvt_scalef32_pk_f32_fp4 v[38:39], v33, 1.0 op_sel:[0,1,0]
	v_pk_fma_f32 v[36:37], v[38:39], v[76:77], v[36:37]
	v_cvt_scalef32_pk_f32_fp4 v[32:33], v33, 1.0 op_sel:[1,1,0]
	v_pk_fma_f32 v[32:33], v[32:33], v[78:79], v[36:37]
	v_cvt_scalef32_pk_f32_fp4 v[36:37], v34, 1.0
	v_pk_fma_f32 v[32:33], v[36:37], v[80:81], v[32:33]
	v_cvt_scalef32_pk_f32_fp4 v[36:37], v34, 1.0 op_sel:[1,0,0]
	v_pk_fma_f32 v[32:33], v[36:37], v[82:83], v[32:33]
	v_cvt_scalef32_pk_f32_fp4 v[36:37], v34, 1.0 op_sel:[0,1,0]
	v_pk_fma_f32 v[32:33], v[36:37], v[84:85], v[32:33]
	v_cvt_scalef32_pk_f32_fp4 v[36:37], v34, 1.0 op_sel:[1,1,0]
	v_pk_fma_f32 v[32:33], v[36:37], v[86:87], v[32:33]
	v_cvt_scalef32_pk_f32_fp4 v[36:37], v35, 1.0
	v_pk_fma_f32 v[32:33], v[36:37], v[88:89], v[32:33]
	v_cvt_scalef32_pk_f32_fp4 v[36:37], v35, 1.0 op_sel:[1,0,0]
	v_pk_fma_f32 v[32:33], v[36:37], v[90:91], v[32:33]
	v_cvt_scalef32_pk_f32_fp4 v[36:37], v35, 1.0 op_sel:[0,1,0]
	v_pk_fma_f32 v[32:33], v[36:37], v[92:93], v[32:33]
	v_cvt_scalef32_pk_f32_fp4 v[34:35], v35, 1.0 op_sel:[1,1,0]
	v_pk_fma_f32 v[32:33], v[34:35], v[94:95], v[32:33]
	s_waitcnt vmcnt(9)
; #define PU_LOAD(BUF, EV, S0) do { _Pragma("unroll") for (int i = 0; i < 8; ++i) { const int row_ = __builtin_amdgcn_readlane(EV, (S0) + i); BUF[i & 3][i >> 2] = *(const u32x4*)(PU8 + (size_t)row_ * 1024 + lane * 16); } } while (0)
; __global__ void __launch_bounds__(NT, 2) mk_fwd(Args args) {
;     ...
;             float act0 = 0.f, act1 = 0.f;
;             u32x4 bA[4][2], bB[4][2];
; #pragma unroll
;             for (int hh = 0; hh < 2; ++hh) {
;                 const int ev = hh ? e1 : e0; const float gv = hh ? g1 : g0; float dv = 0.f;
;                 PU_LOAD(bA, ev, 0);
; #pragma unroll 1
;                 for (int s = 0; s < 64; s += 16) {
;                     PU_LOAD(bB, ev, s + 8);
;                     PU_DOT4(bA, 0, s); PU_DOT4(bA, 1, s + 4);
;                     if (s + 16 < 64) PU_LOAD(bA, ev, s + 16);
;                     PU_DOT4(bB, 0, s + 8); PU_DOT4(bB, 1, s + 12);
;                 }
	v_cvt_scalef32_pk_f32_fp4 v[34:35], v56, 1.0 op_sel:[1,0,0]
	v_add_f32_e32 v36, v32, v33
	v_cvt_scalef32_pk_f32_fp4 v[32:33], v56, 1.0
	v_pk_fma_f32 v[32:33], v[32:33], v[64:65], 0 op_sel_hi:[1,1,0]
	s_nop 0
	v_pk_fma_f32 v[32:33], v[34:35], v[66:67], v[32:33]
	v_cvt_scalef32_pk_f32_fp4 v[34:35], v56, 1.0 op_sel:[0,1,0]
	v_pk_fma_f32 v[32:33], v[34:35], v[68:69], v[32:33]
	v_cvt_scalef32_pk_f32_fp4 v[34:35], v56, 1.0 op_sel:[1,1,0]
	v_pk_fma_f32 v[32:33], v[34:35], v[70:71], v[32:33]
	v_cvt_scalef32_pk_f32_fp4 v[34:35], v57, 1.0
	v_pk_fma_f32 v[32:33], v[34:35], v[72:73], v[32:33]
	v_cvt_scalef32_pk_f32_fp4 v[34:35], v57, 1.0 op_sel:[1,0,0]
	v_pk_fma_f32 v[32:33], v[34:35], v[74:75], v[32:33]
	v_cvt_scalef32_pk_f32_fp4 v[34:35], v57, 1.0 op_sel:[0,1,0]
	v_pk_fma_f32 v[32:33], v[34:35], v[76:77], v[32:33]
	v_cvt_scalef32_pk_f32_fp4 v[34:35], v57, 1.0 op_sel:[1,1,0]
	v_pk_fma_f32 v[32:33], v[34:35], v[78:79], v[32:33]
	v_cvt_scalef32_pk_f32_fp4 v[34:35], v58, 1.0
	v_pk_fma_f32 v[32:33], v[34:35], v[80:81], v[32:33]
	v_cvt_scalef32_pk_f32_fp4 v[34:35], v58, 1.0 op_sel:[1,0,0]
	v_pk_fma_f32 v[32:33], v[34:35], v[82:83], v[32:33]
	v_cvt_scalef32_pk_f32_fp4 v[34:35], v58, 1.0 op_sel:[0,1,0]
	v_pk_fma_f32 v[32:33], v[34:35], v[84:85], v[32:33]
	v_cvt_scalef32_pk_f32_fp4 v[34:35], v58, 1.0 op_sel:[1,1,0]
	v_pk_fma_f32 v[32:33], v[34:35], v[86:87], v[32:33]
	v_cvt_scalef32_pk_f32_fp4 v[34:35], v59, 1.0
	v_pk_fma_f32 v[32:33], v[34:35], v[88:89], v[32:33]
	v_cvt_scalef32_pk_f32_fp4 v[34:35], v59, 1.0 op_sel:[1,0,0]
	v_pk_fma_f32 v[32:33], v[34:35], v[90:91], v[32:33]
	v_cvt_scalef32_pk_f32_fp4 v[34:35], v59, 1.0 op_sel:[0,1,0]
	v_pk_fma_f32 v[32:33], v[34:35], v[92:93], v[32:33]
	v_cvt_scalef32_pk_f32_fp4 v[34:35], v59, 1.0 op_sel:[1,1,0]
	v_pk_fma_f32 v[32:33], v[34:35], v[94:95], v[32:33]
	s_waitcnt vmcnt(0)
	v_cvt_scalef32_pk_f32_fp4 v[34:35], v44, 1.0 op_sel:[1,0,0]
	v_add_f32_e32 v37, v32, v33
	v_cvt_scalef32_pk_f32_fp4 v[32:33], v44, 1.0
	v_pk_fma_f32 v[32:33], v[32:33], v[64:65], 0 op_sel_hi:[1,1,0]
	s_nop 0
	v_pk_fma_f32 v[32:33], v[34:35], v[66:67], v[32:33]
	v_cvt_scalef32_pk_f32_fp4 v[34:35], v44, 1.0 op_sel:[0,1,0]
	v_pk_fma_f32 v[32:33], v[34:35], v[68:69], v[32:33]
	v_cvt_scalef32_pk_f32_fp4 v[34:35], v44, 1.0 op_sel:[1,1,0]
	v_pk_fma_f32 v[32:33], v[34:35], v[70:71], v[32:33]
	v_cvt_scalef32_pk_f32_fp4 v[34:35], v45, 1.0
	v_pk_fma_f32 v[32:33], v[34:35], v[72:73], v[32:33]
	v_cvt_scalef32_pk_f32_fp4 v[34:35], v45, 1.0 op_sel:[1,0,0]
	v_pk_fma_f32 v[32:33], v[34:35], v[74:75], v[32:33]
	v_cvt_scalef32_pk_f32_fp4 v[34:35], v45, 1.0 op_sel:[0,1,0]
	v_pk_fma_f32 v[32:33], v[34:35], v[76:77], v[32:33]
	v_cvt_scalef32_pk_f32_fp4 v[34:35], v45, 1.0 op_sel:[1,1,0]
	v_pk_fma_f32 v[32:33], v[34:35], v[78:79], v[32:33]
	v_cvt_scalef32_pk_f32_fp4 v[34:35], v46, 1.0
	v_pk_fma_f32 v[32:33], v[34:35], v[80:81], v[32:33]
	v_cvt_scalef32_pk_f32_fp4 v[34:35], v46, 1.0 op_sel:[1,0,0]
	v_pk_fma_f32 v[32:33], v[34:35], v[82:83], v[32:33]
	v_cvt_scalef32_pk_f32_fp4 v[34:35], v46, 1.0 op_sel:[0,1,0]
	v_pk_fma_f32 v[32:33], v[34:35], v[84:85], v[32:33]
	v_cvt_scalef32_pk_f32_fp4 v[34:35], v46, 1.0 op_sel:[1,1,0]
	v_pk_fma_f32 v[32:33], v[34:35], v[86:87], v[32:33]
	v_cvt_scalef32_pk_f32_fp4 v[34:35], v47, 1.0
	v_pk_fma_f32 v[32:33], v[34:35], v[88:89], v[32:33]
	v_cvt_scalef32_pk_f32_fp4 v[34:35], v47, 1.0 op_sel:[1,0,0]
	v_pk_fma_f32 v[32:33], v[34:35], v[90:91], v[32:33]
	v_cvt_scalef32_pk_f32_fp4 v[34:35], v47, 1.0 op_sel:[0,1,0]
	v_pk_fma_f32 v[32:33], v[34:35], v[92:93], v[32:33]
	v_cvt_scalef32_pk_f32_fp4 v[34:35], v47, 1.0 op_sel:[1,1,0]
	v_pk_fma_f32 v[32:33], v[34:35], v[94:95], v[32:33]
	s_nop 0
	v_add_f32_e32 v32, v32, v33
	v_cndmask_b32_e64 v33, v40, v37, s[0:1]
	v_cndmask_b32_e64 v34, v36, v32, s[0:1]
	ds_bpermute_b32 v33, v129, v33
	ds_bpermute_b32 v34, v129, v34
	v_cndmask_b32_e64 v37, v37, v40, s[0:1]
	v_cndmask_b32_e64 v32, v32, v36, s[0:1]
	v_add_f32_dpp v35, v49, v49 quad_perm:[2,3,0,1] row_mask:0xf bank_mask:0xf bound_ctrl:1
	s_waitcnt lgkmcnt(1)
	v_add_f32_e32 v33, v37, v33
	s_waitcnt lgkmcnt(0)
	v_add_f32_e32 v32, v32, v34
	v_cndmask_b32_e64 v34, v33, v32, s[2:3]
	ds_bpermute_b32 v34, v146, v34
	v_cndmask_b32_e64 v32, v32, v33, s[2:3]
	v_add_f32_dpp v35, v35, v35 row_half_mirror row_mask:0xf bank_mask:0xf bound_ctrl:1
	v_cndmask_b32_e32 v33, v48, v109, vcc
	v_cmp_eq_u32_e32 vcc, s10, v150
	s_waitcnt lgkmcnt(0)
	v_add_f32_e32 v32, v32, v34
	v_add_f32_dpp v35, v35, v35 row_mirror row_mask:0xf bank_mask:0xf bound_ctrl:1
	ds_bpermute_b32 v35, v147, v35
	v_add_f32_dpp v32, v32, v32 quad_perm:[1,0,3,2] row_mask:0xf bank_mask:0xf bound_ctrl:1
	s_waitcnt lgkmcnt(0)
	v_cndmask_b32_e32 v33, v33, v35, vcc
	v_add_f32_dpp v32, v32, v32 quad_perm:[2,3,0,1] row_mask:0xf bank_mask:0xf bound_ctrl:1
	v_cmp_eq_u32_e32 vcc, s10, v149
	s_nop 0
	v_add_f32_dpp v32, v32, v32 row_half_mirror row_mask:0xf bank_mask:0xf bound_ctrl:1
	s_nop 1
	v_add_f32_dpp v32, v32, v32 row_mirror row_mask:0xf bank_mask:0xf bound_ctrl:1
	ds_bpermute_b32 v32, v147, v32
	s_waitcnt lgkmcnt(0)
	v_cndmask_b32_e32 v107, v33, v32, vcc
	s_and_b64 vcc, exec, s[4:5]
	s_cbranch_vccnz .LBB0_891
	s_mov_b32 s10, s12
	s_branch .LBB0_887

; #define PU_LOAD(BUF, EV, S0) do { _Pragma("unroll") for (int i = 0; i < 8; ++i) { const int row_ = __builtin_amdgcn_readlane(EV, (S0) + i); BUF[i & 3][i >> 2] = *(const u32x4*)(PU8 + (size_t)row_ * 1024 + lane * 16); } } while (0)
; __global__ void __launch_bounds__(NT, 2) mk_fwd(Args args) {
;     ...
;             float act0 = 0.f, act1 = 0.f;
;             u32x4 bA[4][2], bB[4][2];
; #pragma unroll
;             for (int hh = 0; hh < 2; ++hh) {
;                 const int ev = hh ? e1 : e0; const float gv = hh ? g1 : g0; float dv = 0.f;
;                 PU_LOAD(bA, ev, 0);
; #pragma unroll 1
;                 for (int s = 0; s < 64; s += 16) {
;                     PU_LOAD(bB, ev, s + 8);
;                     PU_DOT4(bA, 0, s); PU_DOT4(bA, 1, s + 4);
;                     if (s + 16 < 64) PU_LOAD(bA, ev, s + 16);
;                     PU_DOT4(bB, 0, s + 8); PU_DOT4(bB, 1, s + 12);
.LBB0_896:
	s_add_i32 s4, s10, 8
	v_readlane_b32 s4, v106, s4
	s_ashr_i32 s5, s4, 31
	s_lshl_b64 s[4:5], s[4:5], 10
	v_lshl_add_u64 v[32:33], v[98:99], 0, s[4:5]
	s_add_i32 s4, s10, 9
	v_readlane_b32 s4, v106, s4
	s_ashr_i32 s5, s4, 31
	s_lshl_b64 s[4:5], s[4:5], 10
	v_lshl_add_u64 v[34:35], v[98:99], 0, s[4:5]
	s_add_i32 s4, s10, 10
	v_readlane_b32 s4, v106, s4
	s_ashr_i32 s5, s4, 31
	s_lshl_b64 s[4:5], s[4:5], 10
	global_load_dwordx4 v[60:63], v[32:33], off
	global_load_dwordx4 v[52:55], v[34:35], off
	v_lshl_add_u64 v[32:33], v[98:99], 0, s[4:5]
	s_add_i32 s4, s10, 11
	v_readlane_b32 s4, v106, s4
	s_ashr_i32 s5, s4, 31
	s_lshl_b64 s[4:5], s[4:5], 10
	v_lshl_add_u64 v[34:35], v[98:99], 0, s[4:5]
	s_add_i32 s4, s10, 12
	v_readlane_b32 s4, v106, s4
	s_ashr_i32 s5, s4, 31
	s_lshl_b64 s[4:5], s[4:5], 10
	v_lshl_add_u64 v[44:45], v[98:99], 0, s[4:5]
	s_add_i32 s4, s10, 13
	v_readlane_b32 s4, v106, s4
	s_ashr_i32 s5, s4, 31
	s_lshl_b64 s[4:5], s[4:5], 10
	v_lshl_add_u64 v[46:47], v[98:99], 0, s[4:5]
	global_load_dwordx4 v[48:51], v[32:33], off
	global_load_dwordx4 v[40:43], v[34:35], off
	global_load_dwordx4 v[36:39], v[44:45], off
	s_nop 0
	global_load_dwordx4 v[32:35], v[46:47], off
	s_waitcnt vmcnt(13)
	v_cvt_scalef32_pk_f32_fp4 v[46:47], v0, 1.0
	v_pk_fma_f32 v[46:47], v[46:47], v[64:65], 0 op_sel_hi:[1,1,0]
	v_cvt_scalef32_pk_f32_fp4 v[56:57], v0, 1.0 op_sel:[1,0,0]
	v_pk_fma_f32 v[46:47], v[56:57], v[66:67], v[46:47]
	v_cvt_scalef32_pk_f32_fp4 v[56:57], v0, 1.0 op_sel:[0,1,0]
	v_pk_fma_f32 v[46:47], v[56:57], v[68:69], v[46:47]
	v_cvt_scalef32_pk_f32_fp4 v[56:57], v0, 1.0 op_sel:[1,1,0]
	v_pk_fma_f32 v[46:47], v[56:57], v[70:71], v[46:47]
	v_cvt_scalef32_pk_f32_fp4 v[56:57], v1, 1.0
	v_pk_fma_f32 v[46:47], v[56:57], v[72:73], v[46:47]
	v_cvt_scalef32_pk_f32_fp4 v[56:57], v1, 1.0 op_sel:[1,0,0]
	v_pk_fma_f32 v[46:47], v[56:57], v[74:75], v[46:47]
	v_cvt_scalef32_pk_f32_fp4 v[56:57], v1, 1.0 op_sel:[0,1,0]
	v_pk_fma_f32 v[46:47], v[56:57], v[76:77], v[46:47]
	v_cvt_scalef32_pk_f32_fp4 v[56:57], v1, 1.0 op_sel:[1,1,0]
	v_pk_fma_f32 v[46:47], v[56:57], v[78:79], v[46:47]
	v_cvt_scalef32_pk_f32_fp4 v[56:57], v2, 1.0
	v_pk_fma_f32 v[46:47], v[56:57], v[80:81], v[46:47]
	v_cvt_scalef32_pk_f32_fp4 v[56:57], v2, 1.0 op_sel:[1,0,0]
	v_pk_fma_f32 v[46:47], v[56:57], v[82:83], v[46:47]
	v_cvt_scalef32_pk_f32_fp4 v[56:57], v2, 1.0 op_sel:[0,1,0]
	v_pk_fma_f32 v[46:47], v[56:57], v[84:85], v[46:47]
	v_cvt_scalef32_pk_f32_fp4 v[56:57], v2, 1.0 op_sel:[1,1,0]
	v_pk_fma_f32 v[46:47], v[56:57], v[86:87], v[46:47]
	v_cvt_scalef32_pk_f32_fp4 v[56:57], v3, 1.0
	v_pk_fma_f32 v[46:47], v[56:57], v[88:89], v[46:47]
	v_cvt_scalef32_pk_f32_fp4 v[56:57], v3, 1.0 op_sel:[1,0,0]
	v_pk_fma_f32 v[46:47], v[56:57], v[90:91], v[46:47]
	v_cvt_scalef32_pk_f32_fp4 v[56:57], v3, 1.0 op_sel:[0,1,0]
	v_pk_fma_f32 v[46:47], v[56:57], v[92:93], v[46:47]
	v_cvt_scalef32_pk_f32_fp4 v[56:57], v3, 1.0 op_sel:[1,1,0]
	v_pk_fma_f32 v[46:47], v[56:57], v[94:95], v[46:47]
	s_waitcnt vmcnt(12)
	v_cvt_scalef32_pk_f32_fp4 v[56:57], v4, 1.0 op_sel:[1,0,0]
	v_add_f32_e32 v58, v46, v47
	v_cvt_scalef32_pk_f32_fp4 v[46:47], v4, 1.0
	v_pk_fma_f32 v[46:47], v[46:47], v[64:65], 0 op_sel_hi:[1,1,0]
	s_waitcnt vmcnt(9)
	v_cvt_scalef32_pk_f32_fp4 v[118:119], v16, 1.0 op_sel:[1,0,0]
	v_pk_fma_f32 v[46:47], v[56:57], v[66:67], v[46:47]
	v_cvt_scalef32_pk_f32_fp4 v[56:57], v4, 1.0 op_sel:[0,1,0]
	v_pk_fma_f32 v[46:47], v[56:57], v[68:69], v[46:47]
	v_cvt_scalef32_pk_f32_fp4 v[56:57], v4, 1.0 op_sel:[1,1,0]
	v_pk_fma_f32 v[46:47], v[56:57], v[70:71], v[46:47]
	v_cvt_scalef32_pk_f32_fp4 v[56:57], v5, 1.0
	v_pk_fma_f32 v[46:47], v[56:57], v[72:73], v[46:47]
	v_cvt_scalef32_pk_f32_fp4 v[56:57], v5, 1.0 op_sel:[1,0,0]
	v_pk_fma_f32 v[46:47], v[56:57], v[74:75], v[46:47]
	v_cvt_scalef32_pk_f32_fp4 v[56:57], v5, 1.0 op_sel:[0,1,0]
	v_pk_fma_f32 v[46:47], v[56:57], v[76:77], v[46:47]
	v_cvt_scalef32_pk_f32_fp4 v[56:57], v5, 1.0 op_sel:[1,1,0]
	v_pk_fma_f32 v[46:47], v[56:57], v[78:79], v[46:47]
	v_cvt_scalef32_pk_f32_fp4 v[56:57], v6, 1.0
	v_pk_fma_f32 v[46:47], v[56:57], v[80:81], v[46:47]
	v_cvt_scalef32_pk_f32_fp4 v[56:57], v6, 1.0 op_sel:[1,0,0]
	v_pk_fma_f32 v[46:47], v[56:57], v[82:83], v[46:47]
	v_cvt_scalef32_pk_f32_fp4 v[56:57], v6, 1.0 op_sel:[0,1,0]
	v_pk_fma_f32 v[46:47], v[56:57], v[84:85], v[46:47]
	v_cvt_scalef32_pk_f32_fp4 v[56:57], v6, 1.0 op_sel:[1,1,0]
	v_pk_fma_f32 v[46:47], v[56:57], v[86:87], v[46:47]
	v_cvt_scalef32_pk_f32_fp4 v[56:57], v7, 1.0
	v_pk_fma_f32 v[46:47], v[56:57], v[88:89], v[46:47]
	v_cvt_scalef32_pk_f32_fp4 v[56:57], v7, 1.0 op_sel:[1,0,0]
	v_pk_fma_f32 v[46:47], v[56:57], v[90:91], v[46:47]
	v_cvt_scalef32_pk_f32_fp4 v[56:57], v7, 1.0 op_sel:[0,1,0]
	v_pk_fma_f32 v[46:47], v[56:57], v[92:93], v[46:47]
	v_cvt_scalef32_pk_f32_fp4 v[56:57], v7, 1.0 op_sel:[1,1,0]
	v_pk_fma_f32 v[46:47], v[56:57], v[94:95], v[46:47]
	v_cvt_scalef32_pk_f32_fp4 v[56:57], v8, 1.0 op_sel:[1,0,0]
	v_add_f32_e32 v59, v46, v47
	v_cvt_scalef32_pk_f32_fp4 v[46:47], v8, 1.0
	v_pk_fma_f32 v[46:47], v[46:47], v[64:65], 0 op_sel_hi:[1,1,0]
	s_add_i32 s4, s10, 14
	v_pk_fma_f32 v[46:47], v[56:57], v[66:67], v[46:47]
	v_cvt_scalef32_pk_f32_fp4 v[56:57], v8, 1.0 op_sel:[0,1,0]
	v_pk_fma_f32 v[46:47], v[56:57], v[68:69], v[46:47]
	v_cvt_scalef32_pk_f32_fp4 v[56:57], v8, 1.0 op_sel:[1,1,0]
	v_pk_fma_f32 v[46:47], v[56:57], v[70:71], v[46:47]
	v_cvt_scalef32_pk_f32_fp4 v[56:57], v9, 1.0
	v_pk_fma_f32 v[46:47], v[56:57], v[72:73], v[46:47]
	v_cvt_scalef32_pk_f32_fp4 v[56:57], v9, 1.0 op_sel:[1,0,0]
	v_pk_fma_f32 v[46:47], v[56:57], v[74:75], v[46:47]
	v_cvt_scalef32_pk_f32_fp4 v[56:57], v9, 1.0 op_sel:[0,1,0]
	v_pk_fma_f32 v[46:47], v[56:57], v[76:77], v[46:47]
	v_cvt_scalef32_pk_f32_fp4 v[56:57], v9, 1.0 op_sel:[1,1,0]
	v_pk_fma_f32 v[46:47], v[56:57], v[78:79], v[46:47]
	v_cvt_scalef32_pk_f32_fp4 v[56:57], v10, 1.0
	v_pk_fma_f32 v[46:47], v[56:57], v[80:81], v[46:47]
	v_cvt_scalef32_pk_f32_fp4 v[56:57], v10, 1.0 op_sel:[1,0,0]
	v_pk_fma_f32 v[46:47], v[56:57], v[82:83], v[46:47]
	v_cvt_scalef32_pk_f32_fp4 v[56:57], v10, 1.0 op_sel:[0,1,0]
	v_pk_fma_f32 v[46:47], v[56:57], v[84:85], v[46:47]
	v_cvt_scalef32_pk_f32_fp4 v[56:57], v10, 1.0 op_sel:[1,1,0]
	v_pk_fma_f32 v[46:47], v[56:57], v[86:87], v[46:47]
	v_cvt_scalef32_pk_f32_fp4 v[56:57], v11, 1.0
	v_pk_fma_f32 v[46:47], v[56:57], v[88:89], v[46:47]
	v_cvt_scalef32_pk_f32_fp4 v[56:57], v11, 1.0 op_sel:[1,0,0]
	v_pk_fma_f32 v[46:47], v[56:57], v[90:91], v[46:47]
	v_cvt_scalef32_pk_f32_fp4 v[56:57], v11, 1.0 op_sel:[0,1,0]
	v_pk_fma_f32 v[46:47], v[56:57], v[92:93], v[46:47]
	v_cvt_scalef32_pk_f32_fp4 v[56:57], v11, 1.0 op_sel:[1,1,0]
	v_pk_fma_f32 v[46:47], v[56:57], v[94:95], v[46:47]
	v_cvt_scalef32_pk_f32_fp4 v[56:57], v12, 1.0 op_sel:[1,0,0]
	v_add_f32_e32 v107, v46, v47
	v_cvt_scalef32_pk_f32_fp4 v[46:47], v12, 1.0
	v_pk_fma_f32 v[46:47], v[46:47], v[64:65], 0 op_sel_hi:[1,1,0]
	v_readlane_b32 s4, v106, s4
	v_pk_fma_f32 v[46:47], v[56:57], v[66:67], v[46:47]
	v_cvt_scalef32_pk_f32_fp4 v[56:57], v12, 1.0 op_sel:[0,1,0]
	v_pk_fma_f32 v[46:47], v[56:57], v[68:69], v[46:47]
	v_cvt_scalef32_pk_f32_fp4 v[56:57], v12, 1.0 op_sel:[1,1,0]
	v_pk_fma_f32 v[46:47], v[56:57], v[70:71], v[46:47]
	v_cvt_scalef32_pk_f32_fp4 v[56:57], v13, 1.0
	v_pk_fma_f32 v[46:47], v[56:57], v[72:73], v[46:47]
	v_cvt_scalef32_pk_f32_fp4 v[56:57], v13, 1.0 op_sel:[1,0,0]
	v_pk_fma_f32 v[46:47], v[56:57], v[74:75], v[46:47]
	v_cvt_scalef32_pk_f32_fp4 v[56:57], v13, 1.0 op_sel:[0,1,0]
	v_pk_fma_f32 v[46:47], v[56:57], v[76:77], v[46:47]
	v_cvt_scalef32_pk_f32_fp4 v[56:57], v13, 1.0 op_sel:[1,1,0]
	v_pk_fma_f32 v[46:47], v[56:57], v[78:79], v[46:47]
	v_cvt_scalef32_pk_f32_fp4 v[56:57], v14, 1.0
	v_pk_fma_f32 v[46:47], v[56:57], v[80:81], v[46:47]
	v_cvt_scalef32_pk_f32_fp4 v[56:57], v14, 1.0 op_sel:[1,0,0]
	v_pk_fma_f32 v[46:47], v[56:57], v[82:83], v[46:47]
	v_cvt_scalef32_pk_f32_fp4 v[56:57], v14, 1.0 op_sel:[0,1,0]
	v_pk_fma_f32 v[46:47], v[56:57], v[84:85], v[46:47]
	v_cvt_scalef32_pk_f32_fp4 v[56:57], v14, 1.0 op_sel:[1,1,0]
	v_pk_fma_f32 v[46:47], v[56:57], v[86:87], v[46:47]
	v_cvt_scalef32_pk_f32_fp4 v[56:57], v15, 1.0
	v_pk_fma_f32 v[46:47], v[56:57], v[88:89], v[46:47]
	v_cvt_scalef32_pk_f32_fp4 v[56:57], v15, 1.0 op_sel:[1,0,0]
	v_pk_fma_f32 v[46:47], v[56:57], v[90:91], v[46:47]
	v_cvt_scalef32_pk_f32_fp4 v[56:57], v15, 1.0 op_sel:[0,1,0]
	v_pk_fma_f32 v[46:47], v[56:57], v[92:93], v[46:47]
	v_cvt_scalef32_pk_f32_fp4 v[56:57], v15, 1.0 op_sel:[1,1,0]
	v_pk_fma_f32 v[46:47], v[56:57], v[94:95], v[46:47]
	v_cndmask_b32_e64 v57, v107, v58, s[0:1]
	v_add_f32_e32 v46, v46, v47
	v_cndmask_b32_e64 v47, v58, v107, s[0:1]
	v_cndmask_b32_e64 v56, v59, v46, s[0:1]
	ds_bpermute_b32 v47, v129, v47
	ds_bpermute_b32 v56, v129, v56
	v_cndmask_b32_e64 v46, v46, v59, s[0:1]
	s_ashr_i32 s5, s4, 31
	s_lshl_b64 s[4:5], s[4:5], 10
	s_waitcnt lgkmcnt(1)
	v_add_f32_e32 v107, v57, v47
	s_waitcnt lgkmcnt(0)
	v_add_f32_e32 v115, v46, v56
	v_cndmask_b32_e64 v46, v107, v115, s[2:3]
	ds_bpermute_b32 v116, v146, v46
	v_cndmask_b32_e64 v107, v115, v107, s[2:3]
	v_lshl_add_u64 v[44:45], v[98:99], 0, s[4:5]
	s_add_i32 s4, s10, 15
	v_readlane_b32 s4, v106, s4
	s_waitcnt lgkmcnt(0)
	v_add_f32_e32 v107, v107, v116
	v_cvt_scalef32_pk_f32_fp4 v[116:117], v16, 1.0
	v_pk_fma_f32 v[116:117], v[116:117], v[64:65], 0 op_sel_hi:[1,1,0]
	s_ashr_i32 s5, s4, 31
	v_pk_fma_f32 v[116:117], v[118:119], v[66:67], v[116:117]
	v_cvt_scalef32_pk_f32_fp4 v[118:119], v16, 1.0 op_sel:[0,1,0]
	v_pk_fma_f32 v[116:117], v[118:119], v[68:69], v[116:117]
	v_cvt_scalef32_pk_f32_fp4 v[118:119], v16, 1.0 op_sel:[1,1,0]
	v_pk_fma_f32 v[116:117], v[118:119], v[70:71], v[116:117]
	v_cvt_scalef32_pk_f32_fp4 v[118:119], v17, 1.0
	v_pk_fma_f32 v[116:117], v[118:119], v[72:73], v[116:117]
	v_cvt_scalef32_pk_f32_fp4 v[118:119], v17, 1.0 op_sel:[1,0,0]
	v_pk_fma_f32 v[116:117], v[118:119], v[74:75], v[116:117]
	v_cvt_scalef32_pk_f32_fp4 v[118:119], v17, 1.0 op_sel:[0,1,0]
	v_pk_fma_f32 v[116:117], v[118:119], v[76:77], v[116:117]
	v_cvt_scalef32_pk_f32_fp4 v[118:119], v17, 1.0 op_sel:[1,1,0]
	v_pk_fma_f32 v[116:117], v[118:119], v[78:79], v[116:117]
	v_cvt_scalef32_pk_f32_fp4 v[118:119], v18, 1.0
	v_pk_fma_f32 v[116:117], v[118:119], v[80:81], v[116:117]
	v_cvt_scalef32_pk_f32_fp4 v[118:119], v18, 1.0 op_sel:[1,0,0]
	s_lshl_b64 s[4:5], s[4:5], 10
	v_pk_fma_f32 v[116:117], v[118:119], v[82:83], v[116:117]
	v_cvt_scalef32_pk_f32_fp4 v[118:119], v18, 1.0 op_sel:[0,1,0]
	v_lshl_add_u64 v[46:47], v[98:99], 0, s[4:5]
	v_pk_fma_f32 v[116:117], v[118:119], v[84:85], v[116:117]
	v_cvt_scalef32_pk_f32_fp4 v[118:119], v18, 1.0 op_sel:[1,1,0]
	global_load_dwordx4 v[56:59], v[44:45], off
	s_nop 0
	global_load_dwordx4 v[44:47], v[46:47], off
	v_pk_fma_f32 v[116:117], v[118:119], v[86:87], v[116:117]
	v_cvt_scalef32_pk_f32_fp4 v[118:119], v19, 1.0
	v_pk_fma_f32 v[116:117], v[118:119], v[88:89], v[116:117]
	v_cvt_scalef32_pk_f32_fp4 v[118:119], v19, 1.0 op_sel:[1,0,0]
	v_pk_fma_f32 v[116:117], v[118:119], v[90:91], v[116:117]
	v_cvt_scalef32_pk_f32_fp4 v[118:119], v19, 1.0 op_sel:[0,1,0]
	v_pk_fma_f32 v[116:117], v[118:119], v[92:93], v[116:117]
	v_cvt_scalef32_pk_f32_fp4 v[118:119], v19, 1.0 op_sel:[1,1,0]
	v_pk_fma_f32 v[116:117], v[118:119], v[94:95], v[116:117]
	s_waitcnt vmcnt(10)
	v_cvt_scalef32_pk_f32_fp4 v[118:119], v20, 1.0 op_sel:[1,0,0]
	v_add_f32_e32 v115, v116, v117
	v_cvt_scalef32_pk_f32_fp4 v[116:117], v20, 1.0
	v_pk_fma_f32 v[116:117], v[116:117], v[64:65], 0 op_sel_hi:[1,1,0]
	v_add_f32_dpp v107, v107, v107 quad_perm:[1,0,3,2] row_mask:0xf bank_mask:0xf bound_ctrl:1
	v_pk_fma_f32 v[116:117], v[118:119], v[66:67], v[116:117]
	v_cvt_scalef32_pk_f32_fp4 v[118:119], v20, 1.0 op_sel:[0,1,0]
	v_pk_fma_f32 v[116:117], v[118:119], v[68:69], v[116:117]
	v_cvt_scalef32_pk_f32_fp4 v[118:119], v20, 1.0 op_sel:[1,1,0]
	v_pk_fma_f32 v[116:117], v[118:119], v[70:71], v[116:117]
	v_cvt_scalef32_pk_f32_fp4 v[118:119], v21, 1.0
	v_pk_fma_f32 v[116:117], v[118:119], v[72:73], v[116:117]
	v_cvt_scalef32_pk_f32_fp4 v[118:119], v21, 1.0 op_sel:[1,0,0]
	v_pk_fma_f32 v[116:117], v[118:119], v[74:75], v[116:117]
	v_cvt_scalef32_pk_f32_fp4 v[118:119], v21, 1.0 op_sel:[0,1,0]
	v_pk_fma_f32 v[116:117], v[118:119], v[76:77], v[116:117]
	v_cvt_scalef32_pk_f32_fp4 v[118:119], v21, 1.0 op_sel:[1,1,0]
	v_pk_fma_f32 v[116:117], v[118:119], v[78:79], v[116:117]
	v_cvt_scalef32_pk_f32_fp4 v[118:119], v22, 1.0
	v_pk_fma_f32 v[116:117], v[118:119], v[80:81], v[116:117]
	v_cvt_scalef32_pk_f32_fp4 v[118:119], v22, 1.0 op_sel:[1,0,0]
	v_pk_fma_f32 v[116:117], v[118:119], v[82:83], v[116:117]
	v_cvt_scalef32_pk_f32_fp4 v[118:119], v22, 1.0 op_sel:[0,1,0]
	v_pk_fma_f32 v[116:117], v[118:119], v[84:85], v[116:117]
	v_cvt_scalef32_pk_f32_fp4 v[118:119], v22, 1.0 op_sel:[1,1,0]
	v_pk_fma_f32 v[116:117], v[118:119], v[86:87], v[116:117]
	v_cvt_scalef32_pk_f32_fp4 v[118:119], v23, 1.0
	v_pk_fma_f32 v[116:117], v[118:119], v[88:89], v[116:117]
	v_cvt_scalef32_pk_f32_fp4 v[118:119], v23, 1.0 op_sel:[1,0,0]
	v_pk_fma_f32 v[116:117], v[118:119], v[90:91], v[116:117]
	v_cvt_scalef32_pk_f32_fp4 v[118:119], v23, 1.0 op_sel:[0,1,0]
	v_pk_fma_f32 v[116:117], v[118:119], v[92:93], v[116:117]
	v_cvt_scalef32_pk_f32_fp4 v[118:119], v23, 1.0 op_sel:[1,1,0]
	v_pk_fma_f32 v[116:117], v[118:119], v[94:95], v[116:117]
	s_waitcnt vmcnt(9)
	v_cvt_scalef32_pk_f32_fp4 v[118:119], v24, 1.0 op_sel:[1,0,0]
	v_add_f32_e32 v120, v116, v117
	v_cvt_scalef32_pk_f32_fp4 v[116:117], v24, 1.0
	v_pk_fma_f32 v[116:117], v[116:117], v[64:65], 0 op_sel_hi:[1,1,0]
	v_add_f32_dpp v107, v107, v107 quad_perm:[2,3,0,1] row_mask:0xf bank_mask:0xf bound_ctrl:1
	v_pk_fma_f32 v[116:117], v[118:119], v[66:67], v[116:117]
	v_cvt_scalef32_pk_f32_fp4 v[118:119], v24, 1.0 op_sel:[0,1,0]
	v_pk_fma_f32 v[116:117], v[118:119], v[68:69], v[116:117]
	v_cvt_scalef32_pk_f32_fp4 v[118:119], v24, 1.0 op_sel:[1,1,0]
	v_pk_fma_f32 v[116:117], v[118:119], v[70:71], v[116:117]
	v_cvt_scalef32_pk_f32_fp4 v[118:119], v25, 1.0
	v_pk_fma_f32 v[116:117], v[118:119], v[72:73], v[116:117]
	v_cvt_scalef32_pk_f32_fp4 v[118:119], v25, 1.0 op_sel:[1,0,0]
	v_pk_fma_f32 v[116:117], v[118:119], v[74:75], v[116:117]
	v_cvt_scalef32_pk_f32_fp4 v[118:119], v25, 1.0 op_sel:[0,1,0]
	v_pk_fma_f32 v[116:117], v[118:119], v[76:77], v[116:117]
	v_cvt_scalef32_pk_f32_fp4 v[118:119], v25, 1.0 op_sel:[1,1,0]
	v_pk_fma_f32 v[116:117], v[118:119], v[78:79], v[116:117]
	v_cvt_scalef32_pk_f32_fp4 v[118:119], v26, 1.0
	v_pk_fma_f32 v[116:117], v[118:119], v[80:81], v[116:117]
	v_cvt_scalef32_pk_f32_fp4 v[118:119], v26, 1.0 op_sel:[1,0,0]
	v_pk_fma_f32 v[116:117], v[118:119], v[82:83], v[116:117]
	v_cvt_scalef32_pk_f32_fp4 v[118:119], v26, 1.0 op_sel:[0,1,0]
	v_pk_fma_f32 v[116:117], v[118:119], v[84:85], v[116:117]
	v_cvt_scalef32_pk_f32_fp4 v[118:119], v26, 1.0 op_sel:[1,1,0]
	v_pk_fma_f32 v[116:117], v[118:119], v[86:87], v[116:117]
	v_cvt_scalef32_pk_f32_fp4 v[118:119], v27, 1.0
	v_pk_fma_f32 v[116:117], v[118:119], v[88:89], v[116:117]
	v_cvt_scalef32_pk_f32_fp4 v[118:119], v27, 1.0 op_sel:[1,0,0]
	v_pk_fma_f32 v[116:117], v[118:119], v[90:91], v[116:117]
	v_cvt_scalef32_pk_f32_fp4 v[118:119], v27, 1.0 op_sel:[0,1,0]
	v_pk_fma_f32 v[116:117], v[118:119], v[92:93], v[116:117]
	v_cvt_scalef32_pk_f32_fp4 v[118:119], v27, 1.0 op_sel:[1,1,0]
	v_pk_fma_f32 v[116:117], v[118:119], v[94:95], v[116:117]
	s_waitcnt vmcnt(8)
; #define PU_LOAD(BUF, EV, S0) do { _Pragma("unroll") for (int i = 0; i < 8; ++i) { const int row_ = __builtin_amdgcn_readlane(EV, (S0) + i); BUF[i & 3][i >> 2] = *(const u32x4*)(PU8 + (size_t)row_ * 1024 + lane * 16); } } while (0)
; __global__ void __launch_bounds__(NT, 2) mk_fwd(Args args) {
;     ...
;             float act0 = 0.f, act1 = 0.f;
;             u32x4 bA[4][2], bB[4][2];
; #pragma unroll
;             for (int hh = 0; hh < 2; ++hh) {
;                 const int ev = hh ? e1 : e0; const float gv = hh ? g1 : g0; float dv = 0.f;
;                 PU_LOAD(bA, ev, 0);
; #pragma unroll 1
;                 for (int s = 0; s < 64; s += 16) {
;                     PU_LOAD(bB, ev, s + 8);
;                     PU_DOT4(bA, 0, s); PU_DOT4(bA, 1, s + 4);
;                     if (s + 16 < 64) PU_LOAD(bA, ev, s + 16);
;                     PU_DOT4(bB, 0, s + 8); PU_DOT4(bB, 1, s + 12);
	v_cvt_scalef32_pk_f32_fp4 v[118:119], v28, 1.0 op_sel:[1,0,0]
	v_add_f32_e32 v121, v116, v117
	v_cvt_scalef32_pk_f32_fp4 v[116:117], v28, 1.0
	v_pk_fma_f32 v[116:117], v[116:117], v[64:65], 0 op_sel_hi:[1,1,0]
	v_add_f32_dpp v107, v107, v107 row_half_mirror row_mask:0xf bank_mask:0xf bound_ctrl:1
	v_pk_fma_f32 v[116:117], v[118:119], v[66:67], v[116:117]
	v_cvt_scalef32_pk_f32_fp4 v[118:119], v28, 1.0 op_sel:[0,1,0]
	v_pk_fma_f32 v[116:117], v[118:119], v[68:69], v[116:117]
	v_cvt_scalef32_pk_f32_fp4 v[118:119], v28, 1.0 op_sel:[1,1,0]
	v_pk_fma_f32 v[116:117], v[118:119], v[70:71], v[116:117]
	v_cvt_scalef32_pk_f32_fp4 v[118:119], v29, 1.0
	v_pk_fma_f32 v[116:117], v[118:119], v[72:73], v[116:117]
	v_cvt_scalef32_pk_f32_fp4 v[118:119], v29, 1.0 op_sel:[1,0,0]
	v_pk_fma_f32 v[116:117], v[118:119], v[74:75], v[116:117]
	v_cvt_scalef32_pk_f32_fp4 v[118:119], v29, 1.0 op_sel:[0,1,0]
	v_pk_fma_f32 v[116:117], v[118:119], v[76:77], v[116:117]
	v_cvt_scalef32_pk_f32_fp4 v[118:119], v29, 1.0 op_sel:[1,1,0]
	v_pk_fma_f32 v[116:117], v[118:119], v[78:79], v[116:117]
	v_cvt_scalef32_pk_f32_fp4 v[118:119], v30, 1.0
	v_pk_fma_f32 v[116:117], v[118:119], v[80:81], v[116:117]
	v_cvt_scalef32_pk_f32_fp4 v[118:119], v30, 1.0 op_sel:[1,0,0]
	v_pk_fma_f32 v[116:117], v[118:119], v[82:83], v[116:117]
	v_cvt_scalef32_pk_f32_fp4 v[118:119], v30, 1.0 op_sel:[0,1,0]
	v_pk_fma_f32 v[116:117], v[118:119], v[84:85], v[116:117]
	v_cvt_scalef32_pk_f32_fp4 v[118:119], v30, 1.0 op_sel:[1,1,0]
	v_pk_fma_f32 v[116:117], v[118:119], v[86:87], v[116:117]
	v_cvt_scalef32_pk_f32_fp4 v[118:119], v31, 1.0
	v_pk_fma_f32 v[116:117], v[118:119], v[88:89], v[116:117]
	v_cvt_scalef32_pk_f32_fp4 v[118:119], v31, 1.0 op_sel:[1,0,0]
	v_pk_fma_f32 v[116:117], v[118:119], v[90:91], v[116:117]
	v_cvt_scalef32_pk_f32_fp4 v[118:119], v31, 1.0 op_sel:[0,1,0]
	v_pk_fma_f32 v[116:117], v[118:119], v[92:93], v[116:117]
	v_cvt_scalef32_pk_f32_fp4 v[118:119], v31, 1.0 op_sel:[1,1,0]
	v_pk_fma_f32 v[116:117], v[118:119], v[94:95], v[116:117]
	v_add_f32_dpp v107, v107, v107 row_mirror row_mask:0xf bank_mask:0xf bound_ctrl:1
	v_add_f32_e32 v116, v116, v117
	v_cndmask_b32_e64 v117, v115, v121, s[0:1]
	v_cndmask_b32_e64 v118, v120, v116, s[0:1]
	ds_bpermute_b32 v117, v129, v117
	ds_bpermute_b32 v118, v129, v118
	v_cndmask_b32_e64 v115, v121, v115, s[0:1]
	v_cndmask_b32_e64 v116, v116, v120, s[0:1]
	s_add_i32 s12, s10, 16
	s_waitcnt lgkmcnt(1)
	v_add_f32_e32 v117, v115, v117
	s_waitcnt lgkmcnt(0)
	v_add_f32_e32 v116, v116, v118
	v_cndmask_b32_e64 v115, v117, v116, s[2:3]
	ds_bpermute_b32 v118, v146, v115
	ds_bpermute_b32 v115, v147, v107
	v_cndmask_b32_e64 v107, v116, v117, s[2:3]
	s_cmp_gt_u32 s10, 47
	s_cselect_b64 s[4:5], -1, 0
	s_waitcnt lgkmcnt(1)
	v_add_f32_e32 v107, v107, v118
	s_and_b64 vcc, exec, s[4:5]
	s_nop 0
	v_add_f32_dpp v107, v107, v107 quad_perm:[1,0,3,2] row_mask:0xf bank_mask:0xf bound_ctrl:1
	s_nop 1
	v_add_f32_dpp v107, v107, v107 quad_perm:[2,3,0,1] row_mask:0xf bank_mask:0xf bound_ctrl:1
	s_nop 1
	v_add_f32_dpp v107, v107, v107 row_half_mirror row_mask:0xf bank_mask:0xf bound_ctrl:1
	s_nop 1
	v_add_f32_dpp v107, v107, v107 row_mirror row_mask:0xf bank_mask:0xf bound_ctrl:1
	ds_bpermute_b32 v107, v147, v107
	s_cbranch_vccnz .Lp10_dmy_898
	v_readlane_b32 s30, v106, s12
	s_ashr_i32 s31, s30, 31
	s_lshl_b64 s[30:31], s[30:31], 10
	s_add_i32 s14, s10, 17
	v_lshl_add_u64 v[8:9], v[98:99], 0, s[30:31]
	v_readlane_b32 s30, v106, s14
	s_ashr_i32 s31, s30, 31
	s_lshl_b64 s[30:31], s[30:31], 10
	s_add_i32 s14, s10, 18
	v_lshl_add_u64 v[10:11], v[98:99], 0, s[30:31]
	v_readlane_b32 s30, v106, s14
	s_ashr_i32 s31, s30, 31
	s_lshl_b64 s[30:31], s[30:31], 10
	s_add_i32 s14, s10, 19
	v_lshl_add_u64 v[16:17], v[98:99], 0, s[30:31]
	v_readlane_b32 s30, v106, s14
	s_ashr_i32 s31, s30, 31
	s_lshl_b64 s[30:31], s[30:31], 10
	s_add_i32 s14, s10, 20
	v_lshl_add_u64 v[18:19], v[98:99], 0, s[30:31]
	v_readlane_b32 s30, v106, s14
	s_ashr_i32 s31, s30, 31
	s_lshl_b64 s[30:31], s[30:31], 10
	s_add_i32 s14, s10, 21
	v_lshl_add_u64 v[24:25], v[98:99], 0, s[30:31]
	v_readlane_b32 s30, v106, s14
	s_ashr_i32 s31, s30, 31
	s_lshl_b64 s[30:31], s[30:31], 10
	s_add_i32 s14, s10, 22
	v_lshl_add_u64 v[26:27], v[98:99], 0, s[30:31]
	v_readlane_b32 s30, v106, s14
	s_ashr_i32 s31, s30, 31
	s_lshl_b64 s[30:31], s[30:31], 10
	s_add_i32 s14, s10, 23
	global_load_dwordx4 v[0:3], v[8:9], off
	global_load_dwordx4 v[4:7], v[10:11], off
	s_nop 0
	global_load_dwordx4 v[8:11], v[16:17], off
	global_load_dwordx4 v[12:15], v[18:19], off
	s_nop 0
	global_load_dwordx4 v[16:19], v[24:25], off
	global_load_dwordx4 v[20:23], v[26:27], off
	v_lshl_add_u64 v[24:25], v[98:99], 0, s[30:31]
	v_readlane_b32 s30, v106, s14
	s_ashr_i32 s31, s30, 31
	s_lshl_b64 s[30:31], s[30:31], 10
	v_lshl_add_u64 v[28:29], v[98:99], 0, s[30:31]
	global_load_dwordx4 v[24:27], v[24:25], off
	s_nop 0
	global_load_dwordx4 v[28:31], v[28:29], off
	s_branch .LBB0_898

.LBB0_898:
	s_waitcnt vmcnt(15)
	v_cvt_scalef32_pk_f32_fp4 v[116:117], v60, 1.0
	v_pk_fma_f32 v[116:117], v[116:117], v[64:65], 0 op_sel_hi:[1,1,0]
	v_cvt_scalef32_pk_f32_fp4 v[118:119], v60, 1.0 op_sel:[1,0,0]
	v_pk_fma_f32 v[116:117], v[118:119], v[66:67], v[116:117]
	v_cvt_scalef32_pk_f32_fp4 v[118:119], v60, 1.0 op_sel:[0,1,0]
	v_pk_fma_f32 v[116:117], v[118:119], v[68:69], v[116:117]
	v_cvt_scalef32_pk_f32_fp4 v[118:119], v60, 1.0 op_sel:[1,1,0]
	v_pk_fma_f32 v[116:117], v[118:119], v[70:71], v[116:117]
	v_cvt_scalef32_pk_f32_fp4 v[118:119], v61, 1.0
	v_pk_fma_f32 v[116:117], v[118:119], v[72:73], v[116:117]
	v_cvt_scalef32_pk_f32_fp4 v[118:119], v61, 1.0 op_sel:[1,0,0]
	v_pk_fma_f32 v[116:117], v[118:119], v[74:75], v[116:117]
	v_cvt_scalef32_pk_f32_fp4 v[118:119], v61, 1.0 op_sel:[0,1,0]
	v_pk_fma_f32 v[116:117], v[118:119], v[76:77], v[116:117]
	v_cvt_scalef32_pk_f32_fp4 v[60:61], v61, 1.0 op_sel:[1,1,0]
	v_pk_fma_f32 v[60:61], v[60:61], v[78:79], v[116:117]
	v_cvt_scalef32_pk_f32_fp4 v[116:117], v62, 1.0
	v_pk_fma_f32 v[60:61], v[116:117], v[80:81], v[60:61]
	v_cvt_scalef32_pk_f32_fp4 v[116:117], v62, 1.0 op_sel:[1,0,0]
	v_pk_fma_f32 v[60:61], v[116:117], v[82:83], v[60:61]
	v_cvt_scalef32_pk_f32_fp4 v[116:117], v62, 1.0 op_sel:[0,1,0]
	v_pk_fma_f32 v[60:61], v[116:117], v[84:85], v[60:61]
	v_cvt_scalef32_pk_f32_fp4 v[116:117], v62, 1.0 op_sel:[1,1,0]
	v_pk_fma_f32 v[60:61], v[116:117], v[86:87], v[60:61]
	v_cvt_scalef32_pk_f32_fp4 v[116:117], v63, 1.0
	v_pk_fma_f32 v[60:61], v[116:117], v[88:89], v[60:61]
	v_cvt_scalef32_pk_f32_fp4 v[116:117], v63, 1.0 op_sel:[1,0,0]
	v_pk_fma_f32 v[60:61], v[116:117], v[90:91], v[60:61]
	v_cvt_scalef32_pk_f32_fp4 v[116:117], v63, 1.0 op_sel:[0,1,0]
	v_pk_fma_f32 v[60:61], v[116:117], v[92:93], v[60:61]
	v_cvt_scalef32_pk_f32_fp4 v[62:63], v63, 1.0 op_sel:[1,1,0]
	v_pk_fma_f32 v[60:61], v[62:63], v[94:95], v[60:61]
	s_waitcnt vmcnt(14)
	v_cvt_scalef32_pk_f32_fp4 v[62:63], v52, 1.0 op_sel:[1,0,0]
	v_add_f32_e32 v116, v60, v61
	v_cvt_scalef32_pk_f32_fp4 v[60:61], v52, 1.0
	v_pk_fma_f32 v[60:61], v[60:61], v[64:65], 0 op_sel_hi:[1,1,0]
	v_cmp_eq_u32_e32 vcc, s10, v148
	v_pk_fma_f32 v[60:61], v[62:63], v[66:67], v[60:61]
	v_cvt_scalef32_pk_f32_fp4 v[62:63], v52, 1.0 op_sel:[0,1,0]
	v_pk_fma_f32 v[60:61], v[62:63], v[68:69], v[60:61]
	v_cvt_scalef32_pk_f32_fp4 v[62:63], v52, 1.0 op_sel:[1,1,0]
	v_pk_fma_f32 v[60:61], v[62:63], v[70:71], v[60:61]
	v_cvt_scalef32_pk_f32_fp4 v[62:63], v53, 1.0
	v_pk_fma_f32 v[60:61], v[62:63], v[72:73], v[60:61]
	v_cvt_scalef32_pk_f32_fp4 v[62:63], v53, 1.0 op_sel:[1,0,0]
	v_pk_fma_f32 v[60:61], v[62:63], v[74:75], v[60:61]
	v_cvt_scalef32_pk_f32_fp4 v[62:63], v53, 1.0 op_sel:[0,1,0]
	v_pk_fma_f32 v[60:61], v[62:63], v[76:77], v[60:61]
	v_cvt_scalef32_pk_f32_fp4 v[52:53], v53, 1.0 op_sel:[1,1,0]
	v_pk_fma_f32 v[52:53], v[52:53], v[78:79], v[60:61]
	v_cvt_scalef32_pk_f32_fp4 v[60:61], v54, 1.0
	v_pk_fma_f32 v[52:53], v[60:61], v[80:81], v[52:53]
	v_cvt_scalef32_pk_f32_fp4 v[60:61], v54, 1.0 op_sel:[1,0,0]
	v_pk_fma_f32 v[52:53], v[60:61], v[82:83], v[52:53]
	v_cvt_scalef32_pk_f32_fp4 v[60:61], v54, 1.0 op_sel:[0,1,0]
	v_pk_fma_f32 v[52:53], v[60:61], v[84:85], v[52:53]
	v_cvt_scalef32_pk_f32_fp4 v[60:61], v54, 1.0 op_sel:[1,1,0]
	v_pk_fma_f32 v[52:53], v[60:61], v[86:87], v[52:53]
	v_cvt_scalef32_pk_f32_fp4 v[60:61], v55, 1.0
	v_pk_fma_f32 v[52:53], v[60:61], v[88:89], v[52:53]
	v_cvt_scalef32_pk_f32_fp4 v[60:61], v55, 1.0 op_sel:[1,0,0]
	v_pk_fma_f32 v[52:53], v[60:61], v[90:91], v[52:53]
	v_cvt_scalef32_pk_f32_fp4 v[60:61], v55, 1.0 op_sel:[0,1,0]
	v_pk_fma_f32 v[52:53], v[60:61], v[92:93], v[52:53]
	v_cvt_scalef32_pk_f32_fp4 v[54:55], v55, 1.0 op_sel:[1,1,0]
	v_pk_fma_f32 v[52:53], v[54:55], v[94:95], v[52:53]
	s_waitcnt vmcnt(13)
	v_cvt_scalef32_pk_f32_fp4 v[54:55], v48, 1.0 op_sel:[1,0,0]
	v_add_f32_e32 v60, v52, v53
	v_cvt_scalef32_pk_f32_fp4 v[52:53], v48, 1.0
	v_pk_fma_f32 v[52:53], v[52:53], v[64:65], 0 op_sel_hi:[1,1,0]
	s_nop 0
	v_pk_fma_f32 v[52:53], v[54:55], v[66:67], v[52:53]
	v_cvt_scalef32_pk_f32_fp4 v[54:55], v48, 1.0 op_sel:[0,1,0]
	v_pk_fma_f32 v[52:53], v[54:55], v[68:69], v[52:53]
	v_cvt_scalef32_pk_f32_fp4 v[54:55], v48, 1.0 op_sel:[1,1,0]
	v_pk_fma_f32 v[52:53], v[54:55], v[70:71], v[52:53]
	v_cvt_scalef32_pk_f32_fp4 v[54:55], v49, 1.0
	v_pk_fma_f32 v[52:53], v[54:55], v[72:73], v[52:53]
	v_cvt_scalef32_pk_f32_fp4 v[54:55], v49, 1.0 op_sel:[1,0,0]
	v_pk_fma_f32 v[52:53], v[54:55], v[74:75], v[52:53]
	v_cvt_scalef32_pk_f32_fp4 v[54:55], v49, 1.0 op_sel:[0,1,0]
	v_pk_fma_f32 v[52:53], v[54:55], v[76:77], v[52:53]
	v_cvt_scalef32_pk_f32_fp4 v[48:49], v49, 1.0 op_sel:[1,1,0]
	v_pk_fma_f32 v[48:49], v[48:49], v[78:79], v[52:53]
	v_cvt_scalef32_pk_f32_fp4 v[52:53], v50, 1.0
	v_pk_fma_f32 v[48:49], v[52:53], v[80:81], v[48:49]
	v_cvt_scalef32_pk_f32_fp4 v[52:53], v50, 1.0 op_sel:[1,0,0]
	v_pk_fma_f32 v[48:49], v[52:53], v[82:83], v[48:49]
	v_cvt_scalef32_pk_f32_fp4 v[52:53], v50, 1.0 op_sel:[0,1,0]
	v_pk_fma_f32 v[48:49], v[52:53], v[84:85], v[48:49]
	v_cvt_scalef32_pk_f32_fp4 v[52:53], v50, 1.0 op_sel:[1,1,0]
	v_pk_fma_f32 v[48:49], v[52:53], v[86:87], v[48:49]
	v_cvt_scalef32_pk_f32_fp4 v[52:53], v51, 1.0
	v_pk_fma_f32 v[48:49], v[52:53], v[88:89], v[48:49]
	v_cvt_scalef32_pk_f32_fp4 v[52:53], v51, 1.0 op_sel:[1,0,0]
	v_pk_fma_f32 v[48:49], v[52:53], v[90:91], v[48:49]
	v_cvt_scalef32_pk_f32_fp4 v[52:53], v51, 1.0 op_sel:[0,1,0]
	v_pk_fma_f32 v[48:49], v[52:53], v[92:93], v[48:49]
	v_cvt_scalef32_pk_f32_fp4 v[50:51], v51, 1.0 op_sel:[1,1,0]
	v_pk_fma_f32 v[48:49], v[50:51], v[94:95], v[48:49]
	s_waitcnt vmcnt(12)
	v_cvt_scalef32_pk_f32_fp4 v[50:51], v40, 1.0 op_sel:[1,0,0]
	v_add_f32_e32 v52, v48, v49
	v_cvt_scalef32_pk_f32_fp4 v[48:49], v40, 1.0
	v_pk_fma_f32 v[48:49], v[48:49], v[64:65], 0 op_sel_hi:[1,1,0]
	s_nop 0
	v_pk_fma_f32 v[48:49], v[50:51], v[66:67], v[48:49]
	v_cvt_scalef32_pk_f32_fp4 v[50:51], v40, 1.0 op_sel:[0,1,0]
	v_pk_fma_f32 v[48:49], v[50:51], v[68:69], v[48:49]
	v_cvt_scalef32_pk_f32_fp4 v[50:51], v40, 1.0 op_sel:[1,1,0]
	v_pk_fma_f32 v[48:49], v[50:51], v[70:71], v[48:49]
	v_cvt_scalef32_pk_f32_fp4 v[50:51], v41, 1.0
	v_pk_fma_f32 v[48:49], v[50:51], v[72:73], v[48:49]
	v_cvt_scalef32_pk_f32_fp4 v[50:51], v41, 1.0 op_sel:[1,0,0]
	v_pk_fma_f32 v[48:49], v[50:51], v[74:75], v[48:49]
	v_cvt_scalef32_pk_f32_fp4 v[50:51], v41, 1.0 op_sel:[0,1,0]
	v_pk_fma_f32 v[48:49], v[50:51], v[76:77], v[48:49]
	v_cvt_scalef32_pk_f32_fp4 v[40:41], v41, 1.0 op_sel:[1,1,0]
	v_pk_fma_f32 v[40:41], v[40:41], v[78:79], v[48:49]
	v_cvt_scalef32_pk_f32_fp4 v[48:49], v42, 1.0
	v_pk_fma_f32 v[40:41], v[48:49], v[80:81], v[40:41]
	v_cvt_scalef32_pk_f32_fp4 v[48:49], v42, 1.0 op_sel:[1,0,0]
	v_pk_fma_f32 v[40:41], v[48:49], v[82:83], v[40:41]
	v_cvt_scalef32_pk_f32_fp4 v[48:49], v42, 1.0 op_sel:[0,1,0]
	v_pk_fma_f32 v[40:41], v[48:49], v[84:85], v[40:41]
	v_cvt_scalef32_pk_f32_fp4 v[48:49], v42, 1.0 op_sel:[1,1,0]
	v_pk_fma_f32 v[40:41], v[48:49], v[86:87], v[40:41]
	v_cvt_scalef32_pk_f32_fp4 v[48:49], v43, 1.0
	v_pk_fma_f32 v[40:41], v[48:49], v[88:89], v[40:41]
	v_cvt_scalef32_pk_f32_fp4 v[48:49], v43, 1.0 op_sel:[1,0,0]
	v_pk_fma_f32 v[40:41], v[48:49], v[90:91], v[40:41]
	v_cvt_scalef32_pk_f32_fp4 v[48:49], v43, 1.0 op_sel:[0,1,0]
	v_pk_fma_f32 v[40:41], v[48:49], v[92:93], v[40:41]
	v_cvt_scalef32_pk_f32_fp4 v[42:43], v43, 1.0 op_sel:[1,1,0]
	v_pk_fma_f32 v[40:41], v[42:43], v[94:95], v[40:41]
	v_cndmask_b32_e64 v43, v52, v116, s[0:1]
	v_add_f32_e32 v40, v40, v41
	v_cndmask_b32_e64 v41, v116, v52, s[0:1]
	v_cndmask_b32_e64 v42, v60, v40, s[0:1]
	ds_bpermute_b32 v41, v129, v41
	ds_bpermute_b32 v42, v129, v42
	v_cndmask_b32_e64 v40, v40, v60, s[0:1]
	s_waitcnt lgkmcnt(3)
	v_cndmask_b32_e32 v48, v109, v115, vcc
	v_cmp_eq_u32_e32 vcc, s10, v151
	s_waitcnt lgkmcnt(1)
	v_add_f32_e32 v41, v43, v41
	s_waitcnt lgkmcnt(0)
	v_add_f32_e32 v40, v40, v42
	v_cndmask_b32_e64 v42, v41, v40, s[2:3]
	ds_bpermute_b32 v42, v146, v42
	v_cndmask_b32_e64 v40, v40, v41, s[2:3]
	s_waitcnt lgkmcnt(0)
	v_add_f32_e32 v40, v40, v42
	s_nop 1
	v_add_f32_dpp v40, v40, v40 quad_perm:[1,0,3,2] row_mask:0xf bank_mask:0xf bound_ctrl:1
	s_waitcnt vmcnt(11)
	v_cvt_scalef32_pk_f32_fp4 v[42:43], v36, 1.0 op_sel:[1,0,0]
	v_add_f32_dpp v40, v40, v40 quad_perm:[2,3,0,1] row_mask:0xf bank_mask:0xf bound_ctrl:1
	s_nop 1
	v_add_f32_dpp v40, v40, v40 row_half_mirror row_mask:0xf bank_mask:0xf bound_ctrl:1
	s_nop 1
	v_add_f32_dpp v49, v40, v40 row_mirror row_mask:0xf bank_mask:0xf bound_ctrl:1
	v_cvt_scalef32_pk_f32_fp4 v[40:41], v36, 1.0
	v_pk_fma_f32 v[40:41], v[40:41], v[64:65], 0 op_sel_hi:[1,1,0]
	s_nop 0
	v_pk_fma_f32 v[40:41], v[42:43], v[66:67], v[40:41]
	v_cvt_scalef32_pk_f32_fp4 v[42:43], v36, 1.0 op_sel:[0,1,0]
	v_pk_fma_f32 v[40:41], v[42:43], v[68:69], v[40:41]
	v_cvt_scalef32_pk_f32_fp4 v[42:43], v36, 1.0 op_sel:[1,1,0]
	v_pk_fma_f32 v[40:41], v[42:43], v[70:71], v[40:41]
	v_cvt_scalef32_pk_f32_fp4 v[42:43], v37, 1.0
	v_pk_fma_f32 v[40:41], v[42:43], v[72:73], v[40:41]
	v_cvt_scalef32_pk_f32_fp4 v[42:43], v37, 1.0 op_sel:[1,0,0]
	v_pk_fma_f32 v[40:41], v[42:43], v[74:75], v[40:41]
	v_cvt_scalef32_pk_f32_fp4 v[42:43], v37, 1.0 op_sel:[0,1,0]
	v_pk_fma_f32 v[40:41], v[42:43], v[76:77], v[40:41]
	v_cvt_scalef32_pk_f32_fp4 v[36:37], v37, 1.0 op_sel:[1,1,0]
	v_pk_fma_f32 v[36:37], v[36:37], v[78:79], v[40:41]
	v_cvt_scalef32_pk_f32_fp4 v[40:41], v38, 1.0
	v_pk_fma_f32 v[36:37], v[40:41], v[80:81], v[36:37]
	v_cvt_scalef32_pk_f32_fp4 v[40:41], v38, 1.0 op_sel:[1,0,0]
	v_pk_fma_f32 v[36:37], v[40:41], v[82:83], v[36:37]
	v_cvt_scalef32_pk_f32_fp4 v[40:41], v38, 1.0 op_sel:[0,1,0]
	v_pk_fma_f32 v[36:37], v[40:41], v[84:85], v[36:37]
	v_cvt_scalef32_pk_f32_fp4 v[40:41], v38, 1.0 op_sel:[1,1,0]
	v_pk_fma_f32 v[36:37], v[40:41], v[86:87], v[36:37]
	v_cvt_scalef32_pk_f32_fp4 v[40:41], v39, 1.0
	v_pk_fma_f32 v[36:37], v[40:41], v[88:89], v[36:37]
	v_cvt_scalef32_pk_f32_fp4 v[40:41], v39, 1.0 op_sel:[1,0,0]
	v_pk_fma_f32 v[36:37], v[40:41], v[90:91], v[36:37]
	v_cvt_scalef32_pk_f32_fp4 v[40:41], v39, 1.0 op_sel:[0,1,0]
	v_pk_fma_f32 v[36:37], v[40:41], v[92:93], v[36:37]
	v_cvt_scalef32_pk_f32_fp4 v[38:39], v39, 1.0 op_sel:[1,1,0]
	v_pk_fma_f32 v[36:37], v[38:39], v[94:95], v[36:37]
	s_waitcnt vmcnt(10)
	v_cvt_scalef32_pk_f32_fp4 v[38:39], v32, 1.0 op_sel:[1,0,0]
	v_add_f32_e32 v40, v36, v37
	v_cvt_scalef32_pk_f32_fp4 v[36:37], v32, 1.0
	v_pk_fma_f32 v[36:37], v[36:37], v[64:65], 0 op_sel_hi:[1,1,0]
	s_nop 0
	v_pk_fma_f32 v[36:37], v[38:39], v[66:67], v[36:37]
	v_cvt_scalef32_pk_f32_fp4 v[38:39], v32, 1.0 op_sel:[0,1,0]
	v_pk_fma_f32 v[36:37], v[38:39], v[68:69], v[36:37]
	v_cvt_scalef32_pk_f32_fp4 v[38:39], v32, 1.0 op_sel:[1,1,0]
	v_pk_fma_f32 v[36:37], v[38:39], v[70:71], v[36:37]
	v_cvt_scalef32_pk_f32_fp4 v[38:39], v33, 1.0
	v_pk_fma_f32 v[36:37], v[38:39], v[72:73], v[36:37]
	v_cvt_scalef32_pk_f32_fp4 v[38:39], v33, 1.0 op_sel:[1,0,0]
	v_pk_fma_f32 v[36:37], v[38:39], v[74:75], v[36:37]
	v_cvt_scalef32_pk_f32_fp4 v[38:39], v33, 1.0 op_sel:[0,1,0]
	v_pk_fma_f32 v[36:37], v[38:39], v[76:77], v[36:37]
	v_cvt_scalef32_pk_f32_fp4 v[32:33], v33, 1.0 op_sel:[1,1,0]
	v_pk_fma_f32 v[32:33], v[32:33], v[78:79], v[36:37]
	v_cvt_scalef32_pk_f32_fp4 v[36:37], v34, 1.0
	v_pk_fma_f32 v[32:33], v[36:37], v[80:81], v[32:33]
	v_cvt_scalef32_pk_f32_fp4 v[36:37], v34, 1.0 op_sel:[1,0,0]
	v_pk_fma_f32 v[32:33], v[36:37], v[82:83], v[32:33]
	v_cvt_scalef32_pk_f32_fp4 v[36:37], v34, 1.0 op_sel:[0,1,0]
	v_pk_fma_f32 v[32:33], v[36:37], v[84:85], v[32:33]
	v_cvt_scalef32_pk_f32_fp4 v[36:37], v34, 1.0 op_sel:[1,1,0]
	v_pk_fma_f32 v[32:33], v[36:37], v[86:87], v[32:33]
	v_cvt_scalef32_pk_f32_fp4 v[36:37], v35, 1.0
	v_pk_fma_f32 v[32:33], v[36:37], v[88:89], v[32:33]
	v_cvt_scalef32_pk_f32_fp4 v[36:37], v35, 1.0 op_sel:[1,0,0]
	v_pk_fma_f32 v[32:33], v[36:37], v[90:91], v[32:33]
	v_cvt_scalef32_pk_f32_fp4 v[36:37], v35, 1.0 op_sel:[0,1,0]
	v_pk_fma_f32 v[32:33], v[36:37], v[92:93], v[32:33]
	v_cvt_scalef32_pk_f32_fp4 v[34:35], v35, 1.0 op_sel:[1,1,0]
	v_pk_fma_f32 v[32:33], v[34:35], v[94:95], v[32:33]
	s_waitcnt vmcnt(9)
; #define PU_LOAD(BUF, EV, S0) do { _Pragma("unroll") for (int i = 0; i < 8; ++i) { const int row_ = __builtin_amdgcn_readlane(EV, (S0) + i); BUF[i & 3][i >> 2] = *(const u32x4*)(PU8 + (size_t)row_ * 1024 + lane * 16); } } while (0)
; __global__ void __launch_bounds__(NT, 2) mk_fwd(Args args) {
;     ...
;             float act0 = 0.f, act1 = 0.f;
;             u32x4 bA[4][2], bB[4][2];
; #pragma unroll
;             for (int hh = 0; hh < 2; ++hh) {
;                 const int ev = hh ? e1 : e0; const float gv = hh ? g1 : g0; float dv = 0.f;
;                 PU_LOAD(bA, ev, 0);
; #pragma unroll 1
;                 for (int s = 0; s < 64; s += 16) {
;                     PU_LOAD(bB, ev, s + 8);
;                     PU_DOT4(bA, 0, s); PU_DOT4(bA, 1, s + 4);
;                     if (s + 16 < 64) PU_LOAD(bA, ev, s + 16);
;                     PU_DOT4(bB, 0, s + 8); PU_DOT4(bB, 1, s + 12);
;                 }
	v_cvt_scalef32_pk_f32_fp4 v[34:35], v56, 1.0 op_sel:[1,0,0]
	v_add_f32_e32 v36, v32, v33
	v_cvt_scalef32_pk_f32_fp4 v[32:33], v56, 1.0
	v_pk_fma_f32 v[32:33], v[32:33], v[64:65], 0 op_sel_hi:[1,1,0]
	s_nop 0
	v_pk_fma_f32 v[32:33], v[34:35], v[66:67], v[32:33]
	v_cvt_scalef32_pk_f32_fp4 v[34:35], v56, 1.0 op_sel:[0,1,0]
	v_pk_fma_f32 v[32:33], v[34:35], v[68:69], v[32:33]
	v_cvt_scalef32_pk_f32_fp4 v[34:35], v56, 1.0 op_sel:[1,1,0]
	v_pk_fma_f32 v[32:33], v[34:35], v[70:71], v[32:33]
	v_cvt_scalef32_pk_f32_fp4 v[34:35], v57, 1.0
	v_pk_fma_f32 v[32:33], v[34:35], v[72:73], v[32:33]
	v_cvt_scalef32_pk_f32_fp4 v[34:35], v57, 1.0 op_sel:[1,0,0]
	v_pk_fma_f32 v[32:33], v[34:35], v[74:75], v[32:33]
	v_cvt_scalef32_pk_f32_fp4 v[34:35], v57, 1.0 op_sel:[0,1,0]
	v_pk_fma_f32 v[32:33], v[34:35], v[76:77], v[32:33]
	v_cvt_scalef32_pk_f32_fp4 v[34:35], v57, 1.0 op_sel:[1,1,0]
	v_pk_fma_f32 v[32:33], v[34:35], v[78:79], v[32:33]
	v_cvt_scalef32_pk_f32_fp4 v[34:35], v58, 1.0
	v_pk_fma_f32 v[32:33], v[34:35], v[80:81], v[32:33]
	v_cvt_scalef32_pk_f32_fp4 v[34:35], v58, 1.0 op_sel:[1,0,0]
	v_pk_fma_f32 v[32:33], v[34:35], v[82:83], v[32:33]
	v_cvt_scalef32_pk_f32_fp4 v[34:35], v58, 1.0 op_sel:[0,1,0]
	v_pk_fma_f32 v[32:33], v[34:35], v[84:85], v[32:33]
	v_cvt_scalef32_pk_f32_fp4 v[34:35], v58, 1.0 op_sel:[1,1,0]
	v_pk_fma_f32 v[32:33], v[34:35], v[86:87], v[32:33]
	v_cvt_scalef32_pk_f32_fp4 v[34:35], v59, 1.0
	v_pk_fma_f32 v[32:33], v[34:35], v[88:89], v[32:33]
	v_cvt_scalef32_pk_f32_fp4 v[34:35], v59, 1.0 op_sel:[1,0,0]
	v_pk_fma_f32 v[32:33], v[34:35], v[90:91], v[32:33]
	v_cvt_scalef32_pk_f32_fp4 v[34:35], v59, 1.0 op_sel:[0,1,0]
	v_pk_fma_f32 v[32:33], v[34:35], v[92:93], v[32:33]
	v_cvt_scalef32_pk_f32_fp4 v[34:35], v59, 1.0 op_sel:[1,1,0]
	v_pk_fma_f32 v[32:33], v[34:35], v[94:95], v[32:33]
	s_waitcnt vmcnt(0)
	v_cvt_scalef32_pk_f32_fp4 v[34:35], v44, 1.0 op_sel:[1,0,0]
	v_add_f32_e32 v37, v32, v33
	v_cvt_scalef32_pk_f32_fp4 v[32:33], v44, 1.0
	v_pk_fma_f32 v[32:33], v[32:33], v[64:65], 0 op_sel_hi:[1,1,0]
	s_nop 0
	v_pk_fma_f32 v[32:33], v[34:35], v[66:67], v[32:33]
	v_cvt_scalef32_pk_f32_fp4 v[34:35], v44, 1.0 op_sel:[0,1,0]
	v_pk_fma_f32 v[32:33], v[34:35], v[68:69], v[32:33]
	v_cvt_scalef32_pk_f32_fp4 v[34:35], v44, 1.0 op_sel:[1,1,0]
	v_pk_fma_f32 v[32:33], v[34:35], v[70:71], v[32:33]
	v_cvt_scalef32_pk_f32_fp4 v[34:35], v45, 1.0
	v_pk_fma_f32 v[32:33], v[34:35], v[72:73], v[32:33]
	v_cvt_scalef32_pk_f32_fp4 v[34:35], v45, 1.0 op_sel:[1,0,0]
	v_pk_fma_f32 v[32:33], v[34:35], v[74:75], v[32:33]
	v_cvt_scalef32_pk_f32_fp4 v[34:35], v45, 1.0 op_sel:[0,1,0]
	v_pk_fma_f32 v[32:33], v[34:35], v[76:77], v[32:33]
	v_cvt_scalef32_pk_f32_fp4 v[34:35], v45, 1.0 op_sel:[1,1,0]
	v_pk_fma_f32 v[32:33], v[34:35], v[78:79], v[32:33]
	v_cvt_scalef32_pk_f32_fp4 v[34:35], v46, 1.0
	v_pk_fma_f32 v[32:33], v[34:35], v[80:81], v[32:33]
	v_cvt_scalef32_pk_f32_fp4 v[34:35], v46, 1.0 op_sel:[1,0,0]
	v_pk_fma_f32 v[32:33], v[34:35], v[82:83], v[32:33]
	v_cvt_scalef32_pk_f32_fp4 v[34:35], v46, 1.0 op_sel:[0,1,0]
	v_pk_fma_f32 v[32:33], v[34:35], v[84:85], v[32:33]
	v_cvt_scalef32_pk_f32_fp4 v[34:35], v46, 1.0 op_sel:[1,1,0]
	v_pk_fma_f32 v[32:33], v[34:35], v[86:87], v[32:33]
	v_cvt_scalef32_pk_f32_fp4 v[34:35], v47, 1.0
	v_pk_fma_f32 v[32:33], v[34:35], v[88:89], v[32:33]
	v_cvt_scalef32_pk_f32_fp4 v[34:35], v47, 1.0 op_sel:[1,0,0]
	v_pk_fma_f32 v[32:33], v[34:35], v[90:91], v[32:33]
	v_cvt_scalef32_pk_f32_fp4 v[34:35], v47, 1.0 op_sel:[0,1,0]
	v_pk_fma_f32 v[32:33], v[34:35], v[92:93], v[32:33]
	v_cvt_scalef32_pk_f32_fp4 v[34:35], v47, 1.0 op_sel:[1,1,0]
	v_pk_fma_f32 v[32:33], v[34:35], v[94:95], v[32:33]
	ds_bpermute_b32 v35, v147, v49
	v_add_f32_e32 v32, v32, v33
	v_cndmask_b32_e64 v33, v40, v37, s[0:1]
	v_cndmask_b32_e64 v34, v36, v32, s[0:1]
	ds_bpermute_b32 v33, v129, v33
	ds_bpermute_b32 v34, v129, v34
	v_cndmask_b32_e64 v37, v37, v40, s[0:1]
	v_cndmask_b32_e64 v32, v32, v36, s[0:1]
	v_cndmask_b32_e32 v36, v48, v107, vcc
	s_waitcnt lgkmcnt(1)
	v_add_f32_e32 v33, v37, v33
	s_waitcnt lgkmcnt(0)
	v_add_f32_e32 v32, v32, v34
	v_cndmask_b32_e64 v34, v33, v32, s[2:3]
	ds_bpermute_b32 v34, v146, v34
	v_cndmask_b32_e64 v32, v32, v33, s[2:3]
	v_cmp_eq_u32_e32 vcc, s10, v150
	s_waitcnt lgkmcnt(0)
	v_add_f32_e32 v32, v32, v34
	s_nop 1
	v_add_f32_dpp v32, v32, v32 quad_perm:[1,0,3,2] row_mask:0xf bank_mask:0xf bound_ctrl:1
	v_cndmask_b32_e32 v35, v36, v35, vcc
	s_andn2_b64 vcc, exec, s[4:5]
	v_add_f32_dpp v32, v32, v32 quad_perm:[2,3,0,1] row_mask:0xf bank_mask:0xf bound_ctrl:1
	v_cmp_eq_u32_e64 s[4:5], s10, v149
	s_nop 0
	v_add_f32_dpp v32, v32, v32 row_half_mirror row_mask:0xf bank_mask:0xf bound_ctrl:1
	s_nop 1
	v_add_f32_dpp v32, v32, v32 row_mirror row_mask:0xf bank_mask:0xf bound_ctrl:1
	ds_bpermute_b32 v32, v147, v32
	s_waitcnt lgkmcnt(0)
	v_cndmask_b32_e64 v109, v35, v32, s[4:5]
	s_cbranch_vccz .LBB0_900
	s_mov_b32 s10, s12
	s_branch .LBB0_896

; #define PV_LOAD(BUF, EV, S0) do { _Pragma("unroll") for (int i = 0; i < 8; ++i) { const int row_ = __builtin_amdgcn_readlane(EV, (S0) + i); BUF[i & 3][i >> 2] = *(const u32x4*)(PV8 + (size_t)row_ * 1024 + lane * 16); } } while (0)
; __global__ void __launch_bounds__(NT, 2) mk_fwd(Args args) {
;     ...
; #pragma unroll
;             for (int hh = 0; hh < 2; ++hh) {
;                 const int ev = hh ? e1 : e0; const float av = hh ? act1 : act0;
;                 PV_LOAD(bA, ev, 0);
; #pragma unroll 1
;                 for (int s = 0; s < 64; s += 16) {
;                     PV_LOAD(bB, ev, s + 8);
;                     PV_ACC(bA, av, s);
;                     if (s + 16 < 64) PV_LOAD(bA, ev, s + 16);
;                     PV_ACC(bB, av, s + 8);
.LBB0_905:
	s_add_i32 s39, s40, 8
	v_readlane_b32 s4, v108, s39
	s_ashr_i32 s5, s4, 31
	s_lshl_b64 s[4:5], s[4:5], 10
	s_add_i32 s38, s40, 9
	v_lshl_add_u64 v[32:33], v[100:101], 0, s[4:5]
	v_readlane_b32 s4, v108, s38
	s_ashr_i32 s5, s4, 31
	s_lshl_b64 s[4:5], s[4:5], 10
	s_add_i32 s37, s40, 10
	v_lshl_add_u64 v[34:35], v[100:101], 0, s[4:5]
	v_readlane_b32 s4, v108, s37
	s_ashr_i32 s5, s4, 31
	s_lshl_b64 s[4:5], s[4:5], 10
	s_add_i32 s36, s40, 11
	global_load_dwordx4 v[84:87], v[32:33], off
	global_load_dwordx4 v[72:75], v[34:35], off
	v_lshl_add_u64 v[32:33], v[100:101], 0, s[4:5]
	v_readlane_b32 s4, v108, s36
	s_ashr_i32 s5, s4, 31
	s_lshl_b64 s[4:5], s[4:5], 10
	s_add_i32 s35, s40, 12
	v_lshl_add_u64 v[34:35], v[100:101], 0, s[4:5]
	v_readlane_b32 s4, v108, s35
	s_ashr_i32 s5, s4, 31
	s_lshl_b64 s[4:5], s[4:5], 10
	s_add_i32 s34, s40, 13
	global_load_dwordx4 v[64:67], v[32:33], off
	global_load_dwordx4 v[56:59], v[34:35], off
	v_lshl_add_u64 v[32:33], v[100:101], 0, s[4:5]
	v_readlane_b32 s4, v108, s34
	s_ashr_i32 s5, s4, 31
	s_lshl_b64 s[4:5], s[4:5], 10
	s_add_i32 s33, s40, 14
	v_lshl_add_u64 v[34:35], v[100:101], 0, s[4:5]
	v_readlane_b32 s4, v108, s33
	s_ashr_i32 s5, s4, 31
	s_lshl_b64 s[4:5], s[4:5], 10
	s_add_i32 s31, s40, 15
	global_load_dwordx4 v[52:55], v[32:33], off
	global_load_dwordx4 v[44:47], v[34:35], off
	v_lshl_add_u64 v[32:33], v[100:101], 0, s[4:5]
	v_readlane_b32 s4, v108, s31
	s_ashr_i32 s5, s4, 31
	s_lshl_b64 s[4:5], s[4:5], 10
	v_lshl_add_u64 v[34:35], v[100:101], 0, s[4:5]
	global_load_dwordx4 v[36:39], v[32:33], off
	s_nop 0
	global_load_dwordx4 v[32:35], v[34:35], off
	s_add_i32 s12, s40, 4
	s_add_i32 s30, s40, 6
	s_add_i32 s4, s40, 1
	s_add_i32 s5, s40, 2
	s_add_i32 s10, s40, 3
	s_add_i32 s14, s40, 5
	s_add_i32 s41, s40, 7
	v_readlane_b32 s16, v159, s12
	v_readlane_b32 s12, v159, s30
	s_add_i32 s30, s40, 16
	s_cmp_gt_u32 s40, 47
	v_readlane_b32 s24, v159, s40
	v_readlane_b32 s22, v159, s4
	v_readlane_b32 s20, v159, s5
	v_readlane_b32 s18, v159, s10
	v_readlane_b32 s14, v159, s14
	s_cselect_b64 s[4:5], -1, 0
	s_cmp_lt_u32 s40, 48
	v_readlane_b32 s10, v159, s41
	s_cbranch_scc0 .Lp10_dmy_907
	v_readlane_b32 s42, v108, s30
	s_ashr_i32 s43, s42, 31
	s_lshl_b64 s[42:43], s[42:43], 10
	s_add_i32 s41, s40, 17
	v_lshl_add_u64 v[0:1], v[100:101], 0, s[42:43]
	v_readlane_b32 s42, v108, s41
	s_ashr_i32 s43, s42, 31
	s_lshl_b64 s[42:43], s[42:43], 10
	s_add_i32 s41, s40, 18
	v_lshl_add_u64 v[2:3], v[100:101], 0, s[42:43]
	v_readlane_b32 s42, v108, s41
	s_ashr_i32 s43, s42, 31
	s_lshl_b64 s[42:43], s[42:43], 10
	s_add_i32 s41, s40, 19
	v_lshl_add_u64 v[8:9], v[100:101], 0, s[42:43]
	v_readlane_b32 s42, v108, s41
	s_ashr_i32 s43, s42, 31
	s_lshl_b64 s[42:43], s[42:43], 10
	s_add_i32 s41, s40, 20
	v_lshl_add_u64 v[10:11], v[100:101], 0, s[42:43]
	v_readlane_b32 s42, v108, s41
	s_ashr_i32 s43, s42, 31
	s_lshl_b64 s[42:43], s[42:43], 10
	s_add_i32 s41, s40, 21
	v_lshl_add_u64 v[16:17], v[100:101], 0, s[42:43]
	v_readlane_b32 s42, v108, s41
	s_ashr_i32 s43, s42, 31
	s_lshl_b64 s[42:43], s[42:43], 10
	s_add_i32 s41, s40, 22
	s_add_i32 s40, s40, 23
	v_lshl_add_u64 v[18:19], v[100:101], 0, s[42:43]
	v_readlane_b32 s42, v108, s41
	v_readlane_b32 s40, v108, s40
	s_ashr_i32 s43, s42, 31
	s_ashr_i32 s41, s40, 31
	s_lshl_b64 s[42:43], s[42:43], 10
	s_lshl_b64 s[40:41], s[40:41], 10
	v_lshl_add_u64 v[24:25], v[100:101], 0, s[42:43]
	v_lshl_add_u64 v[26:27], v[100:101], 0, s[40:41]
	global_load_dwordx4 v[4:7], v[0:1], off
	s_nop 0
	global_load_dwordx4 v[0:3], v[2:3], off
	s_nop 0
	global_load_dwordx4 v[12:15], v[8:9], off
	s_nop 0
	global_load_dwordx4 v[8:11], v[10:11], off
	s_nop 0
	global_load_dwordx4 v[20:23], v[16:17], off
	s_nop 0
	global_load_dwordx4 v[16:19], v[18:19], off
	s_nop 0
	global_load_dwordx4 v[28:31], v[24:25], off
	s_nop 0
	global_load_dwordx4 v[24:27], v[26:27], off
	s_branch .LBB0_907

.LBB0_907:
	v_cvt_scalef32_pk_f32_fp4 v[160:161], v92, 1.0
	v_pk_fma_f32 v[118:119], s[24:25], v[160:161], v[118:119] op_sel_hi:[0,1,1]
	v_cvt_scalef32_pk_f32_fp4 v[160:161], v92, 1.0 op_sel:[1,0,0]
	v_pk_fma_f32 v[122:123], s[24:25], v[160:161], v[122:123] op_sel_hi:[0,1,1]
	v_cvt_scalef32_pk_f32_fp4 v[160:161], v92, 1.0 op_sel:[0,1,0]
	v_pk_fma_f32 v[144:145], s[24:25], v[160:161], v[144:145] op_sel_hi:[0,1,1]
	v_cvt_scalef32_pk_f32_fp4 v[160:161], v92, 1.0 op_sel:[1,1,0]
	v_pk_fma_f32 v[142:143], s[24:25], v[160:161], v[142:143] op_sel_hi:[0,1,1]
	v_cvt_scalef32_pk_f32_fp4 v[160:161], v93, 1.0
	v_pk_fma_f32 v[140:141], s[24:25], v[160:161], v[140:141] op_sel_hi:[0,1,1]
	v_cvt_scalef32_pk_f32_fp4 v[160:161], v93, 1.0 op_sel:[1,0,0]
	v_pk_fma_f32 v[138:139], s[24:25], v[160:161], v[138:139] op_sel_hi:[0,1,1]
	v_cvt_scalef32_pk_f32_fp4 v[160:161], v93, 1.0 op_sel:[0,1,0]
	v_cvt_scalef32_pk_f32_fp4 v[92:93], v93, 1.0 op_sel:[1,1,0]
	v_pk_fma_f32 v[92:93], s[24:25], v[92:93], v[132:133] op_sel_hi:[0,1,1]
	v_cvt_scalef32_pk_f32_fp4 v[132:133], v94, 1.0
	v_pk_fma_f32 v[130:131], s[24:25], v[132:133], v[130:131] op_sel_hi:[0,1,1]
	v_cvt_scalef32_pk_f32_fp4 v[132:133], v94, 1.0 op_sel:[1,0,0]
	v_pk_fma_f32 v[126:127], s[24:25], v[132:133], v[126:127] op_sel_hi:[0,1,1]
	v_cvt_scalef32_pk_f32_fp4 v[132:133], v94, 1.0 op_sel:[0,1,0]
	v_pk_fma_f32 v[124:125], s[24:25], v[132:133], v[124:125] op_sel_hi:[0,1,1]
	v_cvt_scalef32_pk_f32_fp4 v[132:133], v94, 1.0 op_sel:[1,1,0]
	v_pk_fma_f32 v[120:121], s[24:25], v[132:133], v[120:121] op_sel_hi:[0,1,1]
	v_cvt_scalef32_pk_f32_fp4 v[132:133], v95, 1.0
	v_pk_fma_f32 v[116:117], s[24:25], v[132:133], v[116:117] op_sel_hi:[0,1,1]
	v_cvt_scalef32_pk_f32_fp4 v[132:133], v95, 1.0 op_sel:[1,0,0]
	v_pk_fma_f32 v[114:115], s[24:25], v[132:133], v[114:115] op_sel_hi:[0,1,1]
	v_cvt_scalef32_pk_f32_fp4 v[132:133], v95, 1.0 op_sel:[0,1,0]
	v_pk_fma_f32 v[112:113], s[24:25], v[132:133], v[112:113] op_sel_hi:[0,1,1]
	v_cvt_scalef32_pk_f32_fp4 v[94:95], v95, 1.0 op_sel:[1,1,0]
	v_cvt_scalef32_pk_f32_fp4 v[132:133], v88, 1.0 op_sel:[1,1,0]
	v_pk_fma_f32 v[94:95], s[24:25], v[94:95], v[110:111] op_sel_hi:[0,1,1]
	v_cvt_scalef32_pk_f32_fp4 v[110:111], v88, 1.0
	v_pk_fma_f32 v[132:133], s[22:23], v[132:133], v[142:143] op_sel_hi:[0,1,1]
	v_cvt_scalef32_pk_f32_fp4 v[142:143], v89, 1.0
	v_pk_fma_f32 v[110:111], s[22:23], v[110:111], v[118:119] op_sel_hi:[0,1,1]
	v_cvt_scalef32_pk_f32_fp4 v[118:119], v88, 1.0 op_sel:[1,0,0]
	v_pk_fma_f32 v[140:141], s[22:23], v[142:143], v[140:141] op_sel_hi:[0,1,1]
	v_cvt_scalef32_pk_f32_fp4 v[142:143], v89, 1.0 op_sel:[1,0,0]
	v_pk_fma_f32 v[118:119], s[22:23], v[118:119], v[122:123] op_sel_hi:[0,1,1]
	v_cvt_scalef32_pk_f32_fp4 v[122:123], v88, 1.0 op_sel:[0,1,0]
	v_pk_fma_f32 v[138:139], s[22:23], v[142:143], v[138:139] op_sel_hi:[0,1,1]
	v_cvt_scalef32_pk_f32_fp4 v[142:143], v89, 1.0 op_sel:[0,1,0]
	v_cvt_scalef32_pk_f32_fp4 v[88:89], v89, 1.0 op_sel:[1,1,0]
	v_pk_fma_f32 v[88:89], s[22:23], v[88:89], v[92:93] op_sel_hi:[0,1,1]
	v_cvt_scalef32_pk_f32_fp4 v[92:93], v90, 1.0
	v_pk_fma_f32 v[92:93], s[22:23], v[92:93], v[130:131] op_sel_hi:[0,1,1]
	v_cvt_scalef32_pk_f32_fp4 v[130:131], v90, 1.0 op_sel:[1,0,0]
	v_pk_fma_f32 v[126:127], s[22:23], v[130:131], v[126:127] op_sel_hi:[0,1,1]
	v_cvt_scalef32_pk_f32_fp4 v[130:131], v90, 1.0 op_sel:[0,1,0]
	v_pk_fma_f32 v[124:125], s[22:23], v[130:131], v[124:125] op_sel_hi:[0,1,1]
	v_cvt_scalef32_pk_f32_fp4 v[130:131], v90, 1.0 op_sel:[1,1,0]
	v_pk_fma_f32 v[120:121], s[22:23], v[130:131], v[120:121] op_sel_hi:[0,1,1]
	v_cvt_scalef32_pk_f32_fp4 v[130:131], v91, 1.0
	v_pk_fma_f32 v[116:117], s[22:23], v[130:131], v[116:117] op_sel_hi:[0,1,1]
	v_cvt_scalef32_pk_f32_fp4 v[130:131], v91, 1.0 op_sel:[1,0,0]
	v_pk_fma_f32 v[114:115], s[22:23], v[130:131], v[114:115] op_sel_hi:[0,1,1]
	v_cvt_scalef32_pk_f32_fp4 v[130:131], v91, 1.0 op_sel:[0,1,0]
	v_cvt_scalef32_pk_f32_fp4 v[90:91], v91, 1.0 op_sel:[1,1,0]
	v_pk_fma_f32 v[90:91], s[22:23], v[90:91], v[94:95] op_sel_hi:[0,1,1]
	v_cvt_scalef32_pk_f32_fp4 v[94:95], v80, 1.0
	v_pk_fma_f32 v[94:95], s[20:21], v[94:95], v[110:111] op_sel_hi:[0,1,1]
	v_cvt_scalef32_pk_f32_fp4 v[110:111], v80, 1.0 op_sel:[1,0,0]
	v_pk_fma_f32 v[122:123], s[22:23], v[122:123], v[144:145] op_sel_hi:[0,1,1]
	v_pk_fma_f32 v[110:111], s[20:21], v[110:111], v[118:119] op_sel_hi:[0,1,1]
	v_cvt_scalef32_pk_f32_fp4 v[118:119], v80, 1.0 op_sel:[0,1,0]
	v_pk_fma_f32 v[118:119], s[20:21], v[118:119], v[122:123] op_sel_hi:[0,1,1]
	v_cvt_scalef32_pk_f32_fp4 v[122:123], v80, 1.0 op_sel:[1,1,0]
	v_pk_fma_f32 v[122:123], s[20:21], v[122:123], v[132:133] op_sel_hi:[0,1,1]
	v_cvt_scalef32_pk_f32_fp4 v[132:133], v81, 1.0 op_sel:[1,0,0]
	v_pk_fma_f32 v[112:113], s[22:23], v[130:131], v[112:113] op_sel_hi:[0,1,1]
	v_cvt_scalef32_pk_f32_fp4 v[130:131], v81, 1.0
	v_pk_fma_f32 v[132:133], s[20:21], v[132:133], v[138:139] op_sel_hi:[0,1,1]
	v_cvt_scalef32_pk_f32_fp4 v[138:139], v81, 1.0 op_sel:[0,1,0]
	v_cvt_scalef32_pk_f32_fp4 v[80:81], v81, 1.0 op_sel:[1,1,0]
	v_pk_fma_f32 v[80:81], s[20:21], v[80:81], v[88:89] op_sel_hi:[0,1,1]
	v_cvt_scalef32_pk_f32_fp4 v[88:89], v82, 1.0
	v_pk_fma_f32 v[88:89], s[20:21], v[88:89], v[92:93] op_sel_hi:[0,1,1]
	v_cvt_scalef32_pk_f32_fp4 v[92:93], v82, 1.0 op_sel:[1,0,0]
	v_pk_fma_f32 v[92:93], s[20:21], v[92:93], v[126:127] op_sel_hi:[0,1,1]
	v_cvt_scalef32_pk_f32_fp4 v[126:127], v82, 1.0 op_sel:[0,1,0]
	v_pk_fma_f32 v[124:125], s[20:21], v[126:127], v[124:125] op_sel_hi:[0,1,1]
	v_cvt_scalef32_pk_f32_fp4 v[126:127], v82, 1.0 op_sel:[1,1,0]
	v_pk_fma_f32 v[120:121], s[20:21], v[126:127], v[120:121] op_sel_hi:[0,1,1]
	v_cvt_scalef32_pk_f32_fp4 v[126:127], v83, 1.0
	v_pk_fma_f32 v[116:117], s[20:21], v[126:127], v[116:117] op_sel_hi:[0,1,1]
	v_cvt_scalef32_pk_f32_fp4 v[126:127], v83, 1.0 op_sel:[1,0,0]
	v_pk_fma_f32 v[114:115], s[20:21], v[126:127], v[114:115] op_sel_hi:[0,1,1]
	v_cvt_scalef32_pk_f32_fp4 v[126:127], v83, 1.0 op_sel:[0,1,0]
	v_cvt_scalef32_pk_f32_fp4 v[82:83], v83, 1.0 op_sel:[1,1,0]
	v_pk_fma_f32 v[82:83], s[20:21], v[82:83], v[90:91] op_sel_hi:[0,1,1]
	v_cvt_scalef32_pk_f32_fp4 v[90:91], v68, 1.0
	v_pk_fma_f32 v[90:91], s[18:19], v[90:91], v[94:95] op_sel_hi:[0,1,1]
	v_cvt_scalef32_pk_f32_fp4 v[94:95], v68, 1.0 op_sel:[1,0,0]
	v_pk_fma_f32 v[94:95], s[18:19], v[94:95], v[110:111] op_sel_hi:[0,1,1]
	v_cvt_scalef32_pk_f32_fp4 v[110:111], v68, 1.0 op_sel:[0,1,0]
	v_pk_fma_f32 v[110:111], s[18:19], v[110:111], v[118:119] op_sel_hi:[0,1,1]
	v_cvt_scalef32_pk_f32_fp4 v[118:119], v68, 1.0 op_sel:[1,1,0]
	v_pk_fma_f32 v[130:131], s[20:21], v[130:131], v[140:141] op_sel_hi:[0,1,1]
	v_pk_fma_f32 v[118:119], s[18:19], v[118:119], v[122:123] op_sel_hi:[0,1,1]
	v_cvt_scalef32_pk_f32_fp4 v[122:123], v69, 1.0
	v_pk_fma_f32 v[112:113], s[20:21], v[126:127], v[112:113] op_sel_hi:[0,1,1]
	v_pk_fma_f32 v[122:123], s[18:19], v[122:123], v[130:131] op_sel_hi:[0,1,1]
	v_cvt_scalef32_pk_f32_fp4 v[126:127], v69, 1.0 op_sel:[1,0,0]
	v_cvt_scalef32_pk_f32_fp4 v[130:131], v69, 1.0 op_sel:[0,1,0]
	v_cvt_scalef32_pk_f32_fp4 v[68:69], v69, 1.0 op_sel:[1,1,0]
	v_pk_fma_f32 v[68:69], s[18:19], v[68:69], v[80:81] op_sel_hi:[0,1,1]
	v_cvt_scalef32_pk_f32_fp4 v[80:81], v70, 1.0
	v_pk_fma_f32 v[80:81], s[18:19], v[80:81], v[88:89] op_sel_hi:[0,1,1]
	v_cvt_scalef32_pk_f32_fp4 v[88:89], v70, 1.0 op_sel:[1,0,0]
	v_pk_fma_f32 v[88:89], s[18:19], v[88:89], v[92:93] op_sel_hi:[0,1,1]
	v_cvt_scalef32_pk_f32_fp4 v[92:93], v70, 1.0 op_sel:[0,1,0]
	v_pk_fma_f32 v[92:93], s[18:19], v[92:93], v[124:125] op_sel_hi:[0,1,1]
	v_cvt_scalef32_pk_f32_fp4 v[124:125], v70, 1.0 op_sel:[1,1,0]
	v_pk_fma_f32 v[120:121], s[18:19], v[124:125], v[120:121] op_sel_hi:[0,1,1]
	v_cvt_scalef32_pk_f32_fp4 v[124:125], v71, 1.0
	v_pk_fma_f32 v[116:117], s[18:19], v[124:125], v[116:117] op_sel_hi:[0,1,1]
	v_cvt_scalef32_pk_f32_fp4 v[124:125], v71, 1.0 op_sel:[1,0,0]
	v_pk_fma_f32 v[114:115], s[18:19], v[124:125], v[114:115] op_sel_hi:[0,1,1]
	v_cvt_scalef32_pk_f32_fp4 v[124:125], v71, 1.0 op_sel:[0,1,0]
	v_cvt_scalef32_pk_f32_fp4 v[70:71], v71, 1.0 op_sel:[1,1,0]
	v_pk_fma_f32 v[70:71], s[18:19], v[70:71], v[82:83] op_sel_hi:[0,1,1]
	v_cvt_scalef32_pk_f32_fp4 v[82:83], v76, 1.0
	v_pk_fma_f32 v[82:83], s[16:17], v[82:83], v[90:91] op_sel_hi:[0,1,1]
	v_cvt_scalef32_pk_f32_fp4 v[90:91], v76, 1.0 op_sel:[1,0,0]
	v_pk_fma_f32 v[90:91], s[16:17], v[90:91], v[94:95] op_sel_hi:[0,1,1]
	v_cvt_scalef32_pk_f32_fp4 v[94:95], v76, 1.0 op_sel:[0,1,0]
	v_pk_fma_f32 v[94:95], s[16:17], v[94:95], v[110:111] op_sel_hi:[0,1,1]
	v_cvt_scalef32_pk_f32_fp4 v[110:111], v76, 1.0 op_sel:[1,1,0]
	v_pk_fma_f32 v[110:111], s[16:17], v[110:111], v[118:119] op_sel_hi:[0,1,1]
	v_cvt_scalef32_pk_f32_fp4 v[118:119], v77, 1.0
	v_pk_fma_f32 v[112:113], s[18:19], v[124:125], v[112:113] op_sel_hi:[0,1,1]
	v_pk_fma_f32 v[118:119], s[16:17], v[118:119], v[122:123] op_sel_hi:[0,1,1]
	v_cvt_scalef32_pk_f32_fp4 v[122:123], v77, 1.0 op_sel:[1,0,0]
	v_cvt_scalef32_pk_f32_fp4 v[124:125], v77, 1.0 op_sel:[0,1,0]
	v_cvt_scalef32_pk_f32_fp4 v[76:77], v77, 1.0 op_sel:[1,1,0]
	v_pk_fma_f32 v[68:69], s[16:17], v[76:77], v[68:69] op_sel_hi:[0,1,1]
	v_cvt_scalef32_pk_f32_fp4 v[76:77], v78, 1.0
	v_pk_fma_f32 v[76:77], s[16:17], v[76:77], v[80:81] op_sel_hi:[0,1,1]
	v_cvt_scalef32_pk_f32_fp4 v[80:81], v78, 1.0 op_sel:[1,0,0]
	v_pk_fma_f32 v[80:81], s[16:17], v[80:81], v[88:89] op_sel_hi:[0,1,1]
	v_cvt_scalef32_pk_f32_fp4 v[88:89], v78, 1.0 op_sel:[0,1,0]
	v_pk_fma_f32 v[88:89], s[16:17], v[88:89], v[92:93] op_sel_hi:[0,1,1]
	v_cvt_scalef32_pk_f32_fp4 v[92:93], v78, 1.0 op_sel:[1,1,0]
	v_pk_fma_f32 v[92:93], s[16:17], v[92:93], v[120:121] op_sel_hi:[0,1,1]
	v_cvt_scalef32_pk_f32_fp4 v[120:121], v79, 1.0
	v_pk_fma_f32 v[116:117], s[16:17], v[120:121], v[116:117] op_sel_hi:[0,1,1]
	v_cvt_scalef32_pk_f32_fp4 v[120:121], v79, 1.0 op_sel:[1,0,0]
	v_pk_fma_f32 v[114:115], s[16:17], v[120:121], v[114:115] op_sel_hi:[0,1,1]
	v_cvt_scalef32_pk_f32_fp4 v[120:121], v79, 1.0 op_sel:[0,1,0]
	v_cvt_scalef32_pk_f32_fp4 v[78:79], v79, 1.0 op_sel:[1,1,0]
	v_pk_fma_f32 v[70:71], s[16:17], v[78:79], v[70:71] op_sel_hi:[0,1,1]
	v_cvt_scalef32_pk_f32_fp4 v[78:79], v60, 1.0
	v_pk_fma_f32 v[78:79], s[14:15], v[78:79], v[82:83] op_sel_hi:[0,1,1]
	v_cvt_scalef32_pk_f32_fp4 v[82:83], v60, 1.0 op_sel:[1,0,0]
	v_pk_fma_f32 v[82:83], s[14:15], v[82:83], v[90:91] op_sel_hi:[0,1,1]
	v_cvt_scalef32_pk_f32_fp4 v[90:91], v60, 1.0 op_sel:[0,1,0]
	v_pk_fma_f32 v[90:91], s[14:15], v[90:91], v[94:95] op_sel_hi:[0,1,1]
	v_cvt_scalef32_pk_f32_fp4 v[94:95], v60, 1.0 op_sel:[1,1,0]
	v_pk_fma_f32 v[94:95], s[14:15], v[94:95], v[110:111] op_sel_hi:[0,1,1]
	v_cvt_scalef32_pk_f32_fp4 v[110:111], v61, 1.0
	v_pk_fma_f32 v[112:113], s[16:17], v[120:121], v[112:113] op_sel_hi:[0,1,1]
	v_pk_fma_f32 v[110:111], s[14:15], v[110:111], v[118:119] op_sel_hi:[0,1,1]
	v_cvt_scalef32_pk_f32_fp4 v[118:119], v61, 1.0 op_sel:[1,0,0]
	v_cvt_scalef32_pk_f32_fp4 v[120:121], v61, 1.0 op_sel:[0,1,0]
	v_cvt_scalef32_pk_f32_fp4 v[60:61], v61, 1.0 op_sel:[1,1,0]
	v_pk_fma_f32 v[60:61], s[14:15], v[60:61], v[68:69] op_sel_hi:[0,1,1]
	v_cvt_scalef32_pk_f32_fp4 v[68:69], v62, 1.0
	v_pk_fma_f32 v[68:69], s[14:15], v[68:69], v[76:77] op_sel_hi:[0,1,1]
	v_cvt_scalef32_pk_f32_fp4 v[76:77], v62, 1.0 op_sel:[1,0,0]
	v_pk_fma_f32 v[76:77], s[14:15], v[76:77], v[80:81] op_sel_hi:[0,1,1]
	v_cvt_scalef32_pk_f32_fp4 v[80:81], v62, 1.0 op_sel:[0,1,0]
	v_pk_fma_f32 v[80:81], s[14:15], v[80:81], v[88:89] op_sel_hi:[0,1,1]
	v_cvt_scalef32_pk_f32_fp4 v[88:89], v62, 1.0 op_sel:[1,1,0]
	v_pk_fma_f32 v[88:89], s[14:15], v[88:89], v[92:93] op_sel_hi:[0,1,1]
	v_cvt_scalef32_pk_f32_fp4 v[92:93], v63, 1.0
	v_pk_fma_f32 v[92:93], s[14:15], v[92:93], v[116:117] op_sel_hi:[0,1,1]
	v_cvt_scalef32_pk_f32_fp4 v[116:117], v63, 1.0 op_sel:[1,0,0]
	v_pk_fma_f32 v[114:115], s[14:15], v[116:117], v[114:115] op_sel_hi:[0,1,1]
	v_cvt_scalef32_pk_f32_fp4 v[116:117], v63, 1.0 op_sel:[0,1,0]
	v_cvt_scalef32_pk_f32_fp4 v[62:63], v63, 1.0 op_sel:[1,1,0]
	v_pk_fma_f32 v[62:63], s[14:15], v[62:63], v[70:71] op_sel_hi:[0,1,1]
	v_cvt_scalef32_pk_f32_fp4 v[70:71], v48, 1.0
	v_pk_fma_f32 v[70:71], s[12:13], v[70:71], v[78:79] op_sel_hi:[0,1,1]
	v_cvt_scalef32_pk_f32_fp4 v[78:79], v48, 1.0 op_sel:[1,0,0]
	v_pk_fma_f32 v[78:79], s[12:13], v[78:79], v[82:83] op_sel_hi:[0,1,1]
	v_cvt_scalef32_pk_f32_fp4 v[82:83], v48, 1.0 op_sel:[0,1,0]
	v_pk_fma_f32 v[82:83], s[12:13], v[82:83], v[90:91] op_sel_hi:[0,1,1]
	v_cvt_scalef32_pk_f32_fp4 v[90:91], v48, 1.0 op_sel:[1,1,0]
	v_pk_fma_f32 v[90:91], s[12:13], v[90:91], v[94:95] op_sel_hi:[0,1,1]
	v_cvt_scalef32_pk_f32_fp4 v[94:95], v49, 1.0
	v_pk_fma_f32 v[112:113], s[14:15], v[116:117], v[112:113] op_sel_hi:[0,1,1]
	v_pk_fma_f32 v[94:95], s[12:13], v[94:95], v[110:111] op_sel_hi:[0,1,1]
	v_cvt_scalef32_pk_f32_fp4 v[110:111], v49, 1.0 op_sel:[1,0,0]
	v_cvt_scalef32_pk_f32_fp4 v[116:117], v49, 1.0 op_sel:[0,1,0]
	v_cvt_scalef32_pk_f32_fp4 v[48:49], v49, 1.0 op_sel:[1,1,0]
	v_pk_fma_f32 v[48:49], s[12:13], v[48:49], v[60:61] op_sel_hi:[0,1,1]
	v_cvt_scalef32_pk_f32_fp4 v[60:61], v50, 1.0
	v_pk_fma_f32 v[60:61], s[12:13], v[60:61], v[68:69] op_sel_hi:[0,1,1]
	v_cvt_scalef32_pk_f32_fp4 v[68:69], v50, 1.0 op_sel:[1,0,0]
	v_pk_fma_f32 v[68:69], s[12:13], v[68:69], v[76:77] op_sel_hi:[0,1,1]
	v_cvt_scalef32_pk_f32_fp4 v[76:77], v50, 1.0 op_sel:[0,1,0]
	v_pk_fma_f32 v[76:77], s[12:13], v[76:77], v[80:81] op_sel_hi:[0,1,1]
	v_cvt_scalef32_pk_f32_fp4 v[80:81], v50, 1.0 op_sel:[1,1,0]
	v_pk_fma_f32 v[80:81], s[12:13], v[80:81], v[88:89] op_sel_hi:[0,1,1]
	v_cvt_scalef32_pk_f32_fp4 v[88:89], v51, 1.0
	v_pk_fma_f32 v[88:89], s[12:13], v[88:89], v[92:93] op_sel_hi:[0,1,1]
	v_cvt_scalef32_pk_f32_fp4 v[92:93], v51, 1.0 op_sel:[1,0,0]
	v_pk_fma_f32 v[92:93], s[12:13], v[92:93], v[114:115] op_sel_hi:[0,1,1]
	v_cvt_scalef32_pk_f32_fp4 v[114:115], v51, 1.0 op_sel:[0,1,0]
	v_cvt_scalef32_pk_f32_fp4 v[50:51], v51, 1.0 op_sel:[1,1,0]
	v_pk_fma_f32 v[50:51], s[12:13], v[50:51], v[62:63] op_sel_hi:[0,1,1]
	v_cvt_scalef32_pk_f32_fp4 v[62:63], v40, 1.0
	v_pk_fma_f32 v[62:63], s[10:11], v[62:63], v[70:71] op_sel_hi:[0,1,1]
	v_cvt_scalef32_pk_f32_fp4 v[70:71], v40, 1.0 op_sel:[1,0,0]
	v_pk_fma_f32 v[126:127], s[18:19], v[126:127], v[132:133] op_sel_hi:[0,1,1]
	v_pk_fma_f32 v[70:71], s[10:11], v[70:71], v[78:79] op_sel_hi:[0,1,1]
	v_cvt_scalef32_pk_f32_fp4 v[78:79], v40, 1.0 op_sel:[0,1,0]
	v_pk_fma_f32 v[122:123], s[16:17], v[122:123], v[126:127] op_sel_hi:[0,1,1]
	v_pk_fma_f32 v[78:79], s[10:11], v[78:79], v[82:83] op_sel_hi:[0,1,1]
	v_cvt_scalef32_pk_f32_fp4 v[82:83], v40, 1.0 op_sel:[1,1,0]
	v_pk_fma_f32 v[118:119], s[14:15], v[118:119], v[122:123] op_sel_hi:[0,1,1]
	v_pk_fma_f32 v[82:83], s[10:11], v[82:83], v[90:91] op_sel_hi:[0,1,1]
	v_cvt_scalef32_pk_f32_fp4 v[90:91], v41, 1.0
	v_pk_fma_f32 v[110:111], s[12:13], v[110:111], v[118:119] op_sel_hi:[0,1,1]
	v_pk_fma_f32 v[90:91], s[10:11], v[90:91], v[94:95] op_sel_hi:[0,1,1]
	v_cvt_scalef32_pk_f32_fp4 v[94:95], v41, 1.0 op_sel:[1,0,0]
	v_pk_fma_f32 v[94:95], s[10:11], v[94:95], v[110:111] op_sel_hi:[0,1,1]
	v_cvt_scalef32_pk_f32_fp4 v[110:111], v41, 1.0 op_sel:[0,1,0]
	v_cvt_scalef32_pk_f32_fp4 v[40:41], v41, 1.0 op_sel:[1,1,0]
	v_pk_fma_f32 v[134:135], s[24:25], v[160:161], v[134:135] op_sel_hi:[0,1,1]
	v_pk_fma_f32 v[40:41], s[10:11], v[40:41], v[48:49] op_sel_hi:[0,1,1]
	v_cvt_scalef32_pk_f32_fp4 v[48:49], v42, 1.0
	v_pk_fma_f32 v[134:135], s[22:23], v[142:143], v[134:135] op_sel_hi:[0,1,1]
	v_pk_fma_f32 v[48:49], s[10:11], v[48:49], v[60:61] op_sel_hi:[0,1,1]
	v_cvt_scalef32_pk_f32_fp4 v[60:61], v42, 1.0 op_sel:[1,0,0]
	v_pk_fma_f32 v[134:135], s[20:21], v[138:139], v[134:135] op_sel_hi:[0,1,1]
	v_pk_fma_f32 v[60:61], s[10:11], v[60:61], v[68:69] op_sel_hi:[0,1,1]
	v_cvt_scalef32_pk_f32_fp4 v[68:69], v42, 1.0 op_sel:[0,1,0]
	v_pk_fma_f32 v[130:131], s[18:19], v[130:131], v[134:135] op_sel_hi:[0,1,1]
	v_pk_fma_f32 v[68:69], s[10:11], v[68:69], v[76:77] op_sel_hi:[0,1,1]
	v_cvt_scalef32_pk_f32_fp4 v[76:77], v42, 1.0 op_sel:[1,1,0]
	v_pk_fma_f32 v[124:125], s[16:17], v[124:125], v[130:131] op_sel_hi:[0,1,1]
	v_pk_fma_f32 v[76:77], s[10:11], v[76:77], v[80:81] op_sel_hi:[0,1,1]
	v_cvt_scalef32_pk_f32_fp4 v[80:81], v43, 1.0
	v_pk_fma_f32 v[120:121], s[14:15], v[120:121], v[124:125] op_sel_hi:[0,1,1]
	v_pk_fma_f32 v[80:81], s[10:11], v[80:81], v[88:89] op_sel_hi:[0,1,1]
	v_cvt_scalef32_pk_f32_fp4 v[88:89], v43, 1.0 op_sel:[1,0,0]
	v_pk_fma_f32 v[116:117], s[12:13], v[116:117], v[120:121] op_sel_hi:[0,1,1]
	v_pk_fma_f32 v[112:113], s[12:13], v[114:115], v[112:113] op_sel_hi:[0,1,1]
	v_pk_fma_f32 v[88:89], s[10:11], v[88:89], v[92:93] op_sel_hi:[0,1,1]
	v_cvt_scalef32_pk_f32_fp4 v[92:93], v43, 1.0 op_sel:[0,1,0]
	v_cvt_scalef32_pk_f32_fp4 v[42:43], v43, 1.0 op_sel:[1,1,0]
	v_pk_fma_f32 v[110:111], s[10:11], v[110:111], v[116:117] op_sel_hi:[0,1,1]
	v_pk_fma_f32 v[92:93], s[10:11], v[92:93], v[112:113] op_sel_hi:[0,1,1]
	v_pk_fma_f32 v[42:43], s[10:11], v[42:43], v[50:51] op_sel_hi:[0,1,1]
	v_readlane_b32 s10, v159, s39
	s_waitcnt vmcnt(15)
	v_cvt_scalef32_pk_f32_fp4 v[50:51], v84, 1.0
	s_and_b64 vcc, exec, s[4:5]
	v_pk_fma_f32 v[50:51], s[10:11], v[50:51], v[62:63] op_sel_hi:[0,1,1]
	v_cvt_scalef32_pk_f32_fp4 v[62:63], v84, 1.0 op_sel:[1,0,0]
	v_pk_fma_f32 v[62:63], s[10:11], v[62:63], v[70:71] op_sel_hi:[0,1,1]
	v_cvt_scalef32_pk_f32_fp4 v[70:71], v84, 1.0 op_sel:[0,1,0]
	v_pk_fma_f32 v[70:71], s[10:11], v[70:71], v[78:79] op_sel_hi:[0,1,1]
	v_cvt_scalef32_pk_f32_fp4 v[78:79], v84, 1.0 op_sel:[1,1,0]
	v_pk_fma_f32 v[78:79], s[10:11], v[78:79], v[82:83] op_sel_hi:[0,1,1]
	v_cvt_scalef32_pk_f32_fp4 v[82:83], v85, 1.0
	v_pk_fma_f32 v[82:83], s[10:11], v[82:83], v[90:91] op_sel_hi:[0,1,1]
	v_cvt_scalef32_pk_f32_fp4 v[90:91], v85, 1.0 op_sel:[1,0,0]
	v_pk_fma_f32 v[90:91], s[10:11], v[90:91], v[94:95] op_sel_hi:[0,1,1]
	v_cvt_scalef32_pk_f32_fp4 v[94:95], v85, 1.0 op_sel:[0,1,0]
	v_cvt_scalef32_pk_f32_fp4 v[84:85], v85, 1.0 op_sel:[1,1,0]
	v_pk_fma_f32 v[40:41], s[10:11], v[84:85], v[40:41] op_sel_hi:[0,1,1]
	v_cvt_scalef32_pk_f32_fp4 v[84:85], v86, 1.0
	v_pk_fma_f32 v[48:49], s[10:11], v[84:85], v[48:49] op_sel_hi:[0,1,1]
	v_cvt_scalef32_pk_f32_fp4 v[84:85], v86, 1.0 op_sel:[1,0,0]
	v_pk_fma_f32 v[60:61], s[10:11], v[84:85], v[60:61] op_sel_hi:[0,1,1]
	v_cvt_scalef32_pk_f32_fp4 v[84:85], v86, 1.0 op_sel:[0,1,0]
	v_pk_fma_f32 v[68:69], s[10:11], v[84:85], v[68:69] op_sel_hi:[0,1,1]
	v_cvt_scalef32_pk_f32_fp4 v[84:85], v86, 1.0 op_sel:[1,1,0]
	v_pk_fma_f32 v[76:77], s[10:11], v[84:85], v[76:77] op_sel_hi:[0,1,1]
	v_cvt_scalef32_pk_f32_fp4 v[84:85], v87, 1.0
	v_pk_fma_f32 v[80:81], s[10:11], v[84:85], v[80:81] op_sel_hi:[0,1,1]
	v_cvt_scalef32_pk_f32_fp4 v[84:85], v87, 1.0 op_sel:[1,0,0]
	v_pk_fma_f32 v[84:85], s[10:11], v[84:85], v[88:89] op_sel_hi:[0,1,1]
	v_cvt_scalef32_pk_f32_fp4 v[88:89], v87, 1.0 op_sel:[0,1,0]
	v_cvt_scalef32_pk_f32_fp4 v[86:87], v87, 1.0 op_sel:[1,1,0]
	v_pk_fma_f32 v[94:95], s[10:11], v[94:95], v[110:111] op_sel_hi:[0,1,1]
	v_pk_fma_f32 v[88:89], s[10:11], v[88:89], v[92:93] op_sel_hi:[0,1,1]
	v_pk_fma_f32 v[42:43], s[10:11], v[86:87], v[42:43] op_sel_hi:[0,1,1]
	v_readlane_b32 s10, v159, s38
	s_waitcnt vmcnt(14)
	v_cvt_scalef32_pk_f32_fp4 v[86:87], v72, 1.0
	v_pk_fma_f32 v[50:51], s[10:11], v[86:87], v[50:51] op_sel_hi:[0,1,1]
	v_cvt_scalef32_pk_f32_fp4 v[86:87], v72, 1.0 op_sel:[1,0,0]
	v_pk_fma_f32 v[62:63], s[10:11], v[86:87], v[62:63] op_sel_hi:[0,1,1]
	v_cvt_scalef32_pk_f32_fp4 v[86:87], v72, 1.0 op_sel:[0,1,0]
	v_pk_fma_f32 v[70:71], s[10:11], v[86:87], v[70:71] op_sel_hi:[0,1,1]
	v_cvt_scalef32_pk_f32_fp4 v[86:87], v72, 1.0 op_sel:[1,1,0]
	v_pk_fma_f32 v[78:79], s[10:11], v[86:87], v[78:79] op_sel_hi:[0,1,1]
	v_cvt_scalef32_pk_f32_fp4 v[86:87], v73, 1.0
	v_pk_fma_f32 v[82:83], s[10:11], v[86:87], v[82:83] op_sel_hi:[0,1,1]
	v_cvt_scalef32_pk_f32_fp4 v[86:87], v73, 1.0 op_sel:[1,0,0]
	v_pk_fma_f32 v[86:87], s[10:11], v[86:87], v[90:91] op_sel_hi:[0,1,1]
	v_cvt_scalef32_pk_f32_fp4 v[90:91], v73, 1.0 op_sel:[0,1,0]
	v_cvt_scalef32_pk_f32_fp4 v[72:73], v73, 1.0 op_sel:[1,1,0]
	v_pk_fma_f32 v[40:41], s[10:11], v[72:73], v[40:41] op_sel_hi:[0,1,1]
	v_cvt_scalef32_pk_f32_fp4 v[72:73], v74, 1.0
	v_pk_fma_f32 v[48:49], s[10:11], v[72:73], v[48:49] op_sel_hi:[0,1,1]
	v_cvt_scalef32_pk_f32_fp4 v[72:73], v74, 1.0 op_sel:[1,0,0]
	v_pk_fma_f32 v[60:61], s[10:11], v[72:73], v[60:61] op_sel_hi:[0,1,1]
	v_cvt_scalef32_pk_f32_fp4 v[72:73], v74, 1.0 op_sel:[0,1,0]
	v_pk_fma_f32 v[68:69], s[10:11], v[72:73], v[68:69] op_sel_hi:[0,1,1]
	v_cvt_scalef32_pk_f32_fp4 v[72:73], v74, 1.0 op_sel:[1,1,0]
	v_pk_fma_f32 v[72:73], s[10:11], v[72:73], v[76:77] op_sel_hi:[0,1,1]
	v_cvt_scalef32_pk_f32_fp4 v[76:77], v75, 1.0
	v_pk_fma_f32 v[76:77], s[10:11], v[76:77], v[80:81] op_sel_hi:[0,1,1]
	v_cvt_scalef32_pk_f32_fp4 v[80:81], v75, 1.0 op_sel:[1,0,0]
	v_pk_fma_f32 v[80:81], s[10:11], v[80:81], v[84:85] op_sel_hi:[0,1,1]
	v_cvt_scalef32_pk_f32_fp4 v[84:85], v75, 1.0 op_sel:[0,1,0]
	v_cvt_scalef32_pk_f32_fp4 v[74:75], v75, 1.0 op_sel:[1,1,0]
	v_pk_fma_f32 v[90:91], s[10:11], v[90:91], v[94:95] op_sel_hi:[0,1,1]
	v_pk_fma_f32 v[84:85], s[10:11], v[84:85], v[88:89] op_sel_hi:[0,1,1]
	v_pk_fma_f32 v[42:43], s[10:11], v[74:75], v[42:43] op_sel_hi:[0,1,1]
	v_readlane_b32 s10, v159, s37
	s_waitcnt vmcnt(13)
	v_cvt_scalef32_pk_f32_fp4 v[74:75], v64, 1.0
	v_pk_fma_f32 v[50:51], s[10:11], v[74:75], v[50:51] op_sel_hi:[0,1,1]
	v_cvt_scalef32_pk_f32_fp4 v[74:75], v64, 1.0 op_sel:[1,0,0]
	v_pk_fma_f32 v[62:63], s[10:11], v[74:75], v[62:63] op_sel_hi:[0,1,1]
	v_cvt_scalef32_pk_f32_fp4 v[74:75], v64, 1.0 op_sel:[0,1,0]
	v_pk_fma_f32 v[70:71], s[10:11], v[74:75], v[70:71] op_sel_hi:[0,1,1]
	v_cvt_scalef32_pk_f32_fp4 v[74:75], v64, 1.0 op_sel:[1,1,0]
	v_pk_fma_f32 v[74:75], s[10:11], v[74:75], v[78:79] op_sel_hi:[0,1,1]
	v_cvt_scalef32_pk_f32_fp4 v[78:79], v65, 1.0
	v_pk_fma_f32 v[78:79], s[10:11], v[78:79], v[82:83] op_sel_hi:[0,1,1]
	v_cvt_scalef32_pk_f32_fp4 v[82:83], v65, 1.0 op_sel:[1,0,0]
	v_pk_fma_f32 v[82:83], s[10:11], v[82:83], v[86:87] op_sel_hi:[0,1,1]
	v_cvt_scalef32_pk_f32_fp4 v[86:87], v65, 1.0 op_sel:[0,1,0]
	v_cvt_scalef32_pk_f32_fp4 v[64:65], v65, 1.0 op_sel:[1,1,0]
	v_pk_fma_f32 v[40:41], s[10:11], v[64:65], v[40:41] op_sel_hi:[0,1,1]
	v_cvt_scalef32_pk_f32_fp4 v[64:65], v66, 1.0
	v_pk_fma_f32 v[48:49], s[10:11], v[64:65], v[48:49] op_sel_hi:[0,1,1]
	v_cvt_scalef32_pk_f32_fp4 v[64:65], v66, 1.0 op_sel:[1,0,0]
	v_pk_fma_f32 v[60:61], s[10:11], v[64:65], v[60:61] op_sel_hi:[0,1,1]
	v_cvt_scalef32_pk_f32_fp4 v[64:65], v66, 1.0 op_sel:[0,1,0]
	v_pk_fma_f32 v[64:65], s[10:11], v[64:65], v[68:69] op_sel_hi:[0,1,1]
	v_cvt_scalef32_pk_f32_fp4 v[68:69], v66, 1.0 op_sel:[1,1,0]
	v_pk_fma_f32 v[68:69], s[10:11], v[68:69], v[72:73] op_sel_hi:[0,1,1]
	v_cvt_scalef32_pk_f32_fp4 v[72:73], v67, 1.0
	v_pk_fma_f32 v[72:73], s[10:11], v[72:73], v[76:77] op_sel_hi:[0,1,1]
	v_cvt_scalef32_pk_f32_fp4 v[76:77], v67, 1.0 op_sel:[1,0,0]
	v_pk_fma_f32 v[76:77], s[10:11], v[76:77], v[80:81] op_sel_hi:[0,1,1]
	v_cvt_scalef32_pk_f32_fp4 v[80:81], v67, 1.0 op_sel:[0,1,0]
	v_cvt_scalef32_pk_f32_fp4 v[66:67], v67, 1.0 op_sel:[1,1,0]
	v_pk_fma_f32 v[86:87], s[10:11], v[86:87], v[90:91] op_sel_hi:[0,1,1]
	v_pk_fma_f32 v[80:81], s[10:11], v[80:81], v[84:85] op_sel_hi:[0,1,1]
	v_pk_fma_f32 v[42:43], s[10:11], v[66:67], v[42:43] op_sel_hi:[0,1,1]
	v_readlane_b32 s10, v159, s36
	s_waitcnt vmcnt(12)
	v_cvt_scalef32_pk_f32_fp4 v[66:67], v56, 1.0
	v_pk_fma_f32 v[50:51], s[10:11], v[66:67], v[50:51] op_sel_hi:[0,1,1]
	v_cvt_scalef32_pk_f32_fp4 v[66:67], v56, 1.0 op_sel:[1,0,0]
	v_pk_fma_f32 v[62:63], s[10:11], v[66:67], v[62:63] op_sel_hi:[0,1,1]
	v_cvt_scalef32_pk_f32_fp4 v[66:67], v56, 1.0 op_sel:[0,1,0]
	v_pk_fma_f32 v[66:67], s[10:11], v[66:67], v[70:71] op_sel_hi:[0,1,1]
	v_cvt_scalef32_pk_f32_fp4 v[70:71], v56, 1.0 op_sel:[1,1,0]
	v_pk_fma_f32 v[70:71], s[10:11], v[70:71], v[74:75] op_sel_hi:[0,1,1]
	v_cvt_scalef32_pk_f32_fp4 v[74:75], v57, 1.0
	v_pk_fma_f32 v[74:75], s[10:11], v[74:75], v[78:79] op_sel_hi:[0,1,1]
	v_cvt_scalef32_pk_f32_fp4 v[78:79], v57, 1.0 op_sel:[1,0,0]
	v_pk_fma_f32 v[78:79], s[10:11], v[78:79], v[82:83] op_sel_hi:[0,1,1]
	v_cvt_scalef32_pk_f32_fp4 v[82:83], v57, 1.0 op_sel:[0,1,0]
	v_cvt_scalef32_pk_f32_fp4 v[56:57], v57, 1.0 op_sel:[1,1,0]
	v_pk_fma_f32 v[40:41], s[10:11], v[56:57], v[40:41] op_sel_hi:[0,1,1]
	v_cvt_scalef32_pk_f32_fp4 v[56:57], v58, 1.0
	v_pk_fma_f32 v[48:49], s[10:11], v[56:57], v[48:49] op_sel_hi:[0,1,1]
	v_cvt_scalef32_pk_f32_fp4 v[56:57], v58, 1.0 op_sel:[1,0,0]
	v_pk_fma_f32 v[56:57], s[10:11], v[56:57], v[60:61] op_sel_hi:[0,1,1]
	v_cvt_scalef32_pk_f32_fp4 v[60:61], v58, 1.0 op_sel:[0,1,0]
	v_pk_fma_f32 v[60:61], s[10:11], v[60:61], v[64:65] op_sel_hi:[0,1,1]
	v_cvt_scalef32_pk_f32_fp4 v[64:65], v58, 1.0 op_sel:[1,1,0]
	v_pk_fma_f32 v[64:65], s[10:11], v[64:65], v[68:69] op_sel_hi:[0,1,1]
	v_cvt_scalef32_pk_f32_fp4 v[68:69], v59, 1.0
	v_pk_fma_f32 v[68:69], s[10:11], v[68:69], v[72:73] op_sel_hi:[0,1,1]
	v_cvt_scalef32_pk_f32_fp4 v[72:73], v59, 1.0 op_sel:[1,0,0]
	v_pk_fma_f32 v[72:73], s[10:11], v[72:73], v[76:77] op_sel_hi:[0,1,1]
	v_cvt_scalef32_pk_f32_fp4 v[76:77], v59, 1.0 op_sel:[0,1,0]
	v_cvt_scalef32_pk_f32_fp4 v[58:59], v59, 1.0 op_sel:[1,1,0]
	v_pk_fma_f32 v[82:83], s[10:11], v[82:83], v[86:87] op_sel_hi:[0,1,1]
	v_pk_fma_f32 v[76:77], s[10:11], v[76:77], v[80:81] op_sel_hi:[0,1,1]
	v_pk_fma_f32 v[42:43], s[10:11], v[58:59], v[42:43] op_sel_hi:[0,1,1]
	v_readlane_b32 s10, v159, s35
	s_waitcnt vmcnt(11)
	v_cvt_scalef32_pk_f32_fp4 v[58:59], v52, 1.0
	v_pk_fma_f32 v[50:51], s[10:11], v[58:59], v[50:51] op_sel_hi:[0,1,1]
	v_cvt_scalef32_pk_f32_fp4 v[58:59], v52, 1.0 op_sel:[1,0,0]
	v_pk_fma_f32 v[58:59], s[10:11], v[58:59], v[62:63] op_sel_hi:[0,1,1]
	v_cvt_scalef32_pk_f32_fp4 v[62:63], v52, 1.0 op_sel:[0,1,0]
	v_pk_fma_f32 v[62:63], s[10:11], v[62:63], v[66:67] op_sel_hi:[0,1,1]
	v_cvt_scalef32_pk_f32_fp4 v[66:67], v52, 1.0 op_sel:[1,1,0]
	v_pk_fma_f32 v[66:67], s[10:11], v[66:67], v[70:71] op_sel_hi:[0,1,1]
	v_cvt_scalef32_pk_f32_fp4 v[70:71], v53, 1.0
	v_pk_fma_f32 v[70:71], s[10:11], v[70:71], v[74:75] op_sel_hi:[0,1,1]
	v_cvt_scalef32_pk_f32_fp4 v[74:75], v53, 1.0 op_sel:[1,0,0]
	v_pk_fma_f32 v[74:75], s[10:11], v[74:75], v[78:79] op_sel_hi:[0,1,1]
	v_cvt_scalef32_pk_f32_fp4 v[78:79], v53, 1.0 op_sel:[0,1,0]
	v_cvt_scalef32_pk_f32_fp4 v[52:53], v53, 1.0 op_sel:[1,1,0]
	v_pk_fma_f32 v[40:41], s[10:11], v[52:53], v[40:41] op_sel_hi:[0,1,1]
	v_cvt_scalef32_pk_f32_fp4 v[52:53], v54, 1.0
	v_pk_fma_f32 v[48:49], s[10:11], v[52:53], v[48:49] op_sel_hi:[0,1,1]
	v_cvt_scalef32_pk_f32_fp4 v[52:53], v54, 1.0 op_sel:[1,0,0]
	v_pk_fma_f32 v[52:53], s[10:11], v[52:53], v[56:57] op_sel_hi:[0,1,1]
	v_cvt_scalef32_pk_f32_fp4 v[56:57], v54, 1.0 op_sel:[0,1,0]
	v_pk_fma_f32 v[56:57], s[10:11], v[56:57], v[60:61] op_sel_hi:[0,1,1]
	v_cvt_scalef32_pk_f32_fp4 v[60:61], v54, 1.0 op_sel:[1,1,0]
	v_pk_fma_f32 v[60:61], s[10:11], v[60:61], v[64:65] op_sel_hi:[0,1,1]
	v_cvt_scalef32_pk_f32_fp4 v[64:65], v55, 1.0
	v_pk_fma_f32 v[64:65], s[10:11], v[64:65], v[68:69] op_sel_hi:[0,1,1]
	v_cvt_scalef32_pk_f32_fp4 v[68:69], v55, 1.0 op_sel:[1,0,0]
	v_pk_fma_f32 v[68:69], s[10:11], v[68:69], v[72:73] op_sel_hi:[0,1,1]
	v_cvt_scalef32_pk_f32_fp4 v[72:73], v55, 1.0 op_sel:[0,1,0]
	v_cvt_scalef32_pk_f32_fp4 v[54:55], v55, 1.0 op_sel:[1,1,0]
	v_pk_fma_f32 v[78:79], s[10:11], v[78:79], v[82:83] op_sel_hi:[0,1,1]
	v_pk_fma_f32 v[72:73], s[10:11], v[72:73], v[76:77] op_sel_hi:[0,1,1]
	v_pk_fma_f32 v[42:43], s[10:11], v[54:55], v[42:43] op_sel_hi:[0,1,1]
	v_readlane_b32 s10, v159, s34
	s_waitcnt vmcnt(10)
	v_cvt_scalef32_pk_f32_fp4 v[54:55], v44, 1.0
	v_pk_fma_f32 v[50:51], s[10:11], v[54:55], v[50:51] op_sel_hi:[0,1,1]
	v_cvt_scalef32_pk_f32_fp4 v[54:55], v44, 1.0 op_sel:[1,0,0]
	v_pk_fma_f32 v[54:55], s[10:11], v[54:55], v[58:59] op_sel_hi:[0,1,1]
	v_cvt_scalef32_pk_f32_fp4 v[58:59], v44, 1.0 op_sel:[0,1,0]
	v_pk_fma_f32 v[58:59], s[10:11], v[58:59], v[62:63] op_sel_hi:[0,1,1]
	v_cvt_scalef32_pk_f32_fp4 v[62:63], v44, 1.0 op_sel:[1,1,0]
	v_pk_fma_f32 v[62:63], s[10:11], v[62:63], v[66:67] op_sel_hi:[0,1,1]
	v_cvt_scalef32_pk_f32_fp4 v[66:67], v45, 1.0
	v_pk_fma_f32 v[66:67], s[10:11], v[66:67], v[70:71] op_sel_hi:[0,1,1]
	v_cvt_scalef32_pk_f32_fp4 v[70:71], v45, 1.0 op_sel:[1,0,0]
	v_pk_fma_f32 v[70:71], s[10:11], v[70:71], v[74:75] op_sel_hi:[0,1,1]
	v_cvt_scalef32_pk_f32_fp4 v[74:75], v45, 1.0 op_sel:[0,1,0]
	v_cvt_scalef32_pk_f32_fp4 v[44:45], v45, 1.0 op_sel:[1,1,0]
	v_pk_fma_f32 v[40:41], s[10:11], v[44:45], v[40:41] op_sel_hi:[0,1,1]
	v_cvt_scalef32_pk_f32_fp4 v[44:45], v46, 1.0
	v_pk_fma_f32 v[44:45], s[10:11], v[44:45], v[48:49] op_sel_hi:[0,1,1]
	v_cvt_scalef32_pk_f32_fp4 v[48:49], v46, 1.0 op_sel:[1,0,0]
	v_pk_fma_f32 v[48:49], s[10:11], v[48:49], v[52:53] op_sel_hi:[0,1,1]
	v_cvt_scalef32_pk_f32_fp4 v[52:53], v46, 1.0 op_sel:[0,1,0]
	v_pk_fma_f32 v[52:53], s[10:11], v[52:53], v[56:57] op_sel_hi:[0,1,1]
	v_cvt_scalef32_pk_f32_fp4 v[56:57], v46, 1.0 op_sel:[1,1,0]
	v_pk_fma_f32 v[56:57], s[10:11], v[56:57], v[60:61] op_sel_hi:[0,1,1]
	v_cvt_scalef32_pk_f32_fp4 v[60:61], v47, 1.0
	v_pk_fma_f32 v[60:61], s[10:11], v[60:61], v[64:65] op_sel_hi:[0,1,1]
	v_cvt_scalef32_pk_f32_fp4 v[64:65], v47, 1.0 op_sel:[1,0,0]
	v_pk_fma_f32 v[64:65], s[10:11], v[64:65], v[68:69] op_sel_hi:[0,1,1]
	v_cvt_scalef32_pk_f32_fp4 v[68:69], v47, 1.0 op_sel:[0,1,0]
	v_cvt_scalef32_pk_f32_fp4 v[46:47], v47, 1.0 op_sel:[1,1,0]
	v_pk_fma_f32 v[74:75], s[10:11], v[74:75], v[78:79] op_sel_hi:[0,1,1]
	v_pk_fma_f32 v[68:69], s[10:11], v[68:69], v[72:73] op_sel_hi:[0,1,1]
	v_pk_fma_f32 v[42:43], s[10:11], v[46:47], v[42:43] op_sel_hi:[0,1,1]
	v_readlane_b32 s10, v159, s33
	s_waitcnt vmcnt(9)
; #define PV_LOAD(BUF, EV, S0) do { _Pragma("unroll") for (int i = 0; i < 8; ++i) { const int row_ = __builtin_amdgcn_readlane(EV, (S0) + i); BUF[i & 3][i >> 2] = *(const u32x4*)(PV8 + (size_t)row_ * 1024 + lane * 16); } } while (0)
; __global__ void __launch_bounds__(NT, 2) mk_fwd(Args args) {
;     ...
; #pragma unroll
;             for (int hh = 0; hh < 2; ++hh) {
;                 const int ev = hh ? e1 : e0; const float av = hh ? act1 : act0;
;                 PV_LOAD(bA, ev, 0);
; #pragma unroll 1
;                 for (int s = 0; s < 64; s += 16) {
;                     PV_LOAD(bB, ev, s + 8);
;                     PV_ACC(bA, av, s);
;                     if (s + 16 < 64) PV_LOAD(bA, ev, s + 16);
;                     PV_ACC(bB, av, s + 8);
;                 }
	v_cvt_scalef32_pk_f32_fp4 v[46:47], v36, 1.0
	v_pk_fma_f32 v[46:47], s[10:11], v[46:47], v[50:51] op_sel_hi:[0,1,1]
	v_cvt_scalef32_pk_f32_fp4 v[50:51], v36, 1.0 op_sel:[1,0,0]
	v_pk_fma_f32 v[50:51], s[10:11], v[50:51], v[54:55] op_sel_hi:[0,1,1]
	v_cvt_scalef32_pk_f32_fp4 v[54:55], v36, 1.0 op_sel:[0,1,0]
	v_pk_fma_f32 v[54:55], s[10:11], v[54:55], v[58:59] op_sel_hi:[0,1,1]
	v_cvt_scalef32_pk_f32_fp4 v[58:59], v36, 1.0 op_sel:[1,1,0]
	v_pk_fma_f32 v[58:59], s[10:11], v[58:59], v[62:63] op_sel_hi:[0,1,1]
	v_cvt_scalef32_pk_f32_fp4 v[62:63], v37, 1.0
	v_pk_fma_f32 v[62:63], s[10:11], v[62:63], v[66:67] op_sel_hi:[0,1,1]
	v_cvt_scalef32_pk_f32_fp4 v[66:67], v37, 1.0 op_sel:[1,0,0]
	v_pk_fma_f32 v[66:67], s[10:11], v[66:67], v[70:71] op_sel_hi:[0,1,1]
	v_cvt_scalef32_pk_f32_fp4 v[70:71], v37, 1.0 op_sel:[0,1,0]
	v_cvt_scalef32_pk_f32_fp4 v[36:37], v37, 1.0 op_sel:[1,1,0]
	v_pk_fma_f32 v[36:37], s[10:11], v[36:37], v[40:41] op_sel_hi:[0,1,1]
	v_cvt_scalef32_pk_f32_fp4 v[40:41], v38, 1.0
	v_pk_fma_f32 v[40:41], s[10:11], v[40:41], v[44:45] op_sel_hi:[0,1,1]
	v_cvt_scalef32_pk_f32_fp4 v[44:45], v38, 1.0 op_sel:[1,0,0]
	v_pk_fma_f32 v[44:45], s[10:11], v[44:45], v[48:49] op_sel_hi:[0,1,1]
	v_cvt_scalef32_pk_f32_fp4 v[48:49], v38, 1.0 op_sel:[0,1,0]
	v_pk_fma_f32 v[48:49], s[10:11], v[48:49], v[52:53] op_sel_hi:[0,1,1]
	v_cvt_scalef32_pk_f32_fp4 v[52:53], v38, 1.0 op_sel:[1,1,0]
	v_pk_fma_f32 v[52:53], s[10:11], v[52:53], v[56:57] op_sel_hi:[0,1,1]
	v_cvt_scalef32_pk_f32_fp4 v[56:57], v39, 1.0
	v_pk_fma_f32 v[56:57], s[10:11], v[56:57], v[60:61] op_sel_hi:[0,1,1]
	v_cvt_scalef32_pk_f32_fp4 v[60:61], v39, 1.0 op_sel:[1,0,0]
	v_pk_fma_f32 v[60:61], s[10:11], v[60:61], v[64:65] op_sel_hi:[0,1,1]
	v_cvt_scalef32_pk_f32_fp4 v[64:65], v39, 1.0 op_sel:[0,1,0]
	v_cvt_scalef32_pk_f32_fp4 v[38:39], v39, 1.0 op_sel:[1,1,0]
	v_pk_fma_f32 v[70:71], s[10:11], v[70:71], v[74:75] op_sel_hi:[0,1,1]
	v_pk_fma_f32 v[64:65], s[10:11], v[64:65], v[68:69] op_sel_hi:[0,1,1]
	v_pk_fma_f32 v[38:39], s[10:11], v[38:39], v[42:43] op_sel_hi:[0,1,1]
	v_readlane_b32 s10, v159, s31
	s_waitcnt vmcnt(0)
	v_cvt_scalef32_pk_f32_fp4 v[42:43], v32, 1.0
	v_pk_fma_f32 v[118:119], s[10:11], v[42:43], v[46:47] op_sel_hi:[0,1,1]
	v_cvt_scalef32_pk_f32_fp4 v[42:43], v32, 1.0 op_sel:[1,0,0]
	v_pk_fma_f32 v[122:123], s[10:11], v[42:43], v[50:51] op_sel_hi:[0,1,1]
	v_cvt_scalef32_pk_f32_fp4 v[42:43], v32, 1.0 op_sel:[0,1,0]
	v_pk_fma_f32 v[144:145], s[10:11], v[42:43], v[54:55] op_sel_hi:[0,1,1]
	v_cvt_scalef32_pk_f32_fp4 v[42:43], v32, 1.0 op_sel:[1,1,0]
	v_pk_fma_f32 v[142:143], s[10:11], v[42:43], v[58:59] op_sel_hi:[0,1,1]
	v_cvt_scalef32_pk_f32_fp4 v[42:43], v33, 1.0
	v_pk_fma_f32 v[140:141], s[10:11], v[42:43], v[62:63] op_sel_hi:[0,1,1]
	v_cvt_scalef32_pk_f32_fp4 v[42:43], v33, 1.0 op_sel:[1,0,0]
	v_pk_fma_f32 v[138:139], s[10:11], v[42:43], v[66:67] op_sel_hi:[0,1,1]
	v_cvt_scalef32_pk_f32_fp4 v[42:43], v33, 1.0 op_sel:[0,1,0]
	v_cvt_scalef32_pk_f32_fp4 v[32:33], v33, 1.0 op_sel:[1,1,0]
	v_pk_fma_f32 v[132:133], s[10:11], v[32:33], v[36:37] op_sel_hi:[0,1,1]
	v_cvt_scalef32_pk_f32_fp4 v[32:33], v34, 1.0
	v_pk_fma_f32 v[130:131], s[10:11], v[32:33], v[40:41] op_sel_hi:[0,1,1]
	v_cvt_scalef32_pk_f32_fp4 v[32:33], v34, 1.0 op_sel:[1,0,0]
	v_pk_fma_f32 v[126:127], s[10:11], v[32:33], v[44:45] op_sel_hi:[0,1,1]
	v_cvt_scalef32_pk_f32_fp4 v[32:33], v34, 1.0 op_sel:[0,1,0]
	v_pk_fma_f32 v[124:125], s[10:11], v[32:33], v[48:49] op_sel_hi:[0,1,1]
	v_cvt_scalef32_pk_f32_fp4 v[32:33], v34, 1.0 op_sel:[1,1,0]
	v_pk_fma_f32 v[120:121], s[10:11], v[32:33], v[52:53] op_sel_hi:[0,1,1]
	v_cvt_scalef32_pk_f32_fp4 v[32:33], v35, 1.0
	v_pk_fma_f32 v[116:117], s[10:11], v[32:33], v[56:57] op_sel_hi:[0,1,1]
	v_cvt_scalef32_pk_f32_fp4 v[32:33], v35, 1.0 op_sel:[1,0,0]
	v_pk_fma_f32 v[114:115], s[10:11], v[32:33], v[60:61] op_sel_hi:[0,1,1]
	v_cvt_scalef32_pk_f32_fp4 v[32:33], v35, 1.0 op_sel:[0,1,0]
	v_pk_fma_f32 v[112:113], s[10:11], v[32:33], v[64:65] op_sel_hi:[0,1,1]
	v_cvt_scalef32_pk_f32_fp4 v[32:33], v35, 1.0 op_sel:[1,1,0]
	v_pk_fma_f32 v[134:135], s[10:11], v[42:43], v[70:71] op_sel_hi:[0,1,1]
	v_pk_fma_f32 v[110:111], s[10:11], v[32:33], v[38:39] op_sel_hi:[0,1,1]
	s_cbranch_vccnz .LBB0_909
	v_mov_b64_e32 v[42:43], v[26:27]
	v_mov_b64_e32 v[70:71], v[10:11]
	v_mov_b64_e32 v[50:51], v[30:31]
	v_mov_b64_e32 v[82:83], v[14:15]
	v_mov_b64_e32 v[62:63], v[18:19]
	v_mov_b64_e32 v[90:91], v[2:3]
	v_mov_b64_e32 v[78:79], v[22:23]
	v_mov_b64_e32 v[94:95], v[6:7]
	v_mov_b64_e32 v[40:41], v[24:25]
	v_mov_b64_e32 v[68:69], v[8:9]
	v_mov_b64_e32 v[48:49], v[28:29]
	v_mov_b64_e32 v[80:81], v[12:13]
	v_mov_b64_e32 v[60:61], v[16:17]
	v_mov_b64_e32 v[88:89], v[0:1]
	v_mov_b64_e32 v[76:77], v[20:21]
	v_mov_b64_e32 v[92:93], v[4:5]
	s_mov_b32 s40, s30
	s_branch .LBB0_905

.LBB0_910:
	v_cvt_scalef32_pk_f32_fp4 v[108:109], v92, 1.0
	v_pk_fma_f32 v[108:109], s[24:25], v[108:109], v[118:119] op_sel_hi:[0,1,1]
	v_cvt_scalef32_pk_f32_fp4 v[118:119], v92, 1.0 op_sel:[1,0,0]
	v_pk_fma_f32 v[118:119], s[24:25], v[118:119], v[122:123] op_sel_hi:[0,1,1]
	v_cvt_scalef32_pk_f32_fp4 v[122:123], v92, 1.0 op_sel:[0,1,0]
	v_pk_fma_f32 v[122:123], s[24:25], v[122:123], v[144:145] op_sel_hi:[0,1,1]
	v_cvt_scalef32_pk_f32_fp4 v[144:145], v92, 1.0 op_sel:[1,1,0]
	v_pk_fma_f32 v[142:143], s[24:25], v[144:145], v[142:143] op_sel_hi:[0,1,1]
	v_cvt_scalef32_pk_f32_fp4 v[144:145], v93, 1.0
	v_pk_fma_f32 v[140:141], s[24:25], v[144:145], v[140:141] op_sel_hi:[0,1,1]
	v_cvt_scalef32_pk_f32_fp4 v[144:145], v93, 1.0 op_sel:[1,0,0]
	v_pk_fma_f32 v[138:139], s[24:25], v[144:145], v[138:139] op_sel_hi:[0,1,1]
	v_cvt_scalef32_pk_f32_fp4 v[144:145], v93, 1.0 op_sel:[0,1,0]
	v_cvt_scalef32_pk_f32_fp4 v[92:93], v93, 1.0 op_sel:[1,1,0]
	v_pk_fma_f32 v[92:93], s[24:25], v[92:93], v[132:133] op_sel_hi:[0,1,1]
	v_cvt_scalef32_pk_f32_fp4 v[132:133], v94, 1.0
	v_pk_fma_f32 v[130:131], s[24:25], v[132:133], v[130:131] op_sel_hi:[0,1,1]
	v_cvt_scalef32_pk_f32_fp4 v[132:133], v94, 1.0 op_sel:[1,0,0]
	v_pk_fma_f32 v[126:127], s[24:25], v[132:133], v[126:127] op_sel_hi:[0,1,1]
	v_cvt_scalef32_pk_f32_fp4 v[132:133], v94, 1.0 op_sel:[0,1,0]
	v_pk_fma_f32 v[124:125], s[24:25], v[132:133], v[124:125] op_sel_hi:[0,1,1]
	v_cvt_scalef32_pk_f32_fp4 v[132:133], v94, 1.0 op_sel:[1,1,0]
	v_pk_fma_f32 v[120:121], s[24:25], v[132:133], v[120:121] op_sel_hi:[0,1,1]
	v_cvt_scalef32_pk_f32_fp4 v[132:133], v95, 1.0
	v_pk_fma_f32 v[116:117], s[24:25], v[132:133], v[116:117] op_sel_hi:[0,1,1]
	v_cvt_scalef32_pk_f32_fp4 v[132:133], v95, 1.0 op_sel:[1,0,0]
	v_pk_fma_f32 v[114:115], s[24:25], v[132:133], v[114:115] op_sel_hi:[0,1,1]
	v_cvt_scalef32_pk_f32_fp4 v[132:133], v95, 1.0 op_sel:[0,1,0]
	v_cvt_scalef32_pk_f32_fp4 v[94:95], v95, 1.0 op_sel:[1,1,0]
	v_pk_fma_f32 v[94:95], s[24:25], v[94:95], v[110:111] op_sel_hi:[0,1,1]
	v_cvt_scalef32_pk_f32_fp4 v[110:111], v88, 1.0
	v_pk_fma_f32 v[112:113], s[24:25], v[132:133], v[112:113] op_sel_hi:[0,1,1]
	v_pk_fma_f32 v[108:109], s[22:23], v[110:111], v[108:109] op_sel_hi:[0,1,1]
	v_cvt_scalef32_pk_f32_fp4 v[110:111], v88, 1.0 op_sel:[1,0,0]
	v_cvt_scalef32_pk_f32_fp4 v[132:133], v89, 1.0
	v_pk_fma_f32 v[110:111], s[22:23], v[110:111], v[118:119] op_sel_hi:[0,1,1]
	v_cvt_scalef32_pk_f32_fp4 v[118:119], v88, 1.0 op_sel:[0,1,0]
	v_pk_fma_f32 v[132:133], s[22:23], v[132:133], v[140:141] op_sel_hi:[0,1,1]
	v_cvt_scalef32_pk_f32_fp4 v[140:141], v89, 1.0 op_sel:[1,0,0]
	v_pk_fma_f32 v[118:119], s[22:23], v[118:119], v[122:123] op_sel_hi:[0,1,1]
	v_cvt_scalef32_pk_f32_fp4 v[122:123], v88, 1.0 op_sel:[1,1,0]
	v_pk_fma_f32 v[138:139], s[22:23], v[140:141], v[138:139] op_sel_hi:[0,1,1]
	v_cvt_scalef32_pk_f32_fp4 v[140:141], v89, 1.0 op_sel:[0,1,0]
	v_cvt_scalef32_pk_f32_fp4 v[88:89], v89, 1.0 op_sel:[1,1,0]
	v_pk_fma_f32 v[88:89], s[22:23], v[88:89], v[92:93] op_sel_hi:[0,1,1]
	v_cvt_scalef32_pk_f32_fp4 v[92:93], v90, 1.0
	v_pk_fma_f32 v[92:93], s[22:23], v[92:93], v[130:131] op_sel_hi:[0,1,1]
	v_cvt_scalef32_pk_f32_fp4 v[130:131], v90, 1.0 op_sel:[1,0,0]
	v_pk_fma_f32 v[126:127], s[22:23], v[130:131], v[126:127] op_sel_hi:[0,1,1]
	v_cvt_scalef32_pk_f32_fp4 v[130:131], v90, 1.0 op_sel:[0,1,0]
	v_pk_fma_f32 v[124:125], s[22:23], v[130:131], v[124:125] op_sel_hi:[0,1,1]
	v_cvt_scalef32_pk_f32_fp4 v[130:131], v90, 1.0 op_sel:[1,1,0]
	v_pk_fma_f32 v[120:121], s[22:23], v[130:131], v[120:121] op_sel_hi:[0,1,1]
	v_cvt_scalef32_pk_f32_fp4 v[130:131], v91, 1.0
	v_pk_fma_f32 v[116:117], s[22:23], v[130:131], v[116:117] op_sel_hi:[0,1,1]
	v_cvt_scalef32_pk_f32_fp4 v[130:131], v91, 1.0 op_sel:[1,0,0]
	v_pk_fma_f32 v[114:115], s[22:23], v[130:131], v[114:115] op_sel_hi:[0,1,1]
	v_cvt_scalef32_pk_f32_fp4 v[130:131], v91, 1.0 op_sel:[0,1,0]
	v_cvt_scalef32_pk_f32_fp4 v[90:91], v91, 1.0 op_sel:[1,1,0]
	v_pk_fma_f32 v[90:91], s[22:23], v[90:91], v[94:95] op_sel_hi:[0,1,1]
	v_cvt_scalef32_pk_f32_fp4 v[94:95], v80, 1.0
	v_pk_fma_f32 v[94:95], s[20:21], v[94:95], v[108:109] op_sel_hi:[0,1,1]
	v_cvt_scalef32_pk_f32_fp4 v[108:109], v80, 1.0 op_sel:[1,0,0]
	v_pk_fma_f32 v[108:109], s[20:21], v[108:109], v[110:111] op_sel_hi:[0,1,1]
	v_cvt_scalef32_pk_f32_fp4 v[110:111], v80, 1.0 op_sel:[0,1,0]
	v_pk_fma_f32 v[122:123], s[22:23], v[122:123], v[142:143] op_sel_hi:[0,1,1]
	v_pk_fma_f32 v[110:111], s[20:21], v[110:111], v[118:119] op_sel_hi:[0,1,1]
	v_cvt_scalef32_pk_f32_fp4 v[118:119], v80, 1.0 op_sel:[1,1,0]
	v_pk_fma_f32 v[118:119], s[20:21], v[118:119], v[122:123] op_sel_hi:[0,1,1]
	v_cvt_scalef32_pk_f32_fp4 v[122:123], v81, 1.0
	v_pk_fma_f32 v[112:113], s[22:23], v[130:131], v[112:113] op_sel_hi:[0,1,1]
	v_pk_fma_f32 v[122:123], s[20:21], v[122:123], v[132:133] op_sel_hi:[0,1,1]
	v_cvt_scalef32_pk_f32_fp4 v[130:131], v81, 1.0 op_sel:[1,0,0]
	v_cvt_scalef32_pk_f32_fp4 v[132:133], v81, 1.0 op_sel:[0,1,0]
	v_cvt_scalef32_pk_f32_fp4 v[80:81], v81, 1.0 op_sel:[1,1,0]
	v_pk_fma_f32 v[80:81], s[20:21], v[80:81], v[88:89] op_sel_hi:[0,1,1]
	v_cvt_scalef32_pk_f32_fp4 v[88:89], v82, 1.0
	v_pk_fma_f32 v[88:89], s[20:21], v[88:89], v[92:93] op_sel_hi:[0,1,1]
	v_cvt_scalef32_pk_f32_fp4 v[92:93], v82, 1.0 op_sel:[1,0,0]
	v_pk_fma_f32 v[92:93], s[20:21], v[92:93], v[126:127] op_sel_hi:[0,1,1]
	v_cvt_scalef32_pk_f32_fp4 v[126:127], v82, 1.0 op_sel:[0,1,0]
	v_pk_fma_f32 v[124:125], s[20:21], v[126:127], v[124:125] op_sel_hi:[0,1,1]
	v_cvt_scalef32_pk_f32_fp4 v[126:127], v82, 1.0 op_sel:[1,1,0]
	v_pk_fma_f32 v[120:121], s[20:21], v[126:127], v[120:121] op_sel_hi:[0,1,1]
	v_cvt_scalef32_pk_f32_fp4 v[126:127], v83, 1.0
	v_pk_fma_f32 v[116:117], s[20:21], v[126:127], v[116:117] op_sel_hi:[0,1,1]
	v_cvt_scalef32_pk_f32_fp4 v[126:127], v83, 1.0 op_sel:[1,0,0]
	v_pk_fma_f32 v[114:115], s[20:21], v[126:127], v[114:115] op_sel_hi:[0,1,1]
	v_cvt_scalef32_pk_f32_fp4 v[126:127], v83, 1.0 op_sel:[0,1,0]
	v_cvt_scalef32_pk_f32_fp4 v[82:83], v83, 1.0 op_sel:[1,1,0]
	v_pk_fma_f32 v[82:83], s[20:21], v[82:83], v[90:91] op_sel_hi:[0,1,1]
	v_cvt_scalef32_pk_f32_fp4 v[90:91], v68, 1.0
	v_pk_fma_f32 v[90:91], s[18:19], v[90:91], v[94:95] op_sel_hi:[0,1,1]
	v_cvt_scalef32_pk_f32_fp4 v[94:95], v68, 1.0 op_sel:[1,0,0]
	v_pk_fma_f32 v[94:95], s[18:19], v[94:95], v[108:109] op_sel_hi:[0,1,1]
	v_cvt_scalef32_pk_f32_fp4 v[108:109], v68, 1.0 op_sel:[0,1,0]
	v_pk_fma_f32 v[108:109], s[18:19], v[108:109], v[110:111] op_sel_hi:[0,1,1]
	v_cvt_scalef32_pk_f32_fp4 v[110:111], v68, 1.0 op_sel:[1,1,0]
	v_pk_fma_f32 v[110:111], s[18:19], v[110:111], v[118:119] op_sel_hi:[0,1,1]
	v_cvt_scalef32_pk_f32_fp4 v[118:119], v69, 1.0
	v_pk_fma_f32 v[112:113], s[20:21], v[126:127], v[112:113] op_sel_hi:[0,1,1]
	v_pk_fma_f32 v[118:119], s[18:19], v[118:119], v[122:123] op_sel_hi:[0,1,1]
	v_cvt_scalef32_pk_f32_fp4 v[122:123], v69, 1.0 op_sel:[1,0,0]
	v_cvt_scalef32_pk_f32_fp4 v[126:127], v69, 1.0 op_sel:[0,1,0]
	v_cvt_scalef32_pk_f32_fp4 v[68:69], v69, 1.0 op_sel:[1,1,0]
	v_pk_fma_f32 v[68:69], s[18:19], v[68:69], v[80:81] op_sel_hi:[0,1,1]
	v_cvt_scalef32_pk_f32_fp4 v[80:81], v70, 1.0
	v_pk_fma_f32 v[80:81], s[18:19], v[80:81], v[88:89] op_sel_hi:[0,1,1]
	v_cvt_scalef32_pk_f32_fp4 v[88:89], v70, 1.0 op_sel:[1,0,0]
	v_pk_fma_f32 v[88:89], s[18:19], v[88:89], v[92:93] op_sel_hi:[0,1,1]
	v_cvt_scalef32_pk_f32_fp4 v[92:93], v70, 1.0 op_sel:[0,1,0]
	v_pk_fma_f32 v[92:93], s[18:19], v[92:93], v[124:125] op_sel_hi:[0,1,1]
	v_cvt_scalef32_pk_f32_fp4 v[124:125], v70, 1.0 op_sel:[1,1,0]
	v_pk_fma_f32 v[120:121], s[18:19], v[124:125], v[120:121] op_sel_hi:[0,1,1]
	v_cvt_scalef32_pk_f32_fp4 v[124:125], v71, 1.0
	v_pk_fma_f32 v[116:117], s[18:19], v[124:125], v[116:117] op_sel_hi:[0,1,1]
	v_cvt_scalef32_pk_f32_fp4 v[124:125], v71, 1.0 op_sel:[1,0,0]
	v_pk_fma_f32 v[114:115], s[18:19], v[124:125], v[114:115] op_sel_hi:[0,1,1]
	v_cvt_scalef32_pk_f32_fp4 v[124:125], v71, 1.0 op_sel:[0,1,0]
	v_cvt_scalef32_pk_f32_fp4 v[70:71], v71, 1.0 op_sel:[1,1,0]
	v_pk_fma_f32 v[70:71], s[18:19], v[70:71], v[82:83] op_sel_hi:[0,1,1]
	v_cvt_scalef32_pk_f32_fp4 v[82:83], v76, 1.0
	v_pk_fma_f32 v[82:83], s[16:17], v[82:83], v[90:91] op_sel_hi:[0,1,1]
	v_cvt_scalef32_pk_f32_fp4 v[90:91], v76, 1.0 op_sel:[1,0,0]
	v_pk_fma_f32 v[90:91], s[16:17], v[90:91], v[94:95] op_sel_hi:[0,1,1]
	v_cvt_scalef32_pk_f32_fp4 v[94:95], v76, 1.0 op_sel:[0,1,0]
	v_pk_fma_f32 v[94:95], s[16:17], v[94:95], v[108:109] op_sel_hi:[0,1,1]
	v_cvt_scalef32_pk_f32_fp4 v[108:109], v76, 1.0 op_sel:[1,1,0]
	v_pk_fma_f32 v[130:131], s[20:21], v[130:131], v[138:139] op_sel_hi:[0,1,1]
	v_pk_fma_f32 v[108:109], s[16:17], v[108:109], v[110:111] op_sel_hi:[0,1,1]
	v_cvt_scalef32_pk_f32_fp4 v[110:111], v77, 1.0
	v_pk_fma_f32 v[122:123], s[18:19], v[122:123], v[130:131] op_sel_hi:[0,1,1]
	v_pk_fma_f32 v[110:111], s[16:17], v[110:111], v[118:119] op_sel_hi:[0,1,1]
	v_cvt_scalef32_pk_f32_fp4 v[118:119], v77, 1.0 op_sel:[1,0,0]
	v_pk_fma_f32 v[118:119], s[16:17], v[118:119], v[122:123] op_sel_hi:[0,1,1]
	v_cvt_scalef32_pk_f32_fp4 v[122:123], v77, 1.0 op_sel:[0,1,0]
	v_cvt_scalef32_pk_f32_fp4 v[76:77], v77, 1.0 op_sel:[1,1,0]
	v_pk_fma_f32 v[68:69], s[16:17], v[76:77], v[68:69] op_sel_hi:[0,1,1]
	v_cvt_scalef32_pk_f32_fp4 v[76:77], v78, 1.0
	v_pk_fma_f32 v[76:77], s[16:17], v[76:77], v[80:81] op_sel_hi:[0,1,1]
	v_cvt_scalef32_pk_f32_fp4 v[80:81], v78, 1.0 op_sel:[1,0,0]
	v_pk_fma_f32 v[80:81], s[16:17], v[80:81], v[88:89] op_sel_hi:[0,1,1]
	v_cvt_scalef32_pk_f32_fp4 v[88:89], v78, 1.0 op_sel:[0,1,0]
	v_pk_fma_f32 v[88:89], s[16:17], v[88:89], v[92:93] op_sel_hi:[0,1,1]
	v_cvt_scalef32_pk_f32_fp4 v[92:93], v78, 1.0 op_sel:[1,1,0]
	v_pk_fma_f32 v[92:93], s[16:17], v[92:93], v[120:121] op_sel_hi:[0,1,1]
	v_cvt_scalef32_pk_f32_fp4 v[120:121], v79, 1.0
	v_pk_fma_f32 v[116:117], s[16:17], v[120:121], v[116:117] op_sel_hi:[0,1,1]
	v_cvt_scalef32_pk_f32_fp4 v[120:121], v79, 1.0 op_sel:[1,0,0]
	v_pk_fma_f32 v[114:115], s[16:17], v[120:121], v[114:115] op_sel_hi:[0,1,1]
	v_cvt_scalef32_pk_f32_fp4 v[120:121], v79, 1.0 op_sel:[0,1,0]
	v_cvt_scalef32_pk_f32_fp4 v[78:79], v79, 1.0 op_sel:[1,1,0]
	v_pk_fma_f32 v[70:71], s[16:17], v[78:79], v[70:71] op_sel_hi:[0,1,1]
	v_cvt_scalef32_pk_f32_fp4 v[78:79], v60, 1.0
	v_pk_fma_f32 v[78:79], s[14:15], v[78:79], v[82:83] op_sel_hi:[0,1,1]
	v_cvt_scalef32_pk_f32_fp4 v[82:83], v60, 1.0 op_sel:[1,0,0]
	v_pk_fma_f32 v[82:83], s[14:15], v[82:83], v[90:91] op_sel_hi:[0,1,1]
	v_cvt_scalef32_pk_f32_fp4 v[90:91], v60, 1.0 op_sel:[0,1,0]
	v_pk_fma_f32 v[90:91], s[14:15], v[90:91], v[94:95] op_sel_hi:[0,1,1]
	v_cvt_scalef32_pk_f32_fp4 v[94:95], v60, 1.0 op_sel:[1,1,0]
	v_pk_fma_f32 v[94:95], s[14:15], v[94:95], v[108:109] op_sel_hi:[0,1,1]
	v_cvt_scalef32_pk_f32_fp4 v[108:109], v61, 1.0
	v_pk_fma_f32 v[108:109], s[14:15], v[108:109], v[110:111] op_sel_hi:[0,1,1]
	v_cvt_scalef32_pk_f32_fp4 v[110:111], v61, 1.0 op_sel:[1,0,0]
	v_pk_fma_f32 v[110:111], s[14:15], v[110:111], v[118:119] op_sel_hi:[0,1,1]
	v_cvt_scalef32_pk_f32_fp4 v[118:119], v61, 1.0 op_sel:[0,1,0]
	v_cvt_scalef32_pk_f32_fp4 v[60:61], v61, 1.0 op_sel:[1,1,0]
	v_pk_fma_f32 v[60:61], s[14:15], v[60:61], v[68:69] op_sel_hi:[0,1,1]
	v_cvt_scalef32_pk_f32_fp4 v[68:69], v62, 1.0
	v_pk_fma_f32 v[68:69], s[14:15], v[68:69], v[76:77] op_sel_hi:[0,1,1]
	v_cvt_scalef32_pk_f32_fp4 v[76:77], v62, 1.0 op_sel:[1,0,0]
	v_pk_fma_f32 v[76:77], s[14:15], v[76:77], v[80:81] op_sel_hi:[0,1,1]
	v_cvt_scalef32_pk_f32_fp4 v[80:81], v62, 1.0 op_sel:[0,1,0]
	v_pk_fma_f32 v[80:81], s[14:15], v[80:81], v[88:89] op_sel_hi:[0,1,1]
	v_cvt_scalef32_pk_f32_fp4 v[88:89], v62, 1.0 op_sel:[1,1,0]
	v_pk_fma_f32 v[88:89], s[14:15], v[88:89], v[92:93] op_sel_hi:[0,1,1]
	v_cvt_scalef32_pk_f32_fp4 v[92:93], v63, 1.0
	v_pk_fma_f32 v[92:93], s[14:15], v[92:93], v[116:117] op_sel_hi:[0,1,1]
	v_cvt_scalef32_pk_f32_fp4 v[116:117], v63, 1.0 op_sel:[1,0,0]
	v_pk_fma_f32 v[114:115], s[14:15], v[116:117], v[114:115] op_sel_hi:[0,1,1]
	v_cvt_scalef32_pk_f32_fp4 v[116:117], v63, 1.0 op_sel:[0,1,0]
	v_cvt_scalef32_pk_f32_fp4 v[62:63], v63, 1.0 op_sel:[1,1,0]
	v_pk_fma_f32 v[62:63], s[14:15], v[62:63], v[70:71] op_sel_hi:[0,1,1]
	v_cvt_scalef32_pk_f32_fp4 v[70:71], v48, 1.0
	v_pk_fma_f32 v[70:71], s[12:13], v[70:71], v[78:79] op_sel_hi:[0,1,1]
	v_cvt_scalef32_pk_f32_fp4 v[78:79], v48, 1.0 op_sel:[1,0,0]
	v_pk_fma_f32 v[78:79], s[12:13], v[78:79], v[82:83] op_sel_hi:[0,1,1]
	v_cvt_scalef32_pk_f32_fp4 v[82:83], v48, 1.0 op_sel:[0,1,0]
	v_pk_fma_f32 v[82:83], s[12:13], v[82:83], v[90:91] op_sel_hi:[0,1,1]
	v_cvt_scalef32_pk_f32_fp4 v[90:91], v48, 1.0 op_sel:[1,1,0]
	v_pk_fma_f32 v[90:91], s[12:13], v[90:91], v[94:95] op_sel_hi:[0,1,1]
	v_cvt_scalef32_pk_f32_fp4 v[94:95], v49, 1.0
	v_pk_fma_f32 v[94:95], s[12:13], v[94:95], v[108:109] op_sel_hi:[0,1,1]
	v_cvt_scalef32_pk_f32_fp4 v[108:109], v49, 1.0 op_sel:[1,0,0]
	v_pk_fma_f32 v[108:109], s[12:13], v[108:109], v[110:111] op_sel_hi:[0,1,1]
	v_cvt_scalef32_pk_f32_fp4 v[110:111], v49, 1.0 op_sel:[0,1,0]
	v_cvt_scalef32_pk_f32_fp4 v[48:49], v49, 1.0 op_sel:[1,1,0]
	v_pk_fma_f32 v[48:49], s[12:13], v[48:49], v[60:61] op_sel_hi:[0,1,1]
	v_cvt_scalef32_pk_f32_fp4 v[60:61], v50, 1.0
	v_pk_fma_f32 v[60:61], s[12:13], v[60:61], v[68:69] op_sel_hi:[0,1,1]
	v_cvt_scalef32_pk_f32_fp4 v[68:69], v50, 1.0 op_sel:[1,0,0]
	v_pk_fma_f32 v[68:69], s[12:13], v[68:69], v[76:77] op_sel_hi:[0,1,1]
	v_cvt_scalef32_pk_f32_fp4 v[76:77], v50, 1.0 op_sel:[0,1,0]
	v_pk_fma_f32 v[76:77], s[12:13], v[76:77], v[80:81] op_sel_hi:[0,1,1]
	v_cvt_scalef32_pk_f32_fp4 v[80:81], v50, 1.0 op_sel:[1,1,0]
	v_pk_fma_f32 v[80:81], s[12:13], v[80:81], v[88:89] op_sel_hi:[0,1,1]
	v_cvt_scalef32_pk_f32_fp4 v[88:89], v51, 1.0
	v_pk_fma_f32 v[88:89], s[12:13], v[88:89], v[92:93] op_sel_hi:[0,1,1]
	v_cvt_scalef32_pk_f32_fp4 v[92:93], v51, 1.0 op_sel:[1,0,0]
	v_pk_fma_f32 v[92:93], s[12:13], v[92:93], v[114:115] op_sel_hi:[0,1,1]
	v_cvt_scalef32_pk_f32_fp4 v[114:115], v51, 1.0 op_sel:[0,1,0]
	v_cvt_scalef32_pk_f32_fp4 v[50:51], v51, 1.0 op_sel:[1,1,0]
	v_pk_fma_f32 v[50:51], s[12:13], v[50:51], v[62:63] op_sel_hi:[0,1,1]
	v_cvt_scalef32_pk_f32_fp4 v[62:63], v40, 1.0
	v_pk_fma_f32 v[62:63], s[10:11], v[62:63], v[70:71] op_sel_hi:[0,1,1]
	v_cvt_scalef32_pk_f32_fp4 v[70:71], v40, 1.0 op_sel:[1,0,0]
	v_pk_fma_f32 v[70:71], s[10:11], v[70:71], v[78:79] op_sel_hi:[0,1,1]
	v_cvt_scalef32_pk_f32_fp4 v[78:79], v40, 1.0 op_sel:[0,1,0]
	v_pk_fma_f32 v[78:79], s[10:11], v[78:79], v[82:83] op_sel_hi:[0,1,1]
	v_cvt_scalef32_pk_f32_fp4 v[82:83], v40, 1.0 op_sel:[1,1,0]
	v_pk_fma_f32 v[82:83], s[10:11], v[82:83], v[90:91] op_sel_hi:[0,1,1]
	v_cvt_scalef32_pk_f32_fp4 v[90:91], v41, 1.0
	v_pk_fma_f32 v[90:91], s[10:11], v[90:91], v[94:95] op_sel_hi:[0,1,1]
	v_cvt_scalef32_pk_f32_fp4 v[94:95], v41, 1.0 op_sel:[1,0,0]
	v_pk_fma_f32 v[94:95], s[10:11], v[94:95], v[108:109] op_sel_hi:[0,1,1]
	v_cvt_scalef32_pk_f32_fp4 v[108:109], v41, 1.0 op_sel:[0,1,0]
	v_cvt_scalef32_pk_f32_fp4 v[40:41], v41, 1.0 op_sel:[1,1,0]
	v_pk_fma_f32 v[134:135], s[24:25], v[144:145], v[134:135] op_sel_hi:[0,1,1]
	v_pk_fma_f32 v[40:41], s[10:11], v[40:41], v[48:49] op_sel_hi:[0,1,1]
	v_cvt_scalef32_pk_f32_fp4 v[48:49], v42, 1.0
	v_pk_fma_f32 v[134:135], s[22:23], v[140:141], v[134:135] op_sel_hi:[0,1,1]
	v_pk_fma_f32 v[48:49], s[10:11], v[48:49], v[60:61] op_sel_hi:[0,1,1]
	v_cvt_scalef32_pk_f32_fp4 v[60:61], v42, 1.0 op_sel:[1,0,0]
	v_pk_fma_f32 v[132:133], s[20:21], v[132:133], v[134:135] op_sel_hi:[0,1,1]
	v_pk_fma_f32 v[60:61], s[10:11], v[60:61], v[68:69] op_sel_hi:[0,1,1]
	v_cvt_scalef32_pk_f32_fp4 v[68:69], v42, 1.0 op_sel:[0,1,0]
	v_pk_fma_f32 v[126:127], s[18:19], v[126:127], v[132:133] op_sel_hi:[0,1,1]
	v_pk_fma_f32 v[112:113], s[18:19], v[124:125], v[112:113] op_sel_hi:[0,1,1]
	v_pk_fma_f32 v[68:69], s[10:11], v[68:69], v[76:77] op_sel_hi:[0,1,1]
	v_cvt_scalef32_pk_f32_fp4 v[76:77], v42, 1.0 op_sel:[1,1,0]
	v_pk_fma_f32 v[122:123], s[16:17], v[122:123], v[126:127] op_sel_hi:[0,1,1]
	v_pk_fma_f32 v[112:113], s[16:17], v[120:121], v[112:113] op_sel_hi:[0,1,1]
	v_pk_fma_f32 v[76:77], s[10:11], v[76:77], v[80:81] op_sel_hi:[0,1,1]
	v_cvt_scalef32_pk_f32_fp4 v[80:81], v43, 1.0
	v_pk_fma_f32 v[118:119], s[14:15], v[118:119], v[122:123] op_sel_hi:[0,1,1]
	v_pk_fma_f32 v[112:113], s[14:15], v[116:117], v[112:113] op_sel_hi:[0,1,1]
	v_pk_fma_f32 v[80:81], s[10:11], v[80:81], v[88:89] op_sel_hi:[0,1,1]
	v_cvt_scalef32_pk_f32_fp4 v[88:89], v43, 1.0 op_sel:[1,0,0]
	v_pk_fma_f32 v[110:111], s[12:13], v[110:111], v[118:119] op_sel_hi:[0,1,1]
	v_pk_fma_f32 v[112:113], s[12:13], v[114:115], v[112:113] op_sel_hi:[0,1,1]
	v_pk_fma_f32 v[88:89], s[10:11], v[88:89], v[92:93] op_sel_hi:[0,1,1]
	v_cvt_scalef32_pk_f32_fp4 v[92:93], v43, 1.0 op_sel:[0,1,0]
	v_cvt_scalef32_pk_f32_fp4 v[42:43], v43, 1.0 op_sel:[1,1,0]
	v_pk_fma_f32 v[108:109], s[10:11], v[108:109], v[110:111] op_sel_hi:[0,1,1]
	v_pk_fma_f32 v[92:93], s[10:11], v[92:93], v[112:113] op_sel_hi:[0,1,1]
	v_pk_fma_f32 v[42:43], s[10:11], v[42:43], v[50:51] op_sel_hi:[0,1,1]
	v_readlane_b32 s10, v107, s39
	s_waitcnt vmcnt(15)
	v_cvt_scalef32_pk_f32_fp4 v[50:51], v84, 1.0
	s_andn2_b64 vcc, exec, s[4:5]
	v_pk_fma_f32 v[50:51], s[10:11], v[50:51], v[62:63] op_sel_hi:[0,1,1]
	v_cvt_scalef32_pk_f32_fp4 v[62:63], v84, 1.0 op_sel:[1,0,0]
	v_pk_fma_f32 v[62:63], s[10:11], v[62:63], v[70:71] op_sel_hi:[0,1,1]
	v_cvt_scalef32_pk_f32_fp4 v[70:71], v84, 1.0 op_sel:[0,1,0]
	v_pk_fma_f32 v[70:71], s[10:11], v[70:71], v[78:79] op_sel_hi:[0,1,1]
	v_cvt_scalef32_pk_f32_fp4 v[78:79], v84, 1.0 op_sel:[1,1,0]
	v_pk_fma_f32 v[78:79], s[10:11], v[78:79], v[82:83] op_sel_hi:[0,1,1]
	v_cvt_scalef32_pk_f32_fp4 v[82:83], v85, 1.0
	v_pk_fma_f32 v[82:83], s[10:11], v[82:83], v[90:91] op_sel_hi:[0,1,1]
	v_cvt_scalef32_pk_f32_fp4 v[90:91], v85, 1.0 op_sel:[1,0,0]
	v_pk_fma_f32 v[90:91], s[10:11], v[90:91], v[94:95] op_sel_hi:[0,1,1]
	v_cvt_scalef32_pk_f32_fp4 v[94:95], v85, 1.0 op_sel:[0,1,0]
	v_cvt_scalef32_pk_f32_fp4 v[84:85], v85, 1.0 op_sel:[1,1,0]
	v_pk_fma_f32 v[40:41], s[10:11], v[84:85], v[40:41] op_sel_hi:[0,1,1]
	v_cvt_scalef32_pk_f32_fp4 v[84:85], v86, 1.0
	v_pk_fma_f32 v[48:49], s[10:11], v[84:85], v[48:49] op_sel_hi:[0,1,1]
	v_cvt_scalef32_pk_f32_fp4 v[84:85], v86, 1.0 op_sel:[1,0,0]
	v_pk_fma_f32 v[60:61], s[10:11], v[84:85], v[60:61] op_sel_hi:[0,1,1]
	v_cvt_scalef32_pk_f32_fp4 v[84:85], v86, 1.0 op_sel:[0,1,0]
	v_pk_fma_f32 v[68:69], s[10:11], v[84:85], v[68:69] op_sel_hi:[0,1,1]
	v_cvt_scalef32_pk_f32_fp4 v[84:85], v86, 1.0 op_sel:[1,1,0]
	v_pk_fma_f32 v[76:77], s[10:11], v[84:85], v[76:77] op_sel_hi:[0,1,1]
	v_cvt_scalef32_pk_f32_fp4 v[84:85], v87, 1.0
	v_pk_fma_f32 v[80:81], s[10:11], v[84:85], v[80:81] op_sel_hi:[0,1,1]
	v_cvt_scalef32_pk_f32_fp4 v[84:85], v87, 1.0 op_sel:[1,0,0]
	v_pk_fma_f32 v[84:85], s[10:11], v[84:85], v[88:89] op_sel_hi:[0,1,1]
	v_cvt_scalef32_pk_f32_fp4 v[88:89], v87, 1.0 op_sel:[0,1,0]
	v_cvt_scalef32_pk_f32_fp4 v[86:87], v87, 1.0 op_sel:[1,1,0]
	v_pk_fma_f32 v[94:95], s[10:11], v[94:95], v[108:109] op_sel_hi:[0,1,1]
	v_pk_fma_f32 v[88:89], s[10:11], v[88:89], v[92:93] op_sel_hi:[0,1,1]
	v_pk_fma_f32 v[42:43], s[10:11], v[86:87], v[42:43] op_sel_hi:[0,1,1]
	v_readlane_b32 s10, v107, s38
	s_waitcnt vmcnt(14)
	v_cvt_scalef32_pk_f32_fp4 v[86:87], v72, 1.0
	s_mov_b32 s40, s30
	v_pk_fma_f32 v[50:51], s[10:11], v[86:87], v[50:51] op_sel_hi:[0,1,1]
	v_cvt_scalef32_pk_f32_fp4 v[86:87], v72, 1.0 op_sel:[1,0,0]
	v_pk_fma_f32 v[62:63], s[10:11], v[86:87], v[62:63] op_sel_hi:[0,1,1]
	v_cvt_scalef32_pk_f32_fp4 v[86:87], v72, 1.0 op_sel:[0,1,0]
	v_pk_fma_f32 v[70:71], s[10:11], v[86:87], v[70:71] op_sel_hi:[0,1,1]
	v_cvt_scalef32_pk_f32_fp4 v[86:87], v72, 1.0 op_sel:[1,1,0]
	v_pk_fma_f32 v[78:79], s[10:11], v[86:87], v[78:79] op_sel_hi:[0,1,1]
	v_cvt_scalef32_pk_f32_fp4 v[86:87], v73, 1.0
	v_pk_fma_f32 v[82:83], s[10:11], v[86:87], v[82:83] op_sel_hi:[0,1,1]
	v_cvt_scalef32_pk_f32_fp4 v[86:87], v73, 1.0 op_sel:[1,0,0]
	v_pk_fma_f32 v[86:87], s[10:11], v[86:87], v[90:91] op_sel_hi:[0,1,1]
	v_cvt_scalef32_pk_f32_fp4 v[90:91], v73, 1.0 op_sel:[0,1,0]
	v_cvt_scalef32_pk_f32_fp4 v[72:73], v73, 1.0 op_sel:[1,1,0]
	v_pk_fma_f32 v[40:41], s[10:11], v[72:73], v[40:41] op_sel_hi:[0,1,1]
	v_cvt_scalef32_pk_f32_fp4 v[72:73], v74, 1.0
	v_pk_fma_f32 v[48:49], s[10:11], v[72:73], v[48:49] op_sel_hi:[0,1,1]
	v_cvt_scalef32_pk_f32_fp4 v[72:73], v74, 1.0 op_sel:[1,0,0]
	v_pk_fma_f32 v[60:61], s[10:11], v[72:73], v[60:61] op_sel_hi:[0,1,1]
	v_cvt_scalef32_pk_f32_fp4 v[72:73], v74, 1.0 op_sel:[0,1,0]
	v_pk_fma_f32 v[68:69], s[10:11], v[72:73], v[68:69] op_sel_hi:[0,1,1]
	v_cvt_scalef32_pk_f32_fp4 v[72:73], v74, 1.0 op_sel:[1,1,0]
	v_pk_fma_f32 v[72:73], s[10:11], v[72:73], v[76:77] op_sel_hi:[0,1,1]
	v_cvt_scalef32_pk_f32_fp4 v[76:77], v75, 1.0
	v_pk_fma_f32 v[76:77], s[10:11], v[76:77], v[80:81] op_sel_hi:[0,1,1]
	v_cvt_scalef32_pk_f32_fp4 v[80:81], v75, 1.0 op_sel:[1,0,0]
	v_pk_fma_f32 v[80:81], s[10:11], v[80:81], v[84:85] op_sel_hi:[0,1,1]
	v_cvt_scalef32_pk_f32_fp4 v[84:85], v75, 1.0 op_sel:[0,1,0]
	v_cvt_scalef32_pk_f32_fp4 v[74:75], v75, 1.0 op_sel:[1,1,0]
	v_pk_fma_f32 v[90:91], s[10:11], v[90:91], v[94:95] op_sel_hi:[0,1,1]
	v_pk_fma_f32 v[84:85], s[10:11], v[84:85], v[88:89] op_sel_hi:[0,1,1]
	v_pk_fma_f32 v[42:43], s[10:11], v[74:75], v[42:43] op_sel_hi:[0,1,1]
	v_readlane_b32 s10, v107, s37
	s_waitcnt vmcnt(13)
	v_cvt_scalef32_pk_f32_fp4 v[74:75], v64, 1.0
	v_pk_fma_f32 v[50:51], s[10:11], v[74:75], v[50:51] op_sel_hi:[0,1,1]
	v_cvt_scalef32_pk_f32_fp4 v[74:75], v64, 1.0 op_sel:[1,0,0]
	v_pk_fma_f32 v[62:63], s[10:11], v[74:75], v[62:63] op_sel_hi:[0,1,1]
	v_cvt_scalef32_pk_f32_fp4 v[74:75], v64, 1.0 op_sel:[0,1,0]
	v_pk_fma_f32 v[70:71], s[10:11], v[74:75], v[70:71] op_sel_hi:[0,1,1]
	v_cvt_scalef32_pk_f32_fp4 v[74:75], v64, 1.0 op_sel:[1,1,0]
	v_pk_fma_f32 v[74:75], s[10:11], v[74:75], v[78:79] op_sel_hi:[0,1,1]
	v_cvt_scalef32_pk_f32_fp4 v[78:79], v65, 1.0
	v_pk_fma_f32 v[78:79], s[10:11], v[78:79], v[82:83] op_sel_hi:[0,1,1]
	v_cvt_scalef32_pk_f32_fp4 v[82:83], v65, 1.0 op_sel:[1,0,0]
	v_pk_fma_f32 v[82:83], s[10:11], v[82:83], v[86:87] op_sel_hi:[0,1,1]
	v_cvt_scalef32_pk_f32_fp4 v[86:87], v65, 1.0 op_sel:[0,1,0]
	v_cvt_scalef32_pk_f32_fp4 v[64:65], v65, 1.0 op_sel:[1,1,0]
	v_pk_fma_f32 v[40:41], s[10:11], v[64:65], v[40:41] op_sel_hi:[0,1,1]
	v_cvt_scalef32_pk_f32_fp4 v[64:65], v66, 1.0
	v_pk_fma_f32 v[48:49], s[10:11], v[64:65], v[48:49] op_sel_hi:[0,1,1]
	v_cvt_scalef32_pk_f32_fp4 v[64:65], v66, 1.0 op_sel:[1,0,0]
	v_pk_fma_f32 v[60:61], s[10:11], v[64:65], v[60:61] op_sel_hi:[0,1,1]
	v_cvt_scalef32_pk_f32_fp4 v[64:65], v66, 1.0 op_sel:[0,1,0]
	v_pk_fma_f32 v[64:65], s[10:11], v[64:65], v[68:69] op_sel_hi:[0,1,1]
	v_cvt_scalef32_pk_f32_fp4 v[68:69], v66, 1.0 op_sel:[1,1,0]
	v_pk_fma_f32 v[68:69], s[10:11], v[68:69], v[72:73] op_sel_hi:[0,1,1]
	v_cvt_scalef32_pk_f32_fp4 v[72:73], v67, 1.0
	v_pk_fma_f32 v[72:73], s[10:11], v[72:73], v[76:77] op_sel_hi:[0,1,1]
	v_cvt_scalef32_pk_f32_fp4 v[76:77], v67, 1.0 op_sel:[1,0,0]
	v_pk_fma_f32 v[76:77], s[10:11], v[76:77], v[80:81] op_sel_hi:[0,1,1]
	v_cvt_scalef32_pk_f32_fp4 v[80:81], v67, 1.0 op_sel:[0,1,0]
	v_cvt_scalef32_pk_f32_fp4 v[66:67], v67, 1.0 op_sel:[1,1,0]
	v_pk_fma_f32 v[86:87], s[10:11], v[86:87], v[90:91] op_sel_hi:[0,1,1]
	v_pk_fma_f32 v[80:81], s[10:11], v[80:81], v[84:85] op_sel_hi:[0,1,1]
	v_pk_fma_f32 v[42:43], s[10:11], v[66:67], v[42:43] op_sel_hi:[0,1,1]
	v_readlane_b32 s10, v107, s36
	s_waitcnt vmcnt(12)
	v_cvt_scalef32_pk_f32_fp4 v[66:67], v56, 1.0
	v_pk_fma_f32 v[50:51], s[10:11], v[66:67], v[50:51] op_sel_hi:[0,1,1]
	v_cvt_scalef32_pk_f32_fp4 v[66:67], v56, 1.0 op_sel:[1,0,0]
	v_pk_fma_f32 v[62:63], s[10:11], v[66:67], v[62:63] op_sel_hi:[0,1,1]
	v_cvt_scalef32_pk_f32_fp4 v[66:67], v56, 1.0 op_sel:[0,1,0]
	v_pk_fma_f32 v[66:67], s[10:11], v[66:67], v[70:71] op_sel_hi:[0,1,1]
	v_cvt_scalef32_pk_f32_fp4 v[70:71], v56, 1.0 op_sel:[1,1,0]
	v_pk_fma_f32 v[70:71], s[10:11], v[70:71], v[74:75] op_sel_hi:[0,1,1]
	v_cvt_scalef32_pk_f32_fp4 v[74:75], v57, 1.0
	v_pk_fma_f32 v[74:75], s[10:11], v[74:75], v[78:79] op_sel_hi:[0,1,1]
	v_cvt_scalef32_pk_f32_fp4 v[78:79], v57, 1.0 op_sel:[1,0,0]
	v_pk_fma_f32 v[78:79], s[10:11], v[78:79], v[82:83] op_sel_hi:[0,1,1]
	v_cvt_scalef32_pk_f32_fp4 v[82:83], v57, 1.0 op_sel:[0,1,0]
	v_cvt_scalef32_pk_f32_fp4 v[56:57], v57, 1.0 op_sel:[1,1,0]
	v_pk_fma_f32 v[40:41], s[10:11], v[56:57], v[40:41] op_sel_hi:[0,1,1]
	v_cvt_scalef32_pk_f32_fp4 v[56:57], v58, 1.0
	v_pk_fma_f32 v[48:49], s[10:11], v[56:57], v[48:49] op_sel_hi:[0,1,1]
	v_cvt_scalef32_pk_f32_fp4 v[56:57], v58, 1.0 op_sel:[1,0,0]
	v_pk_fma_f32 v[56:57], s[10:11], v[56:57], v[60:61] op_sel_hi:[0,1,1]
	v_cvt_scalef32_pk_f32_fp4 v[60:61], v58, 1.0 op_sel:[0,1,0]
	v_pk_fma_f32 v[60:61], s[10:11], v[60:61], v[64:65] op_sel_hi:[0,1,1]
	v_cvt_scalef32_pk_f32_fp4 v[64:65], v58, 1.0 op_sel:[1,1,0]
	v_pk_fma_f32 v[64:65], s[10:11], v[64:65], v[68:69] op_sel_hi:[0,1,1]
	v_cvt_scalef32_pk_f32_fp4 v[68:69], v59, 1.0
	v_pk_fma_f32 v[68:69], s[10:11], v[68:69], v[72:73] op_sel_hi:[0,1,1]
	v_cvt_scalef32_pk_f32_fp4 v[72:73], v59, 1.0 op_sel:[1,0,0]
	v_pk_fma_f32 v[72:73], s[10:11], v[72:73], v[76:77] op_sel_hi:[0,1,1]
	v_cvt_scalef32_pk_f32_fp4 v[76:77], v59, 1.0 op_sel:[0,1,0]
	v_cvt_scalef32_pk_f32_fp4 v[58:59], v59, 1.0 op_sel:[1,1,0]
	v_pk_fma_f32 v[82:83], s[10:11], v[82:83], v[86:87] op_sel_hi:[0,1,1]
	v_pk_fma_f32 v[76:77], s[10:11], v[76:77], v[80:81] op_sel_hi:[0,1,1]
	v_pk_fma_f32 v[42:43], s[10:11], v[58:59], v[42:43] op_sel_hi:[0,1,1]
	v_readlane_b32 s10, v107, s35
	s_waitcnt vmcnt(11)
	v_cvt_scalef32_pk_f32_fp4 v[58:59], v52, 1.0
	v_pk_fma_f32 v[50:51], s[10:11], v[58:59], v[50:51] op_sel_hi:[0,1,1]
	v_cvt_scalef32_pk_f32_fp4 v[58:59], v52, 1.0 op_sel:[1,0,0]
	v_pk_fma_f32 v[58:59], s[10:11], v[58:59], v[62:63] op_sel_hi:[0,1,1]
	v_cvt_scalef32_pk_f32_fp4 v[62:63], v52, 1.0 op_sel:[0,1,0]
	v_pk_fma_f32 v[62:63], s[10:11], v[62:63], v[66:67] op_sel_hi:[0,1,1]
	v_cvt_scalef32_pk_f32_fp4 v[66:67], v52, 1.0 op_sel:[1,1,0]
	v_pk_fma_f32 v[66:67], s[10:11], v[66:67], v[70:71] op_sel_hi:[0,1,1]
	v_cvt_scalef32_pk_f32_fp4 v[70:71], v53, 1.0
	v_pk_fma_f32 v[70:71], s[10:11], v[70:71], v[74:75] op_sel_hi:[0,1,1]
	v_cvt_scalef32_pk_f32_fp4 v[74:75], v53, 1.0 op_sel:[1,0,0]
	v_pk_fma_f32 v[74:75], s[10:11], v[74:75], v[78:79] op_sel_hi:[0,1,1]
	v_cvt_scalef32_pk_f32_fp4 v[78:79], v53, 1.0 op_sel:[0,1,0]
	v_cvt_scalef32_pk_f32_fp4 v[52:53], v53, 1.0 op_sel:[1,1,0]
	v_pk_fma_f32 v[40:41], s[10:11], v[52:53], v[40:41] op_sel_hi:[0,1,1]
	v_cvt_scalef32_pk_f32_fp4 v[52:53], v54, 1.0
	v_pk_fma_f32 v[48:49], s[10:11], v[52:53], v[48:49] op_sel_hi:[0,1,1]
	v_cvt_scalef32_pk_f32_fp4 v[52:53], v54, 1.0 op_sel:[1,0,0]
	v_pk_fma_f32 v[52:53], s[10:11], v[52:53], v[56:57] op_sel_hi:[0,1,1]
	v_cvt_scalef32_pk_f32_fp4 v[56:57], v54, 1.0 op_sel:[0,1,0]
	v_pk_fma_f32 v[56:57], s[10:11], v[56:57], v[60:61] op_sel_hi:[0,1,1]
	v_cvt_scalef32_pk_f32_fp4 v[60:61], v54, 1.0 op_sel:[1,1,0]
	v_pk_fma_f32 v[60:61], s[10:11], v[60:61], v[64:65] op_sel_hi:[0,1,1]
	v_cvt_scalef32_pk_f32_fp4 v[64:65], v55, 1.0
	v_pk_fma_f32 v[64:65], s[10:11], v[64:65], v[68:69] op_sel_hi:[0,1,1]
	v_cvt_scalef32_pk_f32_fp4 v[68:69], v55, 1.0 op_sel:[1,0,0]
	v_pk_fma_f32 v[68:69], s[10:11], v[68:69], v[72:73] op_sel_hi:[0,1,1]
	v_cvt_scalef32_pk_f32_fp4 v[72:73], v55, 1.0 op_sel:[0,1,0]
	v_cvt_scalef32_pk_f32_fp4 v[54:55], v55, 1.0 op_sel:[1,1,0]
	v_pk_fma_f32 v[78:79], s[10:11], v[78:79], v[82:83] op_sel_hi:[0,1,1]
	v_pk_fma_f32 v[72:73], s[10:11], v[72:73], v[76:77] op_sel_hi:[0,1,1]
	v_pk_fma_f32 v[42:43], s[10:11], v[54:55], v[42:43] op_sel_hi:[0,1,1]
	v_readlane_b32 s10, v107, s34
	s_waitcnt vmcnt(10)
	v_cvt_scalef32_pk_f32_fp4 v[54:55], v44, 1.0
	v_pk_fma_f32 v[50:51], s[10:11], v[54:55], v[50:51] op_sel_hi:[0,1,1]
	v_cvt_scalef32_pk_f32_fp4 v[54:55], v44, 1.0 op_sel:[1,0,0]
	v_pk_fma_f32 v[54:55], s[10:11], v[54:55], v[58:59] op_sel_hi:[0,1,1]
	v_cvt_scalef32_pk_f32_fp4 v[58:59], v44, 1.0 op_sel:[0,1,0]
	v_pk_fma_f32 v[58:59], s[10:11], v[58:59], v[62:63] op_sel_hi:[0,1,1]
	v_cvt_scalef32_pk_f32_fp4 v[62:63], v44, 1.0 op_sel:[1,1,0]
	v_pk_fma_f32 v[62:63], s[10:11], v[62:63], v[66:67] op_sel_hi:[0,1,1]
	v_cvt_scalef32_pk_f32_fp4 v[66:67], v45, 1.0
	v_pk_fma_f32 v[66:67], s[10:11], v[66:67], v[70:71] op_sel_hi:[0,1,1]
	v_cvt_scalef32_pk_f32_fp4 v[70:71], v45, 1.0 op_sel:[1,0,0]
	v_pk_fma_f32 v[70:71], s[10:11], v[70:71], v[74:75] op_sel_hi:[0,1,1]
	v_cvt_scalef32_pk_f32_fp4 v[74:75], v45, 1.0 op_sel:[0,1,0]
	v_cvt_scalef32_pk_f32_fp4 v[44:45], v45, 1.0 op_sel:[1,1,0]
	v_pk_fma_f32 v[40:41], s[10:11], v[44:45], v[40:41] op_sel_hi:[0,1,1]
	v_cvt_scalef32_pk_f32_fp4 v[44:45], v46, 1.0
	v_pk_fma_f32 v[44:45], s[10:11], v[44:45], v[48:49] op_sel_hi:[0,1,1]
	v_cvt_scalef32_pk_f32_fp4 v[48:49], v46, 1.0 op_sel:[1,0,0]
	v_pk_fma_f32 v[48:49], s[10:11], v[48:49], v[52:53] op_sel_hi:[0,1,1]
	v_cvt_scalef32_pk_f32_fp4 v[52:53], v46, 1.0 op_sel:[0,1,0]
	v_pk_fma_f32 v[52:53], s[10:11], v[52:53], v[56:57] op_sel_hi:[0,1,1]
	v_cvt_scalef32_pk_f32_fp4 v[56:57], v46, 1.0 op_sel:[1,1,0]
	v_pk_fma_f32 v[56:57], s[10:11], v[56:57], v[60:61] op_sel_hi:[0,1,1]
	v_cvt_scalef32_pk_f32_fp4 v[60:61], v47, 1.0
	v_pk_fma_f32 v[60:61], s[10:11], v[60:61], v[64:65] op_sel_hi:[0,1,1]
	v_cvt_scalef32_pk_f32_fp4 v[64:65], v47, 1.0 op_sel:[1,0,0]
	v_pk_fma_f32 v[64:65], s[10:11], v[64:65], v[68:69] op_sel_hi:[0,1,1]
	v_cvt_scalef32_pk_f32_fp4 v[68:69], v47, 1.0 op_sel:[0,1,0]
	v_cvt_scalef32_pk_f32_fp4 v[46:47], v47, 1.0 op_sel:[1,1,0]
	v_pk_fma_f32 v[74:75], s[10:11], v[74:75], v[78:79] op_sel_hi:[0,1,1]
	v_pk_fma_f32 v[68:69], s[10:11], v[68:69], v[72:73] op_sel_hi:[0,1,1]
	v_pk_fma_f32 v[42:43], s[10:11], v[46:47], v[42:43] op_sel_hi:[0,1,1]
	v_readlane_b32 s10, v107, s33
	s_waitcnt vmcnt(9)
; #define PV_LOAD(BUF, EV, S0) do { _Pragma("unroll") for (int i = 0; i < 8; ++i) { const int row_ = __builtin_amdgcn_readlane(EV, (S0) + i); BUF[i & 3][i >> 2] = *(const u32x4*)(PV8 + (size_t)row_ * 1024 + lane * 16); } } while (0)
; __global__ void __launch_bounds__(NT, 2) mk_fwd(Args args) {
;     ...
; #pragma unroll
;             for (int hh = 0; hh < 2; ++hh) {
;                 const int ev = hh ? e1 : e0; const float av = hh ? act1 : act0;
;                 PV_LOAD(bA, ev, 0);
; #pragma unroll 1
;                 for (int s = 0; s < 64; s += 16) {
;                     PV_LOAD(bB, ev, s + 8);
;                     PV_ACC(bA, av, s);
;                     if (s + 16 < 64) PV_LOAD(bA, ev, s + 16);
;                     PV_ACC(bB, av, s + 8);
	v_cvt_scalef32_pk_f32_fp4 v[46:47], v36, 1.0
	v_pk_fma_f32 v[46:47], s[10:11], v[46:47], v[50:51] op_sel_hi:[0,1,1]
	v_cvt_scalef32_pk_f32_fp4 v[50:51], v36, 1.0 op_sel:[1,0,0]
	v_pk_fma_f32 v[50:51], s[10:11], v[50:51], v[54:55] op_sel_hi:[0,1,1]
	v_cvt_scalef32_pk_f32_fp4 v[54:55], v36, 1.0 op_sel:[0,1,0]
	v_pk_fma_f32 v[54:55], s[10:11], v[54:55], v[58:59] op_sel_hi:[0,1,1]
	v_cvt_scalef32_pk_f32_fp4 v[58:59], v36, 1.0 op_sel:[1,1,0]
	v_pk_fma_f32 v[58:59], s[10:11], v[58:59], v[62:63] op_sel_hi:[0,1,1]
	v_cvt_scalef32_pk_f32_fp4 v[62:63], v37, 1.0
	v_pk_fma_f32 v[62:63], s[10:11], v[62:63], v[66:67] op_sel_hi:[0,1,1]
	v_cvt_scalef32_pk_f32_fp4 v[66:67], v37, 1.0 op_sel:[1,0,0]
	v_pk_fma_f32 v[66:67], s[10:11], v[66:67], v[70:71] op_sel_hi:[0,1,1]
	v_cvt_scalef32_pk_f32_fp4 v[70:71], v37, 1.0 op_sel:[0,1,0]
	v_cvt_scalef32_pk_f32_fp4 v[36:37], v37, 1.0 op_sel:[1,1,0]
	v_pk_fma_f32 v[36:37], s[10:11], v[36:37], v[40:41] op_sel_hi:[0,1,1]
	v_cvt_scalef32_pk_f32_fp4 v[40:41], v38, 1.0
	v_pk_fma_f32 v[40:41], s[10:11], v[40:41], v[44:45] op_sel_hi:[0,1,1]
	v_cvt_scalef32_pk_f32_fp4 v[44:45], v38, 1.0 op_sel:[1,0,0]
	v_pk_fma_f32 v[44:45], s[10:11], v[44:45], v[48:49] op_sel_hi:[0,1,1]
	v_cvt_scalef32_pk_f32_fp4 v[48:49], v38, 1.0 op_sel:[0,1,0]
	v_pk_fma_f32 v[48:49], s[10:11], v[48:49], v[52:53] op_sel_hi:[0,1,1]
	v_cvt_scalef32_pk_f32_fp4 v[52:53], v38, 1.0 op_sel:[1,1,0]
	v_pk_fma_f32 v[52:53], s[10:11], v[52:53], v[56:57] op_sel_hi:[0,1,1]
	v_cvt_scalef32_pk_f32_fp4 v[56:57], v39, 1.0
	v_pk_fma_f32 v[56:57], s[10:11], v[56:57], v[60:61] op_sel_hi:[0,1,1]
	v_cvt_scalef32_pk_f32_fp4 v[60:61], v39, 1.0 op_sel:[1,0,0]
	v_pk_fma_f32 v[60:61], s[10:11], v[60:61], v[64:65] op_sel_hi:[0,1,1]
	v_cvt_scalef32_pk_f32_fp4 v[64:65], v39, 1.0 op_sel:[0,1,0]
	v_cvt_scalef32_pk_f32_fp4 v[38:39], v39, 1.0 op_sel:[1,1,0]
	v_pk_fma_f32 v[70:71], s[10:11], v[70:71], v[74:75] op_sel_hi:[0,1,1]
	v_pk_fma_f32 v[64:65], s[10:11], v[64:65], v[68:69] op_sel_hi:[0,1,1]
	v_pk_fma_f32 v[38:39], s[10:11], v[38:39], v[42:43] op_sel_hi:[0,1,1]
	v_readlane_b32 s10, v107, s31
	s_waitcnt vmcnt(0)
	v_mov_b64_e32 v[94:95], v[6:7]
	v_mov_b64_e32 v[90:91], v[2:3]
	v_mov_b64_e32 v[88:89], v[0:1]
	v_mov_b64_e32 v[82:83], v[14:15]
	v_mov_b64_e32 v[78:79], v[22:23]
	v_cvt_scalef32_pk_f32_fp4 v[42:43], v32, 1.0
	v_mov_b64_e32 v[80:81], v[12:13]
	v_pk_fma_f32 v[118:119], s[10:11], v[42:43], v[46:47] op_sel_hi:[0,1,1]
	v_cvt_scalef32_pk_f32_fp4 v[42:43], v32, 1.0 op_sel:[1,0,0]
	v_pk_fma_f32 v[122:123], s[10:11], v[42:43], v[50:51] op_sel_hi:[0,1,1]
	v_cvt_scalef32_pk_f32_fp4 v[42:43], v32, 1.0 op_sel:[0,1,0]
	v_pk_fma_f32 v[144:145], s[10:11], v[42:43], v[54:55] op_sel_hi:[0,1,1]
	v_cvt_scalef32_pk_f32_fp4 v[42:43], v32, 1.0 op_sel:[1,1,0]
	v_pk_fma_f32 v[142:143], s[10:11], v[42:43], v[58:59] op_sel_hi:[0,1,1]
	v_cvt_scalef32_pk_f32_fp4 v[42:43], v33, 1.0
	v_pk_fma_f32 v[140:141], s[10:11], v[42:43], v[62:63] op_sel_hi:[0,1,1]
	v_cvt_scalef32_pk_f32_fp4 v[42:43], v33, 1.0 op_sel:[1,0,0]
	v_pk_fma_f32 v[138:139], s[10:11], v[42:43], v[66:67] op_sel_hi:[0,1,1]
	v_cvt_scalef32_pk_f32_fp4 v[42:43], v33, 1.0 op_sel:[0,1,0]
	v_cvt_scalef32_pk_f32_fp4 v[32:33], v33, 1.0 op_sel:[1,1,0]
	v_pk_fma_f32 v[132:133], s[10:11], v[32:33], v[36:37] op_sel_hi:[0,1,1]
	v_cvt_scalef32_pk_f32_fp4 v[32:33], v34, 1.0
	v_pk_fma_f32 v[130:131], s[10:11], v[32:33], v[40:41] op_sel_hi:[0,1,1]
	v_cvt_scalef32_pk_f32_fp4 v[32:33], v34, 1.0 op_sel:[1,0,0]
	v_pk_fma_f32 v[126:127], s[10:11], v[32:33], v[44:45] op_sel_hi:[0,1,1]
	v_cvt_scalef32_pk_f32_fp4 v[32:33], v34, 1.0 op_sel:[0,1,0]
	v_pk_fma_f32 v[124:125], s[10:11], v[32:33], v[48:49] op_sel_hi:[0,1,1]
	v_cvt_scalef32_pk_f32_fp4 v[32:33], v34, 1.0 op_sel:[1,1,0]
	v_pk_fma_f32 v[120:121], s[10:11], v[32:33], v[52:53] op_sel_hi:[0,1,1]
	v_cvt_scalef32_pk_f32_fp4 v[32:33], v35, 1.0
	v_pk_fma_f32 v[116:117], s[10:11], v[32:33], v[56:57] op_sel_hi:[0,1,1]
	v_cvt_scalef32_pk_f32_fp4 v[32:33], v35, 1.0 op_sel:[1,0,0]
	v_pk_fma_f32 v[114:115], s[10:11], v[32:33], v[60:61] op_sel_hi:[0,1,1]
	v_cvt_scalef32_pk_f32_fp4 v[32:33], v35, 1.0 op_sel:[0,1,0]
	v_pk_fma_f32 v[134:135], s[10:11], v[42:43], v[70:71] op_sel_hi:[0,1,1]
	v_pk_fma_f32 v[112:113], s[10:11], v[32:33], v[64:65] op_sel_hi:[0,1,1]
	v_cvt_scalef32_pk_f32_fp4 v[32:33], v35, 1.0 op_sel:[1,1,0]
	v_mov_b64_e32 v[42:43], v[26:27]
	v_mov_b64_e32 v[70:71], v[10:11]
	v_mov_b64_e32 v[50:51], v[30:31]
	v_mov_b64_e32 v[62:63], v[18:19]
	v_pk_fma_f32 v[110:111], s[10:11], v[32:33], v[38:39] op_sel_hi:[0,1,1]
	v_mov_b64_e32 v[40:41], v[24:25]
	v_mov_b64_e32 v[68:69], v[8:9]
	v_mov_b64_e32 v[48:49], v[28:29]
	v_mov_b64_e32 v[60:61], v[16:17]
	v_mov_b64_e32 v[76:77], v[20:21]
	v_mov_b64_e32 v[92:93], v[4:5]
	s_cbranch_vccz .LBB0_885

; #define PV_LOAD(BUF, EV, S0) do { _Pragma("unroll") for (int i = 0; i < 8; ++i) { const int row_ = __builtin_amdgcn_readlane(EV, (S0) + i); BUF[i & 3][i >> 2] = *(const u32x4*)(PV8 + (size_t)row_ * 1024 + lane * 16); } } while (0)
; __global__ void __launch_bounds__(NT, 2) mk_fwd(Args args) {
;     ...
;                 for (int s = 0; s < 64; s += 16) {
;                     PV_LOAD(bB, ev, s + 8);
;                     PV_ACC(bA, av, s);
;                     if (s + 16 < 64) PV_LOAD(bA, ev, s + 16);
;                     PV_ACC(bB, av, s + 8);
.Lp10_dmy_910:
	global_load_dword v220, v129, s[6:7]
	global_load_dword v221, v129, s[6:7]
	global_load_dword v222, v129, s[6:7]
	global_load_dword v223, v129, s[6:7]
	global_load_dword v224, v129, s[6:7]
	global_load_dword v225, v129, s[6:7]
	global_load_dword v226, v129, s[6:7]
	global_load_dword v227, v129, s[6:7]
	s_branch .LBB0_910
